# S5 pass 2: the four LDS reads of each C-projection MFMA chain issued together into dead registers, counted lgkmcnt waits
# speedup vs baseline: 1.0918x; 1.0038x over previous
.LBB0_209:
	s_or_b64 exec, exec, s[72:73]
	v_fma_f32 v2, v135, v0, v33
	v_fma_f32 v3, -v135, v1, v49
	v_fmac_f32_e32 v2, v134, v1
	v_fmac_f32_e32 v3, v134, v0
	v_fma_f32 v4, v135, v3, v34
	v_fma_f32 v5, -v135, v2, v50
	v_fmac_f32_e32 v4, v134, v2
	v_fmac_f32_e32 v5, v134, v3
	v_fma_f32 v6, v135, v5, v35
	v_fma_f32 v7, -v135, v4, v51
	v_fmac_f32_e32 v6, v134, v4
	v_fmac_f32_e32 v7, v134, v5
	v_fma_f32 v8, v135, v7, v36
	v_fma_f32 v9, -v135, v6, v52
	v_fmac_f32_e32 v8, v134, v6
	v_fmac_f32_e32 v9, v134, v7
	v_fma_f32 v10, v135, v9, v37
	v_fma_f32 v11, -v135, v8, v53
	v_fmac_f32_e32 v10, v134, v8
	v_fmac_f32_e32 v11, v134, v9
	v_fma_f32 v12, v135, v11, v38
	v_fma_f32 v13, -v135, v10, v54
	v_fmac_f32_e32 v12, v134, v10
	v_fmac_f32_e32 v13, v134, v11
	v_fma_f32 v14, v135, v13, v39
	v_fma_f32 v16, -v135, v12, v55
	v_fmac_f32_e32 v14, v134, v12
	v_fmac_f32_e32 v16, v134, v13
	v_fma_f32 v17, v135, v16, v40
	v_fma_f32 v18, -v135, v14, v56
	v_fmac_f32_e32 v17, v134, v14
	v_fmac_f32_e32 v18, v134, v16
	v_fma_f32 v19, v135, v18, v41
	v_fma_f32 v20, -v135, v17, v57
	v_fmac_f32_e32 v19, v134, v17
	v_fmac_f32_e32 v20, v134, v18
	v_fma_f32 v21, v135, v20, v42
	v_fma_f32 v22, -v135, v19, v58
	v_fmac_f32_e32 v21, v134, v19
	v_fmac_f32_e32 v22, v134, v20
	v_fma_f32 v23, v135, v22, v43
	v_fma_f32 v24, -v135, v21, v59
	v_fmac_f32_e32 v23, v134, v21
	v_fmac_f32_e32 v24, v134, v22
	v_fma_f32 v25, v135, v24, v44
	v_fma_f32 v26, -v135, v23, v60
	v_cvt_pk_bf16_f32 v0, v0, v1
	v_cvt_pk_bf16_f32 v1, v3, v2
	v_fmac_f32_e32 v25, v134, v23
	v_fmac_f32_e32 v26, v134, v24
	ds_write2_b32 v169, v0, v1 offset0:32 offset1:100
	v_cvt_pk_bf16_f32 v0, v5, v4
	v_cvt_pk_bf16_f32 v1, v7, v6
	v_fma_f32 v27, v135, v26, v45
	v_fma_f32 v28, -v135, v25, v61
	ds_write2_b32 v169, v0, v1 offset0:168 offset1:236
	v_cvt_pk_bf16_f32 v0, v9, v8
	v_cvt_pk_bf16_f32 v1, v11, v10
	v_fmac_f32_e32 v27, v134, v25
	v_fmac_f32_e32 v28, v134, v26
	ds_write2_b32 v213, v0, v1 offset0:48 offset1:116
	v_cvt_pk_bf16_f32 v0, v13, v12
	v_cvt_pk_bf16_f32 v1, v16, v14
	v_fma_f32 v29, v135, v28, v46
	v_fma_f32 v30, -v135, v27, v62
	ds_write2_b32 v213, v0, v1 offset0:184 offset1:252
	v_cvt_pk_bf16_f32 v0, v18, v17
	v_cvt_pk_bf16_f32 v1, v20, v19
	v_fmac_f32_e32 v29, v134, v27
	v_fmac_f32_e32 v30, v134, v28
	ds_write2_b32 v214, v0, v1 offset0:64 offset1:132
	v_cvt_pk_bf16_f32 v0, v22, v21
	v_cvt_pk_bf16_f32 v1, v24, v23
	v_add_u32_e32 v217, 0xa00, v169
	v_fmac_f32_e32 v47, v135, v30
	v_fma_f32 v34, -v135, v29, v63
	ds_write2_b32 v217, v0, v1 offset0:72 offset1:140
	v_cvt_pk_bf16_f32 v0, v26, v25
	v_cvt_pk_bf16_f32 v1, v28, v27
	v_add_u32_e32 v216, 0xe00, v169
	v_fmac_f32_e32 v47, v134, v29
	v_fmac_f32_e32 v34, v134, v30
	ds_write2_b32 v215, v0, v1 offset0:80 offset1:148
	v_cvt_pk_bf16_f32 v0, v30, v29
	v_cvt_pk_bf16_f32 v1, v34, v47
	ds_write2_b32 v216, v0, v1 offset0:88 offset1:156
	s_nop 7
	ds_read_b128 v[0:3], v171
	ds_read_b128 v[4:7], v171 offset:64
	ds_read_b128 v[8:11], v171 offset:128
	ds_read_b128 v[16:19], v171 offset:192
	s_waitcnt lgkmcnt(3)
	v_mfma_f32_16x16x32_bf16 v[0:3], v[112:115], v[0:3], 0
	s_waitcnt lgkmcnt(2)
	v_mfma_f32_16x16x32_bf16 v[0:3], v[108:111], v[4:7], v[0:3]
	s_waitcnt lgkmcnt(1)
	v_mfma_f32_16x16x32_bf16 v[0:3], v[104:107], v[8:11], v[0:3]
	s_waitcnt lgkmcnt(0)
	v_mfma_f32_16x16x32_bf16 v[80:83], v[100:103], v[16:19], v[0:3]
	ds_read_b128 v[4:7], v171 offset:4416
	s_nop 3
	ds_read_b128 v[0:3], v171 offset:4352
	s_waitcnt lgkmcnt(0)
	v_mfma_f32_16x16x32_bf16 v[0:3], v[112:115], v[0:3], 0
	v_mfma_f32_16x16x32_bf16 v[0:3], v[108:111], v[4:7], v[0:3]
	ds_read_b128 v[4:7], v171 offset:4480
	s_waitcnt lgkmcnt(0)
	v_mfma_f32_16x16x32_bf16 v[0:3], v[104:107], v[4:7], v[0:3]
	ds_read_b128 v[4:7], v171 offset:4544
	s_waitcnt lgkmcnt(0)
	v_mfma_f32_16x16x32_bf16 v[84:87], v[100:103], v[4:7], v[0:3]
	s_nop 4
	ds_read_b128 v[0:3], v212 offset:4352
	s_waitcnt lgkmcnt(0)
	v_mfma_f32_32x32x16_bf16 v[64:79], v[0:3], v[124:127], 0
	s_nop 11
	v_fma_f32 v4, -v133, v31, v64
	v_mfma_f32_32x32x16_bf16 v[48:63], v[0:3], v[128:131], 0
	v_fmac_f32_e32 v4, v132, v15
	s_nop 10
	v_fma_f32 v5, v133, v15, v48
	v_fmac_f32_e32 v5, v132, v31
	v_fma_f32 v6, -v133, v5, v65
	v_fma_f32 v7, v133, v4, v49
	v_fmac_f32_e32 v6, v132, v4
	v_fmac_f32_e32 v7, v132, v5
	v_fma_f32 v8, -v133, v7, v66
	v_fma_f32 v9, v133, v6, v50
	v_fmac_f32_e32 v8, v132, v6
	v_fmac_f32_e32 v9, v132, v7
	v_fma_f32 v10, -v133, v9, v67
	v_fma_f32 v11, v133, v8, v51
	v_fmac_f32_e32 v10, v132, v8
	v_fmac_f32_e32 v11, v132, v9
	v_fma_f32 v12, -v133, v11, v68
	v_fma_f32 v13, v133, v10, v52
	v_fmac_f32_e32 v12, v132, v10
	v_fmac_f32_e32 v13, v132, v11
	v_fma_f32 v14, -v133, v13, v69
	v_fma_f32 v15, v133, v12, v53
	v_fmac_f32_e32 v14, v132, v12
	v_fmac_f32_e32 v15, v132, v13
	v_fma_f32 v16, -v133, v15, v70
	v_fma_f32 v17, v133, v14, v54
	v_fmac_f32_e32 v16, v132, v14
	v_fmac_f32_e32 v17, v132, v15
	v_fma_f32 v18, -v133, v17, v71
	v_fma_f32 v19, v133, v16, v55
	v_fmac_f32_e32 v18, v132, v16
	v_fmac_f32_e32 v19, v132, v17
	v_fma_f32 v20, -v133, v19, v72
	v_fma_f32 v21, v133, v18, v56
	v_fmac_f32_e32 v20, v132, v18
	v_fmac_f32_e32 v21, v132, v19
	v_fma_f32 v35, -v133, v21, v73
	v_fma_f32 v36, v133, v20, v57
	v_fmac_f32_e32 v35, v132, v20
	v_fmac_f32_e32 v36, v132, v21
	v_cvt_pk_bf16_f32 v49, v4, v5
	v_cvt_pk_bf16_f32 v50, v6, v7
	v_cvt_pk_bf16_f32 v51, v8, v9
	v_cvt_pk_bf16_f32 v52, v10, v11
	v_cvt_pk_bf16_f32 v53, v12, v13
	v_cvt_pk_bf16_f32 v54, v14, v15
	v_cvt_pk_bf16_f32 v55, v16, v17
	v_cvt_pk_bf16_f32 v56, v18, v19
	v_cvt_pk_bf16_f32 v57, v20, v21
	v_mfma_f32_32x32x16_bf16 v[18:33], v[0:3], v[120:123], 0
	v_fma_f32 v37, -v133, v36, v74
	v_fma_f32 v38, v133, v35, v58
	v_fmac_f32_e32 v37, v132, v35
	v_fmac_f32_e32 v38, v132, v36
	v_fma_f32 v39, -v133, v38, v75
	v_fma_f32 v40, v133, v37, v59
	v_fmac_f32_e32 v39, v132, v37
	v_mfma_f32_32x32x16_bf16 v[2:17], v[0:3], v[116:119], 0
	s_nop 3
	v_fma_f32 v0, -v135, v47, v18
	v_fmac_f32_e32 v0, v134, v34
	v_fmac_f32_e32 v40, v132, v38
	v_fma_f32 v41, -v133, v40, v76
	v_fma_f32 v42, v133, v39, v60
	v_fmac_f32_e32 v41, v132, v39
	v_fmac_f32_e32 v42, v132, v40
	s_nop 0
	v_fma_f32 v1, v135, v34, v2
	v_fmac_f32_e32 v1, v134, v47
	v_fma_f32 v2, -v135, v1, v19
	v_fma_f32 v3, v135, v0, v3
	v_fmac_f32_e32 v2, v134, v0
	v_fmac_f32_e32 v3, v134, v1
	v_fma_f32 v18, -v135, v3, v20
	v_fma_f32 v4, v135, v2, v4
	v_fmac_f32_e32 v18, v134, v2
	v_fmac_f32_e32 v4, v134, v3
	v_fma_f32 v19, -v135, v4, v21
	v_fma_f32 v5, v135, v18, v5
	v_fmac_f32_e32 v19, v134, v18
	v_fmac_f32_e32 v5, v134, v4
	v_fma_f32 v20, -v135, v5, v22
	v_fma_f32 v6, v135, v19, v6
	v_fmac_f32_e32 v20, v134, v19
	v_fmac_f32_e32 v6, v134, v5
	v_fma_f32 v21, -v135, v6, v23
	v_fma_f32 v7, v135, v20, v7
	v_fmac_f32_e32 v21, v134, v20
	v_fmac_f32_e32 v7, v134, v6
	v_fma_f32 v22, -v135, v7, v24
	v_fma_f32 v8, v135, v21, v8
	v_fmac_f32_e32 v22, v134, v21
	v_fmac_f32_e32 v8, v134, v7
	v_fma_f32 v23, -v135, v8, v25
	v_fma_f32 v9, v135, v22, v9
	v_fmac_f32_e32 v23, v134, v22
	v_fmac_f32_e32 v9, v134, v8
	v_fma_f32 v24, -v135, v9, v26
	v_fma_f32 v10, v135, v23, v10
	v_cvt_pk_bf16_f32 v0, v0, v1
	v_fmac_f32_e32 v24, v134, v23
	v_fmac_f32_e32 v10, v134, v9
	ds_write2_b32 v169, v49, v0 offset1:32
	v_cvt_pk_bf16_f32 v0, v2, v3
	v_fma_f32 v25, -v135, v10, v27
	v_fma_f32 v11, v135, v24, v11
	ds_write2_b32 v169, v50, v0 offset0:68 offset1:100
	v_cvt_pk_bf16_f32 v0, v18, v4
	v_fmac_f32_e32 v25, v134, v24
	v_fmac_f32_e32 v11, v134, v10
	ds_write2_b32 v169, v51, v0 offset0:136 offset1:168
	v_cvt_pk_bf16_f32 v0, v19, v5
	v_fma_f32 v26, -v135, v11, v28
	v_fma_f32 v12, v135, v25, v12
	ds_write2_b32 v169, v52, v0 offset0:204 offset1:236
	v_cvt_pk_bf16_f32 v0, v20, v6
	v_fmac_f32_e32 v26, v134, v25
	v_fmac_f32_e32 v12, v134, v11
	ds_write2_b32 v213, v53, v0 offset0:16 offset1:48
	v_cvt_pk_bf16_f32 v0, v21, v7
	v_fma_f32 v27, -v135, v12, v29
	v_fma_f32 v13, v135, v26, v13
	ds_write2_b32 v213, v54, v0 offset0:84 offset1:116
	v_cvt_pk_bf16_f32 v0, v22, v8
	v_fmac_f32_e32 v27, v134, v26
	v_fmac_f32_e32 v13, v134, v12
	ds_write2_b32 v213, v55, v0 offset0:152 offset1:184
	v_cvt_pk_bf16_f32 v0, v23, v9
	v_fma_f32 v28, -v135, v13, v30
	v_fma_f32 v14, v135, v27, v14
	ds_write2_b32 v213, v56, v0 offset0:220 offset1:252
	v_cvt_pk_bf16_f32 v0, v24, v10
	v_fmac_f32_e32 v28, v134, v27
	v_fmac_f32_e32 v14, v134, v13
	ds_write2_b32 v214, v57, v0 offset0:32 offset1:64
	v_cvt_pk_bf16_f32 v0, v25, v11
	v_fma_f32 v43, -v133, v42, v77
	v_fma_f32 v44, v133, v41, v61
	v_cvt_pk_bf16_f32 v35, v35, v36
	v_fma_f32 v29, -v135, v14, v31
	v_fma_f32 v15, v135, v28, v15
	ds_write2_b32 v214, v35, v0 offset0:100 offset1:132
	v_cvt_pk_bf16_f32 v0, v26, v12
	v_fmac_f32_e32 v43, v132, v41
	v_fmac_f32_e32 v44, v132, v42
	v_cvt_pk_bf16_f32 v36, v37, v38
	v_fmac_f32_e32 v29, v134, v28
	v_fmac_f32_e32 v15, v134, v14
	ds_write2_b32 v214, v36, v0 offset0:168 offset1:200
	v_cvt_pk_bf16_f32 v0, v27, v13
	v_fma_f32 v45, -v133, v44, v78
	v_fma_f32 v46, v133, v43, v62
	v_cvt_pk_bf16_f32 v37, v39, v40
	v_fma_f32 v30, -v135, v15, v32
	v_fma_f32 v16, v135, v29, v16
	ds_write2_b32 v217, v37, v0 offset0:108 offset1:140
	v_cvt_pk_bf16_f32 v0, v28, v14
	v_fmac_f32_e32 v45, v132, v43
	v_fmac_f32_e32 v46, v132, v44
	v_cvt_pk_bf16_f32 v38, v41, v42
	v_fmac_f32_e32 v30, v134, v29
	v_fmac_f32_e32 v16, v134, v15
	ds_write2_b32 v215, v38, v0 offset0:48 offset1:80
	v_cvt_pk_bf16_f32 v0, v29, v15
	v_fma_f32 v48, -v133, v46, v79
	v_fmac_f32_e32 v63, v133, v45
	v_cvt_pk_bf16_f32 v39, v43, v44
	v_fma_f32 v58, -v135, v16, v33
	v_fmac_f32_e32 v17, v135, v30
	ds_write2_b32 v215, v39, v0 offset0:116 offset1:148
	v_cvt_pk_bf16_f32 v0, v30, v16
	v_fmac_f32_e32 v48, v132, v45
	v_fmac_f32_e32 v63, v132, v46
	v_cvt_pk_bf16_f32 v40, v45, v46
	v_cvt_pk_bf16_f32 v41, v48, v63
	v_fmac_f32_e32 v58, v134, v30
	v_fmac_f32_e32 v17, v134, v16
	ds_write2_b32 v215, v40, v0 offset0:184 offset1:216
	v_cvt_pk_bf16_f32 v0, v58, v17
	ds_write2_b32 v216, v41, v0 offset0:124 offset1:156
	s_nop 7
	ds_read_b128 v[0:3], v171
	ds_read_b128 v[4:7], v171 offset:64
	ds_read_b128 v[52:55], v171 offset:128
	ds_read_b128 v[8:11], v171 offset:192
	s_waitcnt lgkmcnt(3)
	v_mfma_f32_16x16x32_bf16 v[0:3], v[112:115], v[0:3], 0
	s_waitcnt lgkmcnt(2)
	v_mfma_f32_16x16x32_bf16 v[0:3], v[108:111], v[4:7], v[0:3]
	s_waitcnt lgkmcnt(1)
	v_mfma_f32_16x16x32_bf16 v[0:3], v[104:107], v[52:55], v[0:3]
	s_waitcnt lgkmcnt(0)
	v_mfma_f32_16x16x32_bf16 v[64:67], v[100:103], v[8:11], v[0:3]
	s_nop 5
	s_nop 7
	ds_read_b128 v[0:3], v171 offset:4352
	ds_read_b128 v[4:7], v171 offset:4416
	ds_read_b128 v[52:55], v171 offset:4480
	ds_read_b128 v[8:11], v171 offset:4544
	s_waitcnt lgkmcnt(3)
	v_mfma_f32_16x16x32_bf16 v[0:3], v[112:115], v[0:3], 0
	s_waitcnt lgkmcnt(2)
	v_mfma_f32_16x16x32_bf16 v[0:3], v[108:111], v[4:7], v[0:3]
	s_waitcnt lgkmcnt(1)
	v_mfma_f32_16x16x32_bf16 v[0:3], v[104:107], v[52:55], v[0:3]
	s_waitcnt lgkmcnt(0)
	v_mfma_f32_16x16x32_bf16 v[68:71], v[100:103], v[8:11], v[0:3]
	ds_read_b128 v[50:53], v212 offset:8704
	s_waitcnt lgkmcnt(0)
	v_mfma_f32_32x32x16_bf16 v[18:33], v[50:53], v[124:127], 0
	s_nop 11
	v_fma_f32 v16, -v133, v63, v18
	v_mfma_f32_32x32x16_bf16 v[0:15], v[50:53], v[128:131], 0
	v_fmac_f32_e32 v16, v132, v48
	s_nop 10
	v_fma_f32 v0, v133, v48, v0
	v_fmac_f32_e32 v0, v132, v63
	v_fma_f32 v18, -v133, v0, v19
	v_fma_f32 v1, v133, v16, v1
	v_fmac_f32_e32 v18, v132, v16
	v_fmac_f32_e32 v1, v132, v0
	v_fma_f32 v19, -v133, v1, v20
	v_fma_f32 v2, v133, v18, v2
	v_fmac_f32_e32 v19, v132, v18
	v_fmac_f32_e32 v2, v132, v1
	v_fma_f32 v20, -v133, v2, v21
	v_fma_f32 v3, v133, v19, v3
	v_fmac_f32_e32 v20, v132, v19
	v_fmac_f32_e32 v3, v132, v2
	v_fma_f32 v21, -v133, v3, v22
	v_fma_f32 v4, v133, v20, v4
	v_fmac_f32_e32 v21, v132, v20
	v_fmac_f32_e32 v4, v132, v3
	v_fma_f32 v22, -v133, v4, v23
	v_fma_f32 v5, v133, v21, v5
	v_fmac_f32_e32 v22, v132, v21
	v_fmac_f32_e32 v5, v132, v4
	v_fma_f32 v23, -v133, v5, v24
	v_fma_f32 v6, v133, v22, v6
	v_fmac_f32_e32 v23, v132, v22
	v_fmac_f32_e32 v6, v132, v5
	v_fma_f32 v24, -v133, v6, v25
	v_fma_f32 v7, v133, v23, v7
	v_fmac_f32_e32 v24, v132, v23
	v_fmac_f32_e32 v7, v132, v6
	v_fma_f32 v25, -v133, v7, v26
	v_fma_f32 v8, v133, v24, v8
	v_fmac_f32_e32 v25, v132, v24
	v_fmac_f32_e32 v8, v132, v7
	v_fma_f32 v26, -v133, v8, v27
	v_fma_f32 v9, v133, v25, v9
	v_fmac_f32_e32 v26, v132, v25
	v_fmac_f32_e32 v9, v132, v8
	v_fma_f32 v27, -v133, v9, v28
	v_fma_f32 v10, v133, v26, v10
	v_fmac_f32_e32 v27, v132, v26
	v_fmac_f32_e32 v10, v132, v9
	v_fma_f32 v28, -v133, v10, v29
	v_fma_f32 v11, v133, v27, v11
	v_fmac_f32_e32 v28, v132, v27
	v_fmac_f32_e32 v11, v132, v10
	v_fma_f32 v29, -v133, v11, v30
	v_fma_f32 v12, v133, v28, v12
	v_fmac_f32_e32 v29, v132, v28
	v_fmac_f32_e32 v12, v132, v11
	v_fma_f32 v30, -v133, v12, v31
	v_fma_f32 v13, v133, v29, v13
	v_fmac_f32_e32 v30, v132, v29
	v_fmac_f32_e32 v13, v132, v12
	v_fma_f32 v31, -v133, v13, v32
	v_fma_f32 v14, v133, v30, v14
	v_fmac_f32_e32 v31, v132, v30
	v_fmac_f32_e32 v14, v132, v13
	v_fma_f32 v54, -v133, v14, v33
	v_fmac_f32_e32 v15, v133, v31
	v_fmac_f32_e32 v54, v132, v31
	v_fmac_f32_e32 v15, v132, v14
	v_cvt_pk_bf16_f32 v1, v18, v1
	v_cvt_pk_bf16_f32 v2, v19, v2
	v_cvt_pk_bf16_f32 v3, v20, v3
	v_cvt_pk_bf16_f32 v4, v21, v4
	v_cvt_pk_bf16_f32 v5, v22, v5
	v_cvt_pk_bf16_f32 v6, v23, v6
	v_cvt_pk_bf16_f32 v7, v24, v7
	v_cvt_pk_bf16_f32 v8, v25, v8
	v_mfma_f32_32x32x16_bf16 v[34:49], v[50:53], v[120:123], 0
	v_cvt_pk_bf16_f32 v9, v26, v9
	v_cvt_pk_bf16_f32 v10, v27, v10
	v_cvt_pk_bf16_f32 v11, v28, v11
	v_cvt_pk_bf16_f32 v12, v29, v12
	v_cvt_pk_bf16_f32 v13, v30, v13
	v_cvt_pk_bf16_f32 v14, v31, v14
	v_cvt_pk_bf16_f32 v0, v16, v0
	v_mfma_f32_32x32x16_bf16 v[18:33], v[50:53], v[116:119], 0
	s_nop 10
	v_fma_f32 v34, -v135, v17, v34
	v_fmac_f32_e32 v34, v134, v58
	v_cvt_pk_bf16_f32 v16, v54, v15
	v_fma_f32 v18, v135, v58, v18
	v_fmac_f32_e32 v18, v134, v17
	v_fma_f32 v17, -v135, v18, v35
	v_fma_f32 v19, v135, v34, v19
	v_fmac_f32_e32 v17, v134, v34
	v_fmac_f32_e32 v19, v134, v18
	v_fma_f32 v35, -v135, v19, v36
	v_fma_f32 v20, v135, v17, v20
	v_fmac_f32_e32 v35, v134, v17
	v_fmac_f32_e32 v20, v134, v19
	v_fma_f32 v36, -v135, v20, v37
	v_fma_f32 v21, v135, v35, v21
	v_fmac_f32_e32 v36, v134, v35
	v_fmac_f32_e32 v21, v134, v20
	v_fma_f32 v37, -v135, v21, v38
	v_fma_f32 v22, v135, v36, v22
	v_fmac_f32_e32 v37, v134, v36
	v_fmac_f32_e32 v22, v134, v21
	v_fma_f32 v38, -v135, v22, v39
	v_fma_f32 v23, v135, v37, v23
	v_fmac_f32_e32 v38, v134, v37
	v_fmac_f32_e32 v23, v134, v22
	v_fma_f32 v39, -v135, v23, v40
	v_fma_f32 v24, v135, v38, v24
	v_fmac_f32_e32 v39, v134, v38
	v_fmac_f32_e32 v24, v134, v23
	v_fma_f32 v40, -v135, v24, v41
	v_fma_f32 v25, v135, v39, v25
	v_fmac_f32_e32 v40, v134, v39
	v_fmac_f32_e32 v25, v134, v24
	v_fma_f32 v41, -v135, v25, v42
	v_fma_f32 v26, v135, v40, v26
	v_fmac_f32_e32 v41, v134, v40
	v_fmac_f32_e32 v26, v134, v25
	v_cvt_pk_bf16_f32 v18, v34, v18
	ds_write2_b32 v169, v0, v18 offset1:32
	v_cvt_pk_bf16_f32 v0, v17, v19
	v_fma_f32 v42, -v135, v26, v43
	v_fma_f32 v27, v135, v41, v27
	ds_write2_b32 v169, v1, v0 offset0:68 offset1:100
	v_cvt_pk_bf16_f32 v0, v35, v20
	v_fmac_f32_e32 v42, v134, v41
	v_fmac_f32_e32 v27, v134, v26
	ds_write2_b32 v169, v2, v0 offset0:136 offset1:168
	v_cvt_pk_bf16_f32 v0, v36, v21
	v_fma_f32 v43, -v135, v27, v44
	v_fma_f32 v28, v135, v42, v28
	ds_write2_b32 v169, v3, v0 offset0:204 offset1:236
	v_cvt_pk_bf16_f32 v0, v37, v22
	v_fmac_f32_e32 v43, v134, v42
	v_fmac_f32_e32 v28, v134, v27
	ds_write2_b32 v213, v4, v0 offset0:16 offset1:48
	v_cvt_pk_bf16_f32 v0, v38, v23
	v_fma_f32 v44, -v135, v28, v45
	v_fma_f32 v29, v135, v43, v29
	ds_write2_b32 v213, v5, v0 offset0:84 offset1:116
	v_cvt_pk_bf16_f32 v0, v39, v24
	v_fmac_f32_e32 v44, v134, v43
	v_fmac_f32_e32 v29, v134, v28
	ds_write2_b32 v213, v6, v0 offset0:152 offset1:184
	v_cvt_pk_bf16_f32 v0, v40, v25
	v_fma_f32 v45, -v135, v29, v46
	v_fma_f32 v30, v135, v44, v30
	ds_write2_b32 v213, v7, v0 offset0:220 offset1:252
	v_cvt_pk_bf16_f32 v0, v41, v26
	v_fmac_f32_e32 v45, v134, v44
	v_fmac_f32_e32 v30, v134, v29
	ds_write2_b32 v214, v8, v0 offset0:32 offset1:64
	v_cvt_pk_bf16_f32 v0, v42, v27
	v_fma_f32 v46, -v135, v30, v47
	v_fma_f32 v31, v135, v45, v31
	ds_write2_b32 v214, v9, v0 offset0:100 offset1:132
	v_cvt_pk_bf16_f32 v0, v43, v28
	v_fmac_f32_e32 v46, v134, v45
	v_fmac_f32_e32 v31, v134, v30
	ds_write2_b32 v214, v10, v0 offset0:168 offset1:200
	v_cvt_pk_bf16_f32 v0, v44, v29
	v_fma_f32 v47, -v135, v31, v48
	v_fma_f32 v32, v135, v46, v32
	ds_write2_b32 v217, v11, v0 offset0:108 offset1:140
	v_cvt_pk_bf16_f32 v0, v45, v30
	v_fmac_f32_e32 v47, v134, v46
	v_fmac_f32_e32 v32, v134, v31
	ds_write2_b32 v215, v12, v0 offset0:48 offset1:80
	v_cvt_pk_bf16_f32 v0, v46, v31
	v_fma_f32 v50, -v135, v32, v49
	v_fmac_f32_e32 v33, v135, v47
	ds_write2_b32 v215, v13, v0 offset0:116 offset1:148
	v_cvt_pk_bf16_f32 v0, v47, v32
	v_fmac_f32_e32 v50, v134, v47
	v_fmac_f32_e32 v33, v134, v32
	ds_write2_b32 v215, v14, v0 offset0:184 offset1:216
	v_cvt_pk_bf16_f32 v0, v50, v33
	ds_write2_b32 v216, v16, v0 offset0:124 offset1:156
	s_nop 7
	ds_read_b128 v[0:3], v171
	ds_read_b128 v[4:7], v171 offset:64
	ds_read_b128 v[56:59], v171 offset:128
	ds_read_b128 v[8:11], v171 offset:192
	s_waitcnt lgkmcnt(3)
	v_mfma_f32_16x16x32_bf16 v[0:3], v[112:115], v[0:3], 0
	s_waitcnt lgkmcnt(2)
	v_mfma_f32_16x16x32_bf16 v[0:3], v[108:111], v[4:7], v[0:3]
	s_waitcnt lgkmcnt(1)
	v_mfma_f32_16x16x32_bf16 v[0:3], v[104:107], v[56:59], v[0:3]
	s_waitcnt lgkmcnt(0)
	v_mfma_f32_16x16x32_bf16 v[88:91], v[100:103], v[8:11], v[0:3]
	s_nop 5
	s_nop 7
	ds_read_b128 v[0:3], v171 offset:4352
	ds_read_b128 v[4:7], v171 offset:4416
	ds_read_b128 v[56:59], v171 offset:4480
	ds_read_b128 v[8:11], v171 offset:4544
	s_waitcnt lgkmcnt(3)
	v_mfma_f32_16x16x32_bf16 v[0:3], v[112:115], v[0:3], 0
	s_waitcnt lgkmcnt(2)
	v_mfma_f32_16x16x32_bf16 v[0:3], v[108:111], v[4:7], v[0:3]
	s_waitcnt lgkmcnt(1)
	v_mfma_f32_16x16x32_bf16 v[0:3], v[104:107], v[56:59], v[0:3]
	s_waitcnt lgkmcnt(0)
	v_mfma_f32_16x16x32_bf16 v[92:95], v[100:103], v[8:11], v[0:3]
	s_nop 5
	ds_read_b128 v[0:3], v212 offset:13056
	s_waitcnt lgkmcnt(0)
	v_mfma_f32_32x32x16_bf16 v[16:31], v[0:3], v[128:131], 0
	s_nop 11
	v_fma_f32 v5, v133, v54, v16
	v_mfma_f32_32x32x16_bf16 v[34:49], v[0:3], v[124:127], 0
	v_fmac_f32_e32 v5, v132, v15
	s_nop 10
	v_fma_f32 v4, -v133, v15, v34
	v_fmac_f32_e32 v4, v132, v54
	v_fma_f32 v6, -v133, v5, v35
	v_fma_f32 v7, v133, v4, v17
	v_fmac_f32_e32 v6, v132, v4
	v_fmac_f32_e32 v7, v132, v5
	v_fma_f32 v9, v133, v6, v18
	v_fma_f32 v8, -v133, v7, v36
	v_fmac_f32_e32 v9, v132, v7
	v_fmac_f32_e32 v8, v132, v6
	v_fma_f32 v10, -v133, v9, v37
	v_fma_f32 v11, v133, v8, v19
	v_fmac_f32_e32 v10, v132, v8
	v_fmac_f32_e32 v11, v132, v9
	v_fma_f32 v13, v133, v10, v20
	v_fma_f32 v12, -v133, v11, v38
	v_fmac_f32_e32 v13, v132, v11
	v_fmac_f32_e32 v12, v132, v10
	v_fma_f32 v14, -v133, v13, v39
	v_fma_f32 v15, v133, v12, v21
	v_fmac_f32_e32 v14, v132, v12
	v_fmac_f32_e32 v15, v132, v13
	v_fma_f32 v17, v133, v14, v22
	v_fma_f32 v16, -v133, v15, v40
	v_fmac_f32_e32 v17, v132, v15
	v_fmac_f32_e32 v16, v132, v14
	v_fma_f32 v18, -v133, v17, v41
	v_fmac_f32_e32 v18, v132, v16
	v_fma_f32 v19, v133, v16, v23
	v_fmac_f32_e32 v19, v132, v17
	v_fma_f32 v21, v133, v18, v24
	v_fma_f32 v20, -v133, v19, v42
	v_fmac_f32_e32 v21, v132, v19
	v_fmac_f32_e32 v20, v132, v18
	v_fma_f32 v22, -v133, v21, v43
	v_fmac_f32_e32 v22, v132, v20
	v_fma_f32 v23, v133, v20, v25
	v_fmac_f32_e32 v23, v132, v21
	v_fma_f32 v25, v133, v22, v26
	v_fma_f32 v24, -v133, v23, v44
	v_fmac_f32_e32 v25, v132, v23
	v_fmac_f32_e32 v24, v132, v22
	v_fma_f32 v26, -v133, v25, v45
	v_fmac_f32_e32 v26, v132, v24
	v_fma_f32 v27, v133, v24, v27
	v_fmac_f32_e32 v27, v132, v25
	v_fma_f32 v28, v133, v26, v28
	v_fma_f32 v32, -v133, v27, v46
	v_fmac_f32_e32 v28, v132, v27
	v_fmac_f32_e32 v32, v132, v26
	v_fma_f32 v51, -v133, v28, v47
	v_fmac_f32_e32 v51, v132, v32
	v_fma_f32 v29, v133, v32, v29
	v_fmac_f32_e32 v29, v132, v28
	v_fma_f32 v30, v133, v51, v30
	v_fmac_f32_e32 v30, v132, v29
	v_fma_f32 v52, -v133, v29, v48
	v_fma_f32 v53, -v133, v30, v49
	v_cvt_pk_bf16_f32 v54, v4, v5
	v_cvt_pk_bf16_f32 v55, v6, v7
	v_cvt_pk_bf16_f32 v56, v8, v9
	v_cvt_pk_bf16_f32 v57, v10, v11
	v_cvt_pk_bf16_f32 v58, v12, v13
	v_cvt_pk_bf16_f32 v59, v14, v15
	v_cvt_pk_bf16_f32 v60, v16, v17
	v_mfma_f32_32x32x16_bf16 v[34:49], v[0:3], v[120:123], 0
	v_cvt_pk_bf16_f32 v18, v18, v19
	v_cvt_pk_bf16_f32 v19, v20, v21
	v_cvt_pk_bf16_f32 v20, v22, v23
	v_cvt_pk_bf16_f32 v22, v26, v27
	v_cvt_pk_bf16_f32 v23, v32, v28
	v_fmac_f32_e32 v52, v132, v51
	v_cvt_pk_bf16_f32 v21, v24, v25
	v_mfma_f32_32x32x16_bf16 v[2:17], v[0:3], v[116:119], 0
	s_nop 9
	v_fma_f32 v0, -v135, v33, v34
	v_fmac_f32_e32 v0, v134, v50
	v_cvt_pk_bf16_f32 v24, v51, v29
	v_fmac_f32_e32 v31, v133, v52
	v_fmac_f32_e32 v31, v132, v30
	v_cvt_pk_bf16_f32 v25, v52, v30
	v_fmac_f32_e32 v53, v132, v52
	v_fma_f32 v1, v135, v50, v2
	v_fmac_f32_e32 v1, v134, v33
	v_fma_f32 v2, -v135, v1, v35
	v_fma_f32 v3, v135, v0, v3
	v_fmac_f32_e32 v2, v134, v0
	v_fmac_f32_e32 v3, v134, v1
	v_fma_f32 v27, -v135, v3, v36
	v_fma_f32 v4, v135, v2, v4
	v_fmac_f32_e32 v27, v134, v2
	v_fmac_f32_e32 v4, v134, v3
	v_fma_f32 v28, -v135, v4, v37
	v_fma_f32 v5, v135, v27, v5
	v_fmac_f32_e32 v28, v134, v27
	v_fmac_f32_e32 v5, v134, v4
	v_fma_f32 v29, -v135, v5, v38
	v_fma_f32 v6, v135, v28, v6
	v_fmac_f32_e32 v29, v134, v28
	v_fmac_f32_e32 v6, v134, v5
	v_fma_f32 v30, -v135, v6, v39
	v_fma_f32 v7, v135, v29, v7
	v_fmac_f32_e32 v30, v134, v29
	v_fmac_f32_e32 v7, v134, v6
	v_fma_f32 v32, -v135, v7, v40
	v_fma_f32 v8, v135, v30, v8
	v_fmac_f32_e32 v32, v134, v30
	v_fmac_f32_e32 v8, v134, v7
	v_fma_f32 v33, -v135, v8, v41
	v_fma_f32 v9, v135, v32, v9
	v_fmac_f32_e32 v33, v134, v32
	v_fmac_f32_e32 v9, v134, v8
	v_fma_f32 v34, -v135, v9, v42
	v_fma_f32 v10, v135, v33, v10
	v_cvt_pk_bf16_f32 v0, v0, v1
	v_fmac_f32_e32 v34, v134, v33
	v_fmac_f32_e32 v10, v134, v9
	ds_write2_b32 v169, v54, v0 offset1:32
	v_cvt_pk_bf16_f32 v0, v2, v3
	v_fma_f32 v35, -v135, v10, v43
	v_fma_f32 v11, v135, v34, v11
	ds_write2_b32 v169, v55, v0 offset0:68 offset1:100
	v_cvt_pk_bf16_f32 v0, v27, v4
	v_fmac_f32_e32 v35, v134, v34
	v_fmac_f32_e32 v11, v134, v10
	ds_write2_b32 v169, v56, v0 offset0:136 offset1:168
	v_cvt_pk_bf16_f32 v0, v28, v5
	v_fma_f32 v36, -v135, v11, v44
	v_fma_f32 v12, v135, v35, v12
	ds_write2_b32 v169, v57, v0 offset0:204 offset1:236
	v_cvt_pk_bf16_f32 v0, v29, v6
	v_fmac_f32_e32 v36, v134, v35
	v_fmac_f32_e32 v12, v134, v11
	ds_write2_b32 v213, v58, v0 offset0:16 offset1:48
	v_cvt_pk_bf16_f32 v0, v30, v7
	v_fma_f32 v37, -v135, v12, v45
	v_fma_f32 v13, v135, v36, v13
	ds_write2_b32 v213, v59, v0 offset0:84 offset1:116
	v_cvt_pk_bf16_f32 v0, v32, v8
	v_fmac_f32_e32 v37, v134, v36
	v_fmac_f32_e32 v13, v134, v12
	ds_write2_b32 v213, v60, v0 offset0:152 offset1:184
	v_cvt_pk_bf16_f32 v0, v33, v9
	v_fma_f32 v38, -v135, v13, v46
	v_fma_f32 v14, v135, v37, v14
	ds_write2_b32 v213, v18, v0 offset0:220 offset1:252
	v_cvt_pk_bf16_f32 v0, v34, v10
	v_fmac_f32_e32 v38, v134, v37
	v_fmac_f32_e32 v14, v134, v13
	ds_write2_b32 v214, v19, v0 offset0:32 offset1:64
	v_cvt_pk_bf16_f32 v0, v35, v11
	v_fma_f32 v39, -v135, v14, v47
	v_fma_f32 v15, v135, v38, v15
	ds_write2_b32 v214, v20, v0 offset0:100 offset1:132
	v_cvt_pk_bf16_f32 v0, v36, v12
	v_fmac_f32_e32 v39, v134, v38
	v_fmac_f32_e32 v15, v134, v14
	ds_write2_b32 v214, v21, v0 offset0:168 offset1:200
	v_cvt_pk_bf16_f32 v0, v37, v13
	v_fma_f32 v40, -v135, v15, v48
	v_fma_f32 v16, v135, v39, v16
	ds_write2_b32 v217, v22, v0 offset0:108 offset1:140
	v_cvt_pk_bf16_f32 v0, v38, v14
	v_fmac_f32_e32 v40, v134, v39
	v_fmac_f32_e32 v16, v134, v15
	ds_write2_b32 v215, v23, v0 offset0:48 offset1:80
	v_cvt_pk_bf16_f32 v0, v39, v15
	v_fma_f32 v50, -v135, v16, v49
	v_fmac_f32_e32 v17, v135, v40
	ds_write2_b32 v215, v24, v0 offset0:116 offset1:148
	v_cvt_pk_bf16_f32 v0, v40, v16
	v_cvt_pk_bf16_f32 v26, v53, v31
	v_fmac_f32_e32 v50, v134, v40
	v_fmac_f32_e32 v17, v134, v16
	ds_write2_b32 v215, v25, v0 offset0:184 offset1:216
	v_cvt_pk_bf16_f32 v0, v50, v17
	ds_write2_b32 v216, v26, v0 offset0:124 offset1:156
	s_nop 7
	ds_read_b128 v[0:3], v171
	ds_read_b128 v[4:7], v171 offset:64
	ds_read_b128 v[20:23], v171 offset:128
	ds_read_b128 v[8:11], v171 offset:192
	s_waitcnt lgkmcnt(3)
	v_mfma_f32_16x16x32_bf16 v[0:3], v[112:115], v[0:3], 0
	s_waitcnt lgkmcnt(2)
	v_mfma_f32_16x16x32_bf16 v[0:3], v[108:111], v[4:7], v[0:3]
	s_waitcnt lgkmcnt(1)
	v_mfma_f32_16x16x32_bf16 v[0:3], v[104:107], v[20:23], v[0:3]
	s_waitcnt lgkmcnt(0)
	v_mfma_f32_16x16x32_bf16 v[76:79], v[100:103], v[8:11], v[0:3]
	s_nop 5
	s_nop 7
	ds_read_b128 v[0:3], v171 offset:4352
	ds_read_b128 v[4:7], v171 offset:4416
	ds_read_b128 v[20:23], v171 offset:4480
	ds_read_b128 v[8:11], v171 offset:4544
	s_waitcnt lgkmcnt(3)
	v_mfma_f32_16x16x32_bf16 v[0:3], v[112:115], v[0:3], 0
	s_waitcnt lgkmcnt(2)
	v_mfma_f32_16x16x32_bf16 v[0:3], v[108:111], v[4:7], v[0:3]
	s_waitcnt lgkmcnt(1)
	v_mfma_f32_16x16x32_bf16 v[0:3], v[104:107], v[20:23], v[0:3]
	s_waitcnt lgkmcnt(0)
	v_mfma_f32_16x16x32_bf16 v[96:99], v[100:103], v[8:11], v[0:3]
	ds_read_b128 v[18:21], v212 offset:17408
	s_waitcnt lgkmcnt(0)
	v_mfma_f32_32x32x16_bf16 v[0:15], v[18:21], v[128:131], 0
	s_nop 11
	v_fma_f32 v0, v133, v53, v0
	v_mfma_f32_32x32x16_bf16 v[32:47], v[18:21], v[124:127], 0
	v_fmac_f32_e32 v0, v132, v31
	s_nop 10
	v_fma_f32 v16, -v133, v31, v32
	v_fmac_f32_e32 v16, v132, v53
	v_fma_f32 v22, -v133, v0, v33
	v_fma_f32 v1, v133, v16, v1
	v_fmac_f32_e32 v22, v132, v16
	v_fmac_f32_e32 v1, v132, v0
	v_fma_f32 v2, v133, v22, v2
	v_fma_f32 v23, -v133, v1, v34
	v_fmac_f32_e32 v2, v132, v1
	v_fmac_f32_e32 v23, v132, v22
	v_fma_f32 v24, -v133, v2, v35
	v_fma_f32 v3, v133, v23, v3
	v_fmac_f32_e32 v24, v132, v23
	v_fmac_f32_e32 v3, v132, v2
	v_fma_f32 v4, v133, v24, v4
	v_fma_f32 v25, -v133, v3, v36
	v_fmac_f32_e32 v4, v132, v3
	v_fmac_f32_e32 v25, v132, v24
	v_fma_f32 v26, -v133, v4, v37
	v_fma_f32 v5, v133, v25, v5
	v_fmac_f32_e32 v26, v132, v25
	v_fmac_f32_e32 v5, v132, v4
	v_fma_f32 v6, v133, v26, v6
	v_fma_f32 v27, -v133, v5, v38
	v_fmac_f32_e32 v6, v132, v5
	v_fmac_f32_e32 v27, v132, v26
	v_fma_f32 v28, -v133, v6, v39
	v_fmac_f32_e32 v28, v132, v27
	v_fma_f32 v7, v133, v27, v7
	v_fmac_f32_e32 v7, v132, v6
	v_fma_f32 v8, v133, v28, v8
	v_fma_f32 v29, -v133, v7, v40
	v_fmac_f32_e32 v8, v132, v7
	v_fmac_f32_e32 v29, v132, v28
	v_fma_f32 v30, -v133, v8, v41
	v_fmac_f32_e32 v30, v132, v29
	v_fma_f32 v9, v133, v29, v9
	v_fmac_f32_e32 v9, v132, v8
	v_fma_f32 v10, v133, v30, v10
	v_fma_f32 v31, -v133, v9, v42
	v_fmac_f32_e32 v10, v132, v9
	v_fmac_f32_e32 v31, v132, v30
	v_fma_f32 v32, -v133, v10, v43
	v_fmac_f32_e32 v32, v132, v31
	v_fma_f32 v11, v133, v31, v11
	v_fmac_f32_e32 v11, v132, v10
	v_fma_f32 v12, v133, v32, v12
	v_fma_f32 v33, -v133, v11, v44
	v_fmac_f32_e32 v12, v132, v11
	v_fmac_f32_e32 v33, v132, v32
	v_fma_f32 v51, -v133, v12, v45
	v_fmac_f32_e32 v51, v132, v33
	v_fma_f32 v13, v133, v33, v13
	v_fmac_f32_e32 v13, v132, v12
	v_fma_f32 v14, v133, v51, v14
	v_fmac_f32_e32 v14, v132, v13
	v_fma_f32 v52, -v133, v13, v46
	v_fma_f32 v53, -v133, v14, v47
	v_cvt_pk_bf16_f32 v1, v22, v1
	v_cvt_pk_bf16_f32 v2, v23, v2
	v_cvt_pk_bf16_f32 v3, v24, v3
	v_cvt_pk_bf16_f32 v4, v25, v4
	v_cvt_pk_bf16_f32 v5, v26, v5
	v_cvt_pk_bf16_f32 v6, v27, v6
	v_cvt_pk_bf16_f32 v7, v28, v7
	v_cvt_pk_bf16_f32 v8, v29, v8
	v_mfma_f32_32x32x16_bf16 v[34:49], v[18:21], v[120:123], 0
	v_cvt_pk_bf16_f32 v9, v30, v9
	v_cvt_pk_bf16_f32 v10, v31, v10
	v_cvt_pk_bf16_f32 v11, v32, v11
	v_cvt_pk_bf16_f32 v12, v33, v12
	v_cvt_pk_bf16_f32 v0, v16, v0
	v_fmac_f32_e32 v52, v132, v51
	v_fmac_f32_e32 v15, v133, v52
	v_mfma_f32_32x32x16_bf16 v[18:33], v[18:21], v[116:119], 0
	s_nop 8
	v_fma_f32 v34, -v135, v17, v34
	v_fmac_f32_e32 v34, v134, v50
	v_cvt_pk_bf16_f32 v13, v51, v13
	v_fmac_f32_e32 v53, v132, v52
	v_fmac_f32_e32 v15, v132, v14
	v_cvt_pk_bf16_f32 v14, v52, v14
	v_cvt_pk_bf16_f32 v16, v53, v15
	v_fma_f32 v18, v135, v50, v18
	v_fmac_f32_e32 v18, v134, v17
	v_fma_f32 v17, -v135, v18, v35
	v_fma_f32 v19, v135, v34, v19
	v_fmac_f32_e32 v17, v134, v34
	v_fmac_f32_e32 v19, v134, v18
	v_fma_f32 v35, -v135, v19, v36
	v_fma_f32 v20, v135, v17, v20
	v_fmac_f32_e32 v35, v134, v17
	v_fmac_f32_e32 v20, v134, v19
	v_fma_f32 v36, -v135, v20, v37
	v_fma_f32 v21, v135, v35, v21
	v_fmac_f32_e32 v36, v134, v35
	v_fmac_f32_e32 v21, v134, v20
	v_fma_f32 v37, -v135, v21, v38
	v_fma_f32 v22, v135, v36, v22
	v_fmac_f32_e32 v37, v134, v36
	v_fmac_f32_e32 v22, v134, v21
	v_fma_f32 v38, -v135, v22, v39
	v_fma_f32 v23, v135, v37, v23
	v_fmac_f32_e32 v38, v134, v37
	v_fmac_f32_e32 v23, v134, v22
	v_fma_f32 v39, -v135, v23, v40
	v_fma_f32 v24, v135, v38, v24
	v_fmac_f32_e32 v39, v134, v38
	v_fmac_f32_e32 v24, v134, v23
	v_fma_f32 v40, -v135, v24, v41
	v_fma_f32 v25, v135, v39, v25
	v_fmac_f32_e32 v40, v134, v39
	v_fmac_f32_e32 v25, v134, v24
	v_fma_f32 v41, -v135, v25, v42
	v_fma_f32 v26, v135, v40, v26
	v_fmac_f32_e32 v41, v134, v40
	v_fmac_f32_e32 v26, v134, v25
	v_cvt_pk_bf16_f32 v18, v34, v18
	ds_write2_b32 v169, v0, v18 offset1:32
	v_cvt_pk_bf16_f32 v0, v17, v19
	v_fma_f32 v42, -v135, v26, v43
	v_fma_f32 v27, v135, v41, v27
	ds_write2_b32 v169, v1, v0 offset0:68 offset1:100
	v_cvt_pk_bf16_f32 v0, v35, v20
	v_fmac_f32_e32 v42, v134, v41
	v_fmac_f32_e32 v27, v134, v26
	ds_write2_b32 v169, v2, v0 offset0:136 offset1:168
	v_cvt_pk_bf16_f32 v0, v36, v21
	v_fma_f32 v43, -v135, v27, v44
	v_fma_f32 v28, v135, v42, v28
	ds_write2_b32 v169, v3, v0 offset0:204 offset1:236
	v_cvt_pk_bf16_f32 v0, v37, v22
	v_fmac_f32_e32 v43, v134, v42
	v_fmac_f32_e32 v28, v134, v27
	ds_write2_b32 v213, v4, v0 offset0:16 offset1:48
	v_cvt_pk_bf16_f32 v0, v38, v23
	v_fma_f32 v44, -v135, v28, v45
	v_fma_f32 v29, v135, v43, v29
	ds_write2_b32 v213, v5, v0 offset0:84 offset1:116
	v_cvt_pk_bf16_f32 v0, v39, v24
	v_fmac_f32_e32 v44, v134, v43
	v_fmac_f32_e32 v29, v134, v28
	ds_write2_b32 v213, v6, v0 offset0:152 offset1:184
	v_cvt_pk_bf16_f32 v0, v40, v25
	v_fma_f32 v45, -v135, v29, v46
	v_fma_f32 v30, v135, v44, v30
	ds_write2_b32 v213, v7, v0 offset0:220 offset1:252
	v_cvt_pk_bf16_f32 v0, v41, v26
	v_fmac_f32_e32 v45, v134, v44
	v_fmac_f32_e32 v30, v134, v29
	ds_write2_b32 v214, v8, v0 offset0:32 offset1:64
	v_cvt_pk_bf16_f32 v0, v42, v27
	v_fma_f32 v46, -v135, v30, v47
	v_fma_f32 v31, v135, v45, v31
	ds_write2_b32 v214, v9, v0 offset0:100 offset1:132
	v_cvt_pk_bf16_f32 v0, v43, v28
	v_fmac_f32_e32 v46, v134, v45
	v_fmac_f32_e32 v31, v134, v30
	ds_write2_b32 v214, v10, v0 offset0:168 offset1:200
	v_cvt_pk_bf16_f32 v0, v44, v29
	v_fma_f32 v47, -v135, v31, v48
	v_fma_f32 v32, v135, v46, v32
	ds_write2_b32 v217, v11, v0 offset0:108 offset1:140
	v_cvt_pk_bf16_f32 v0, v45, v30
	v_fmac_f32_e32 v47, v134, v46
	v_fmac_f32_e32 v32, v134, v31
	ds_write2_b32 v215, v12, v0 offset0:48 offset1:80
	v_cvt_pk_bf16_f32 v0, v46, v31
	v_fma_f32 v50, -v135, v32, v49
	v_fmac_f32_e32 v33, v135, v47
	ds_write2_b32 v215, v13, v0 offset0:116 offset1:148
	v_cvt_pk_bf16_f32 v0, v47, v32
	v_fmac_f32_e32 v50, v134, v47
	v_fmac_f32_e32 v33, v134, v32
	ds_write2_b32 v215, v14, v0 offset0:184 offset1:216
	v_cvt_pk_bf16_f32 v0, v50, v33
	ds_write2_b32 v216, v16, v0 offset0:124 offset1:156
	s_nop 7
	ds_read_b128 v[0:3], v171
	ds_read_b128 v[4:7], v171 offset:64
	ds_read_b128 v[54:57], v171 offset:128
	ds_read_b128 v[8:11], v171 offset:192
	s_waitcnt lgkmcnt(3)
	v_mfma_f32_16x16x32_bf16 v[0:3], v[112:115], v[0:3], 0
	s_waitcnt lgkmcnt(2)
	v_mfma_f32_16x16x32_bf16 v[0:3], v[108:111], v[4:7], v[0:3]
	s_waitcnt lgkmcnt(1)
	v_mfma_f32_16x16x32_bf16 v[0:3], v[104:107], v[54:57], v[0:3]
	s_waitcnt lgkmcnt(0)
	v_mfma_f32_16x16x32_bf16 v[140:143], v[100:103], v[8:11], v[0:3]
	s_nop 5
	s_nop 7
	ds_read_b128 v[0:3], v171 offset:4352
	ds_read_b128 v[4:7], v171 offset:4416
	ds_read_b128 v[54:57], v171 offset:4480
	ds_read_b128 v[8:11], v171 offset:4544
	s_waitcnt lgkmcnt(3)
	v_mfma_f32_16x16x32_bf16 v[0:3], v[112:115], v[0:3], 0
	s_waitcnt lgkmcnt(2)
	v_mfma_f32_16x16x32_bf16 v[0:3], v[108:111], v[4:7], v[0:3]
	s_waitcnt lgkmcnt(1)
	v_mfma_f32_16x16x32_bf16 v[0:3], v[104:107], v[54:57], v[0:3]
	s_waitcnt lgkmcnt(0)
	v_mfma_f32_16x16x32_bf16 v[144:147], v[100:103], v[8:11], v[0:3]
	s_nop 5
	ds_read_b128 v[0:3], v212 offset:21760
	s_waitcnt lgkmcnt(0)
	v_mfma_f32_32x32x16_bf16 v[16:31], v[0:3], v[128:131], 0
	s_nop 11
	v_fma_f32 v5, v133, v53, v16
	v_mfma_f32_32x32x16_bf16 v[34:49], v[0:3], v[124:127], 0
	v_fmac_f32_e32 v5, v132, v15
	s_nop 10
	v_fma_f32 v4, -v133, v15, v34
	v_fmac_f32_e32 v4, v132, v53
	v_fma_f32 v6, -v133, v5, v35
	v_fma_f32 v7, v133, v4, v17
	v_fmac_f32_e32 v6, v132, v4
	v_fmac_f32_e32 v7, v132, v5
	v_fma_f32 v9, v133, v6, v18
	v_fma_f32 v8, -v133, v7, v36
	v_fmac_f32_e32 v9, v132, v7
	v_fmac_f32_e32 v8, v132, v6
	v_fma_f32 v10, -v133, v9, v37
	v_fma_f32 v11, v133, v8, v19
	v_fmac_f32_e32 v10, v132, v8
	v_fmac_f32_e32 v11, v132, v9
	v_fma_f32 v13, v133, v10, v20
	v_fma_f32 v12, -v133, v11, v38
	v_fmac_f32_e32 v13, v132, v11
	v_fmac_f32_e32 v12, v132, v10
	v_fma_f32 v14, -v133, v13, v39
	v_fma_f32 v15, v133, v12, v21
	v_fmac_f32_e32 v14, v132, v12
	v_fmac_f32_e32 v15, v132, v13
	v_fma_f32 v17, v133, v14, v22
	v_fma_f32 v16, -v133, v15, v40
	v_fmac_f32_e32 v17, v132, v15
	v_fmac_f32_e32 v16, v132, v14
	v_fma_f32 v18, -v133, v17, v41
	v_fmac_f32_e32 v18, v132, v16
	v_fma_f32 v19, v133, v16, v23
	v_fmac_f32_e32 v19, v132, v17
	v_fma_f32 v21, v133, v18, v24
	v_fma_f32 v20, -v133, v19, v42
	v_fmac_f32_e32 v21, v132, v19
	v_fmac_f32_e32 v20, v132, v18
	v_fma_f32 v22, -v133, v21, v43
	v_fmac_f32_e32 v22, v132, v20
	v_fma_f32 v23, v133, v20, v25
	v_fmac_f32_e32 v23, v132, v21
	v_fma_f32 v25, v133, v22, v26
	v_fma_f32 v24, -v133, v23, v44
	v_fmac_f32_e32 v25, v132, v23
	v_fmac_f32_e32 v24, v132, v22
	v_fma_f32 v26, -v133, v25, v45
	v_fmac_f32_e32 v26, v132, v24
	v_fma_f32 v27, v133, v24, v27
	v_fmac_f32_e32 v27, v132, v25
	v_fma_f32 v28, v133, v26, v28
	v_fma_f32 v32, -v133, v27, v46
	v_fmac_f32_e32 v28, v132, v27
	v_fmac_f32_e32 v32, v132, v26
	v_fma_f32 v51, -v133, v28, v47
	v_fmac_f32_e32 v51, v132, v32
	v_fma_f32 v29, v133, v32, v29
	v_fmac_f32_e32 v29, v132, v28
	v_fma_f32 v30, v133, v51, v30
	v_fmac_f32_e32 v30, v132, v29
	v_fma_f32 v52, -v133, v29, v48
	v_fma_f32 v72, -v133, v30, v49
	v_cvt_pk_bf16_f32 v53, v4, v5
	v_cvt_pk_bf16_f32 v54, v6, v7
	v_cvt_pk_bf16_f32 v55, v8, v9
	v_cvt_pk_bf16_f32 v56, v10, v11
	v_cvt_pk_bf16_f32 v57, v12, v13
	v_cvt_pk_bf16_f32 v58, v14, v15
	v_mfma_f32_32x32x16_bf16 v[34:49], v[0:3], v[120:123], 0
	v_cvt_pk_bf16_f32 v16, v16, v17
	v_cvt_pk_bf16_f32 v17, v18, v19
	v_cvt_pk_bf16_f32 v18, v20, v21
	v_cvt_pk_bf16_f32 v21, v26, v27
	v_cvt_pk_bf16_f32 v19, v22, v23
	v_cvt_pk_bf16_f32 v22, v32, v28
	v_fmac_f32_e32 v52, v132, v51
	v_mfma_f32_32x32x16_bf16 v[0:15], v[0:3], v[116:119], 0
	s_nop 9
	v_fma_f32 v26, -v135, v33, v34
	v_fmac_f32_e32 v26, v134, v50
	v_cvt_pk_bf16_f32 v23, v51, v29
	v_fmac_f32_e32 v31, v133, v52
	v_fmac_f32_e32 v31, v132, v30
	v_cvt_pk_bf16_f32 v20, v24, v25
	v_cvt_pk_bf16_f32 v24, v52, v30
	v_fma_f32 v0, v135, v50, v0
	v_fmac_f32_e32 v0, v134, v33
	v_fma_f32 v27, -v135, v0, v35
	v_fma_f32 v1, v135, v26, v1
	v_fmac_f32_e32 v27, v134, v26
	v_fmac_f32_e32 v1, v134, v0
	v_fma_f32 v28, -v135, v1, v36
	v_fma_f32 v2, v135, v27, v2
	v_fmac_f32_e32 v28, v134, v27
	v_fmac_f32_e32 v2, v134, v1
	v_fma_f32 v29, -v135, v2, v37
	v_fma_f32 v3, v135, v28, v3
	v_fmac_f32_e32 v29, v134, v28
	v_fmac_f32_e32 v3, v134, v2
	v_fma_f32 v30, -v135, v3, v38
	v_fma_f32 v4, v135, v29, v4
	v_fmac_f32_e32 v30, v134, v29
	v_fmac_f32_e32 v4, v134, v3
	v_fma_f32 v32, -v135, v4, v39
	v_fma_f32 v5, v135, v30, v5
	v_fmac_f32_e32 v32, v134, v30
	v_fmac_f32_e32 v5, v134, v4
	v_fma_f32 v33, -v135, v5, v40
	v_fma_f32 v6, v135, v32, v6
	v_fmac_f32_e32 v33, v134, v32
	v_fmac_f32_e32 v6, v134, v5
	v_fma_f32 v34, -v135, v6, v41
	v_fma_f32 v7, v135, v33, v7
	v_fmac_f32_e32 v34, v134, v33
	v_fmac_f32_e32 v7, v134, v6
	v_fma_f32 v35, -v135, v7, v42
	v_fma_f32 v8, v135, v34, v8
	v_cvt_pk_bf16_f32 v0, v26, v0
	v_fmac_f32_e32 v35, v134, v34
	v_fmac_f32_e32 v8, v134, v7
	ds_write2_b32 v169, v53, v0 offset1:32
	v_cvt_pk_bf16_f32 v0, v27, v1
	v_fma_f32 v36, -v135, v8, v43
	v_fma_f32 v9, v135, v35, v9
	ds_write2_b32 v169, v54, v0 offset0:68 offset1:100
	v_cvt_pk_bf16_f32 v0, v28, v2
	v_fmac_f32_e32 v36, v134, v35
	v_fmac_f32_e32 v9, v134, v8
	ds_write2_b32 v169, v55, v0 offset0:136 offset1:168
	v_cvt_pk_bf16_f32 v0, v29, v3
	v_fma_f32 v37, -v135, v9, v44
	v_fma_f32 v10, v135, v36, v10
	ds_write2_b32 v169, v56, v0 offset0:204 offset1:236
	v_cvt_pk_bf16_f32 v0, v30, v4
	v_fmac_f32_e32 v37, v134, v36
	v_fmac_f32_e32 v10, v134, v9
	ds_write2_b32 v213, v57, v0 offset0:16 offset1:48
	v_cvt_pk_bf16_f32 v0, v32, v5
	v_fma_f32 v38, -v135, v10, v45
	v_fma_f32 v11, v135, v37, v11
	ds_write2_b32 v213, v58, v0 offset0:84 offset1:116
	v_cvt_pk_bf16_f32 v0, v33, v6
	v_fmac_f32_e32 v38, v134, v37
	v_fmac_f32_e32 v11, v134, v10
	ds_write2_b32 v213, v16, v0 offset0:152 offset1:184
	v_cvt_pk_bf16_f32 v0, v34, v7
	v_fma_f32 v39, -v135, v11, v46
	v_fma_f32 v12, v135, v38, v12
	ds_write2_b32 v213, v17, v0 offset0:220 offset1:252
	v_cvt_pk_bf16_f32 v0, v35, v8
	v_fmac_f32_e32 v39, v134, v38
	v_fmac_f32_e32 v12, v134, v11
	ds_write2_b32 v214, v18, v0 offset0:32 offset1:64
	v_cvt_pk_bf16_f32 v0, v36, v9
	v_fma_f32 v40, -v135, v12, v47
	v_fma_f32 v13, v135, v39, v13
	ds_write2_b32 v214, v19, v0 offset0:100 offset1:132
	v_cvt_pk_bf16_f32 v0, v37, v10
	v_fmac_f32_e32 v40, v134, v39
	v_fmac_f32_e32 v13, v134, v12
	ds_write2_b32 v214, v20, v0 offset0:168 offset1:200
	v_cvt_pk_bf16_f32 v0, v38, v11
	v_fma_f32 v41, -v135, v13, v48
	v_fma_f32 v14, v135, v40, v14
	ds_write2_b32 v217, v21, v0 offset0:108 offset1:140
	v_cvt_pk_bf16_f32 v0, v39, v12
	v_fmac_f32_e32 v41, v134, v40
	v_fmac_f32_e32 v14, v134, v13
	ds_write2_b32 v215, v22, v0 offset0:48 offset1:80
	v_cvt_pk_bf16_f32 v0, v40, v13
	v_fma_f32 v73, -v135, v14, v49
	v_fmac_f32_e32 v15, v135, v41
	ds_write2_b32 v215, v23, v0 offset0:116 offset1:148
	v_cvt_pk_bf16_f32 v0, v41, v14
	v_fmac_f32_e32 v72, v132, v52
	v_cvt_pk_bf16_f32 v25, v72, v31
	v_fmac_f32_e32 v73, v134, v41
	v_fmac_f32_e32 v15, v134, v14
	ds_write2_b32 v215, v24, v0 offset0:184 offset1:216
	v_cvt_pk_bf16_f32 v0, v73, v15
	ds_write2_b32 v216, v25, v0 offset0:124 offset1:156
	s_nop 7
	ds_read_b128 v[0:3], v171
	ds_read_b128 v[4:7], v171 offset:64
	ds_read_b128 v[16:19], v171 offset:128
	ds_read_b128 v[8:11], v171 offset:192
	s_waitcnt lgkmcnt(3)
	v_mfma_f32_16x16x32_bf16 v[0:3], v[112:115], v[0:3], 0
	s_waitcnt lgkmcnt(2)
	v_mfma_f32_16x16x32_bf16 v[0:3], v[108:111], v[4:7], v[0:3]
	s_waitcnt lgkmcnt(1)
	v_mfma_f32_16x16x32_bf16 v[0:3], v[104:107], v[16:19], v[0:3]
	s_waitcnt lgkmcnt(0)
	v_mfma_f32_16x16x32_bf16 v[148:151], v[100:103], v[8:11], v[0:3]
	s_nop 5
	s_nop 7
	ds_read_b128 v[0:3], v171 offset:4352
	ds_read_b128 v[4:7], v171 offset:4416
	ds_read_b128 v[16:19], v171 offset:4480
	ds_read_b128 v[8:11], v171 offset:4544
	s_waitcnt lgkmcnt(3)
	v_mfma_f32_16x16x32_bf16 v[0:3], v[112:115], v[0:3], 0
	s_waitcnt lgkmcnt(2)
	v_mfma_f32_16x16x32_bf16 v[0:3], v[108:111], v[4:7], v[0:3]
	s_waitcnt lgkmcnt(1)
	v_mfma_f32_16x16x32_bf16 v[0:3], v[104:107], v[16:19], v[0:3]
	s_waitcnt lgkmcnt(0)
	v_mfma_f32_16x16x32_bf16 v[152:155], v[100:103], v[8:11], v[0:3]
	s_nop 5
	ds_read_b128 v[0:3], v212 offset:26112
	s_waitcnt lgkmcnt(0)
	v_mfma_f32_32x32x16_bf16 v[32:47], v[0:3], v[128:131], 0
	s_nop 11
	v_fma_f32 v5, v133, v72, v32
	v_mfma_f32_32x32x16_bf16 v[48:63], v[0:3], v[124:127], 0
	v_fmac_f32_e32 v5, v132, v31
	s_nop 10
	v_fma_f32 v4, -v133, v31, v48
	v_fmac_f32_e32 v4, v132, v72
	v_fma_f32 v6, -v133, v5, v49
	v_fma_f32 v7, v133, v4, v33
	v_fmac_f32_e32 v6, v132, v4
	v_fmac_f32_e32 v7, v132, v5
	v_fma_f32 v9, v133, v6, v34
	v_fma_f32 v8, -v133, v7, v50
	v_fmac_f32_e32 v9, v132, v7
	v_fmac_f32_e32 v8, v132, v6
	v_fma_f32 v10, -v133, v9, v51
	v_fma_f32 v11, v133, v8, v35
	v_fmac_f32_e32 v10, v132, v8
	v_fmac_f32_e32 v11, v132, v9
	v_fma_f32 v13, v133, v10, v36
	v_fma_f32 v12, -v133, v11, v52
	v_fmac_f32_e32 v13, v132, v11
	v_fmac_f32_e32 v12, v132, v10
	v_fma_f32 v14, -v133, v13, v53
	v_fma_f32 v16, v133, v12, v37
	v_fmac_f32_e32 v14, v132, v12
	v_fmac_f32_e32 v16, v132, v13
	v_fma_f32 v18, v133, v14, v38
	v_fma_f32 v17, -v133, v16, v54
	v_fmac_f32_e32 v18, v132, v16
	v_fmac_f32_e32 v17, v132, v14
	v_fma_f32 v19, -v133, v18, v55
	v_fmac_f32_e32 v19, v132, v17
	v_fma_f32 v20, v133, v17, v39
	v_fmac_f32_e32 v20, v132, v18
	v_fma_f32 v22, v133, v19, v40
	v_fma_f32 v21, -v133, v20, v56
	v_fmac_f32_e32 v22, v132, v20
	v_fmac_f32_e32 v21, v132, v19
	v_fma_f32 v23, -v133, v22, v57
	v_fmac_f32_e32 v23, v132, v21
	v_fma_f32 v24, v133, v21, v41
	v_fmac_f32_e32 v24, v132, v22
	v_fma_f32 v26, v133, v23, v42
	v_fma_f32 v25, -v133, v24, v58
	v_fmac_f32_e32 v26, v132, v24
	v_fmac_f32_e32 v25, v132, v23
	v_fma_f32 v27, -v133, v26, v59
	v_fmac_f32_e32 v27, v132, v25
	v_fma_f32 v28, v133, v25, v43
	v_fmac_f32_e32 v28, v132, v26
	v_fma_f32 v30, v133, v27, v44
	v_fma_f32 v29, -v133, v28, v60
	v_fmac_f32_e32 v30, v132, v28
	v_fmac_f32_e32 v29, v132, v27
	v_fma_f32 v31, -v133, v30, v61
	v_fmac_f32_e32 v31, v132, v29
	v_fma_f32 v32, v133, v29, v45
	v_fmac_f32_e32 v32, v132, v30
	v_fma_f32 v34, v133, v31, v46
	v_fma_f32 v33, -v133, v32, v62
	v_fmac_f32_e32 v34, v132, v32
	v_fmac_f32_e32 v33, v132, v31
	v_fma_f32 v35, -v133, v34, v63
	v_cvt_pk_bf16_f32 v4, v4, v5
	v_cvt_pk_bf16_f32 v5, v6, v7
	v_cvt_pk_bf16_f32 v6, v8, v9
	v_cvt_pk_bf16_f32 v7, v10, v11
	v_cvt_pk_bf16_f32 v8, v12, v13
	v_cvt_pk_bf16_f32 v9, v14, v16
	v_cvt_pk_bf16_f32 v10, v17, v18
	v_cvt_pk_bf16_f32 v11, v19, v20
	v_cvt_pk_bf16_f32 v12, v21, v22
	v_mfma_f32_32x32x16_bf16 v[48:63], v[0:3], v[120:123], 0
	v_cvt_pk_bf16_f32 v13, v23, v24
	v_cvt_pk_bf16_f32 v14, v25, v26
	v_cvt_pk_bf16_f32 v36, v27, v28
	v_cvt_pk_bf16_f32 v37, v29, v30
	v_cvt_pk_bf16_f32 v32, v31, v32
	v_fmac_f32_e32 v47, v133, v33
	v_fmac_f32_e32 v35, v132, v33
	v_mfma_f32_32x32x16_bf16 v[16:31], v[0:3], v[116:119], 0
	s_nop 8
	v_fma_f32 v0, -v135, v15, v48
	v_fmac_f32_e32 v0, v134, v73
	v_fmac_f32_e32 v47, v132, v34
	v_cvt_pk_bf16_f32 v33, v33, v34
	v_cvt_pk_bf16_f32 v34, v35, v47
	v_fma_f32 v1, v135, v73, v16
	v_fmac_f32_e32 v1, v134, v15
	v_fma_f32 v2, -v135, v1, v49
	v_fma_f32 v3, v135, v0, v17
	v_fmac_f32_e32 v2, v134, v0
	v_fmac_f32_e32 v3, v134, v1
	v_fma_f32 v15, -v135, v3, v50
	v_fma_f32 v16, v135, v2, v18
	v_fmac_f32_e32 v15, v134, v2
	v_fmac_f32_e32 v16, v134, v3
	v_fma_f32 v17, -v135, v16, v51
	v_fma_f32 v18, v135, v15, v19
	v_fmac_f32_e32 v17, v134, v15
	v_fmac_f32_e32 v18, v134, v16
	v_fma_f32 v19, -v135, v18, v52
	v_fma_f32 v20, v135, v17, v20
	v_fmac_f32_e32 v19, v134, v17
	v_fmac_f32_e32 v20, v134, v18
	v_fma_f32 v38, -v135, v20, v53
	v_fma_f32 v21, v135, v19, v21
	v_fmac_f32_e32 v38, v134, v19
	v_fmac_f32_e32 v21, v134, v20
	v_fma_f32 v39, -v135, v21, v54
	v_fma_f32 v22, v135, v38, v22
	v_fmac_f32_e32 v39, v134, v38
	v_fmac_f32_e32 v22, v134, v21
	v_fma_f32 v40, -v135, v22, v55
	v_fma_f32 v23, v135, v39, v23
	v_fmac_f32_e32 v40, v134, v39
	v_fmac_f32_e32 v23, v134, v22
	v_fma_f32 v41, -v135, v23, v56
	v_fma_f32 v24, v135, v40, v24
	v_cvt_pk_bf16_f32 v0, v0, v1
	v_fmac_f32_e32 v41, v134, v40
	v_fmac_f32_e32 v24, v134, v23
	ds_write2_b32 v169, v4, v0 offset1:32
	v_cvt_pk_bf16_f32 v0, v2, v3
	v_fma_f32 v42, -v135, v24, v57
	v_fma_f32 v25, v135, v41, v25
	ds_write2_b32 v169, v5, v0 offset0:68 offset1:100
	v_cvt_pk_bf16_f32 v0, v15, v16
	v_fmac_f32_e32 v42, v134, v41
	v_fmac_f32_e32 v25, v134, v24
	ds_write2_b32 v169, v6, v0 offset0:136 offset1:168
	v_cvt_pk_bf16_f32 v0, v17, v18
	v_fma_f32 v43, -v135, v25, v58
	v_fma_f32 v26, v135, v42, v26
	ds_write2_b32 v169, v7, v0 offset0:204 offset1:236
	v_cvt_pk_bf16_f32 v0, v19, v20
	v_fmac_f32_e32 v43, v134, v42
	v_fmac_f32_e32 v26, v134, v25
	ds_write2_b32 v213, v8, v0 offset0:16 offset1:48
	v_cvt_pk_bf16_f32 v0, v38, v21
	v_fma_f32 v44, -v135, v26, v59
	v_fma_f32 v27, v135, v43, v27
	ds_write2_b32 v213, v9, v0 offset0:84 offset1:116
	v_cvt_pk_bf16_f32 v0, v39, v22
	v_fmac_f32_e32 v44, v134, v43
	v_fmac_f32_e32 v27, v134, v26
	ds_write2_b32 v213, v10, v0 offset0:152 offset1:184
	v_cvt_pk_bf16_f32 v0, v40, v23
	v_fma_f32 v45, -v135, v27, v60
	v_fma_f32 v28, v135, v44, v28
	ds_write2_b32 v213, v11, v0 offset0:220 offset1:252
	v_cvt_pk_bf16_f32 v0, v41, v24
	v_fmac_f32_e32 v45, v134, v44
	v_fmac_f32_e32 v28, v134, v27
	ds_write2_b32 v214, v12, v0 offset0:32 offset1:64
	v_cvt_pk_bf16_f32 v0, v42, v25
	v_fma_f32 v46, -v135, v28, v61
	v_fma_f32 v29, v135, v45, v29
	ds_write2_b32 v214, v13, v0 offset0:100 offset1:132
	v_cvt_pk_bf16_f32 v0, v43, v26
	v_fmac_f32_e32 v46, v134, v45
	v_fmac_f32_e32 v29, v134, v28
	ds_write2_b32 v214, v14, v0 offset0:168 offset1:200
	v_cvt_pk_bf16_f32 v0, v44, v27
	v_fma_f32 v48, -v135, v29, v62
	v_fma_f32 v30, v135, v46, v30
	ds_write2_b32 v217, v36, v0 offset0:108 offset1:140
	v_cvt_pk_bf16_f32 v0, v45, v28
	v_fmac_f32_e32 v48, v134, v46
	v_fmac_f32_e32 v30, v134, v29
	ds_write2_b32 v215, v37, v0 offset0:48 offset1:80
	v_cvt_pk_bf16_f32 v0, v46, v29
	v_fma_f32 v72, -v135, v30, v63
	v_fmac_f32_e32 v31, v135, v48
	ds_write2_b32 v215, v32, v0 offset0:116 offset1:148
	v_cvt_pk_bf16_f32 v0, v48, v30
	v_fmac_f32_e32 v72, v134, v48
	v_fmac_f32_e32 v31, v134, v30
	ds_write2_b32 v215, v33, v0 offset0:184 offset1:216
	v_cvt_pk_bf16_f32 v0, v72, v31
	ds_write2_b32 v216, v34, v0 offset0:124 offset1:156
	s_nop 7
	ds_read_b128 v[0:3], v171
	ds_read_b128 v[4:7], v171 offset:64
	ds_read_b128 v[16:19], v171 offset:128
	ds_read_b128 v[8:11], v171 offset:192
	s_waitcnt lgkmcnt(3)
	v_mfma_f32_16x16x32_bf16 v[0:3], v[112:115], v[0:3], 0
	s_waitcnt lgkmcnt(2)
	v_mfma_f32_16x16x32_bf16 v[0:3], v[108:111], v[4:7], v[0:3]
	s_waitcnt lgkmcnt(1)
	v_mfma_f32_16x16x32_bf16 v[0:3], v[104:107], v[16:19], v[0:3]
	s_waitcnt lgkmcnt(0)
	v_mfma_f32_16x16x32_bf16 v[156:159], v[100:103], v[8:11], v[0:3]
	s_nop 5
	s_nop 7
	ds_read_b128 v[0:3], v171 offset:4352
	ds_read_b128 v[4:7], v171 offset:4416
	ds_read_b128 v[16:19], v171 offset:4480
	ds_read_b128 v[8:11], v171 offset:4544
	s_waitcnt lgkmcnt(3)
	v_mfma_f32_16x16x32_bf16 v[0:3], v[112:115], v[0:3], 0
	s_waitcnt lgkmcnt(2)
	v_mfma_f32_16x16x32_bf16 v[0:3], v[108:111], v[4:7], v[0:3]
	s_waitcnt lgkmcnt(1)
	v_mfma_f32_16x16x32_bf16 v[0:3], v[104:107], v[16:19], v[0:3]
	s_waitcnt lgkmcnt(0)
	v_mfma_f32_16x16x32_bf16 v[160:163], v[100:103], v[8:11], v[0:3]
	ds_read_b128 v[16:19], v212 offset:30464
	s_waitcnt lgkmcnt(0)
	v_mfma_f32_32x32x16_bf16 v[48:63], v[16:19], v[124:127], 0
	s_nop 11
	v_fma_f32 v20, -v133, v47, v48
	v_mfma_f32_32x32x16_bf16 v[0:15], v[16:19], v[128:131], 0
	v_fmac_f32_e32 v20, v132, v35
	s_nop 10
	v_fma_f32 v0, v133, v35, v0
	v_fmac_f32_e32 v0, v132, v47
	v_fma_f32 v1, v133, v20, v1
	v_fma_f32 v21, -v133, v0, v49
	v_fmac_f32_e32 v1, v132, v0
	v_fmac_f32_e32 v21, v132, v20
	v_fma_f32 v2, v133, v21, v2
	v_fma_f32 v22, -v133, v1, v50
	v_fmac_f32_e32 v2, v132, v1
	v_fmac_f32_e32 v22, v132, v21
	v_fma_f32 v3, v133, v22, v3
	v_fma_f32 v23, -v133, v2, v51
	v_fmac_f32_e32 v3, v132, v2
	v_fmac_f32_e32 v23, v132, v22
	v_fma_f32 v4, v133, v23, v4
	v_fma_f32 v24, -v133, v3, v52
	v_fmac_f32_e32 v4, v132, v3
	v_fmac_f32_e32 v24, v132, v23
	v_fma_f32 v5, v133, v24, v5
	v_fma_f32 v25, -v133, v4, v53
	v_fmac_f32_e32 v5, v132, v4
	v_fmac_f32_e32 v25, v132, v24
	v_fma_f32 v6, v133, v25, v6
	v_fma_f32 v26, -v133, v5, v54
	v_fmac_f32_e32 v6, v132, v5
	v_fmac_f32_e32 v26, v132, v25
	v_fma_f32 v7, v133, v26, v7
	v_fma_f32 v27, -v133, v6, v55
	v_fmac_f32_e32 v7, v132, v6
	v_fmac_f32_e32 v27, v132, v26
	v_fma_f32 v8, v133, v27, v8
	v_fma_f32 v28, -v133, v7, v56
	v_fmac_f32_e32 v8, v132, v7
	v_fmac_f32_e32 v28, v132, v27
	v_fma_f32 v9, v133, v28, v9
	v_fma_f32 v29, -v133, v8, v57
	v_fmac_f32_e32 v9, v132, v8
	v_fmac_f32_e32 v29, v132, v28
	v_fma_f32 v10, v133, v29, v10
	v_fma_f32 v30, -v133, v9, v58
	v_fmac_f32_e32 v10, v132, v9
	v_fmac_f32_e32 v30, v132, v29
	v_fma_f32 v11, v133, v30, v11
	v_fma_f32 v48, -v133, v10, v59
	v_fmac_f32_e32 v11, v132, v10
	v_fmac_f32_e32 v48, v132, v30
	v_fma_f32 v12, v133, v48, v12
	v_fma_f32 v49, -v133, v11, v60
	v_fmac_f32_e32 v12, v132, v11
	v_fmac_f32_e32 v49, v132, v48
	v_fma_f32 v13, v133, v49, v13
	v_fma_f32 v50, -v133, v12, v61
	v_fmac_f32_e32 v13, v132, v12
	v_fmac_f32_e32 v50, v132, v49
	v_fma_f32 v14, v133, v50, v14
	v_fma_f32 v51, -v133, v13, v62
	v_fmac_f32_e32 v14, v132, v13
	v_fmac_f32_e32 v51, v132, v50
	v_fmac_f32_e32 v15, v133, v51
	v_fma_f32 v52, -v133, v14, v63
	v_fmac_f32_e32 v15, v132, v14
	v_fmac_f32_e32 v52, v132, v51
	v_cvt_pk_bf16_f32 v20, v20, v0
	v_cvt_pk_bf16_f32 v21, v21, v1
	v_cvt_pk_bf16_f32 v22, v22, v2
	v_cvt_pk_bf16_f32 v23, v23, v3
	v_cvt_pk_bf16_f32 v24, v24, v4
	v_cvt_pk_bf16_f32 v25, v25, v5
	v_cvt_pk_bf16_f32 v26, v26, v6
	v_cvt_pk_bf16_f32 v27, v27, v7
	v_cvt_pk_bf16_f32 v28, v28, v8
	v_mfma_f32_32x32x16_bf16 v[32:47], v[16:19], v[120:123], 0
	v_cvt_pk_bf16_f32 v29, v29, v9
	v_cvt_pk_bf16_f32 v30, v30, v10
	v_cvt_pk_bf16_f32 v48, v48, v11
	v_cvt_pk_bf16_f32 v49, v49, v12
	v_cvt_pk_bf16_f32 v50, v50, v13
	v_cvt_pk_bf16_f32 v51, v51, v14
	v_cvt_pk_bf16_f32 v52, v52, v15
	v_mfma_f32_32x32x16_bf16 v[0:15], v[16:19], v[116:119], 0
	s_nop 10
	v_fma_f32 v16, -v135, v31, v32
	v_fmac_f32_e32 v16, v134, v72
	v_fma_f32 v0, v135, v72, v0
	v_fmac_f32_e32 v0, v134, v31
	v_fma_f32 v1, v135, v16, v1
	v_fma_f32 v17, -v135, v0, v33
	v_fmac_f32_e32 v1, v134, v0
	v_fmac_f32_e32 v17, v134, v16
	v_fma_f32 v2, v135, v17, v2
	v_fma_f32 v18, -v135, v1, v34
	v_fmac_f32_e32 v2, v134, v1
	v_fmac_f32_e32 v18, v134, v17
	v_fma_f32 v3, v135, v18, v3
	v_fma_f32 v19, -v135, v2, v35
	v_fmac_f32_e32 v3, v134, v2
	v_fmac_f32_e32 v19, v134, v18
	v_fma_f32 v4, v135, v19, v4
	v_fma_f32 v31, -v135, v3, v36
	v_fmac_f32_e32 v4, v134, v3
	v_fmac_f32_e32 v31, v134, v19
	v_fma_f32 v5, v135, v31, v5
	v_fma_f32 v32, -v135, v4, v37
	v_fmac_f32_e32 v5, v134, v4
	v_fmac_f32_e32 v32, v134, v31
	v_fma_f32 v6, v135, v32, v6
	v_fma_f32 v33, -v135, v5, v38
	v_fmac_f32_e32 v6, v134, v5
	v_fmac_f32_e32 v33, v134, v32
	v_fma_f32 v7, v135, v33, v7
	v_fma_f32 v34, -v135, v6, v39
	v_fmac_f32_e32 v7, v134, v6
	v_fmac_f32_e32 v34, v134, v33
	v_fma_f32 v8, v135, v34, v8
	v_fma_f32 v35, -v135, v7, v40
	v_cvt_pk_bf16_f32 v0, v16, v0
	v_fmac_f32_e32 v8, v134, v7
	v_fmac_f32_e32 v35, v134, v34
	ds_write2_b32 v169, v20, v0 offset1:32
	v_cvt_pk_bf16_f32 v0, v17, v1
	v_fma_f32 v9, v135, v35, v9
	v_fma_f32 v36, -v135, v8, v41
	ds_write2_b32 v169, v21, v0 offset0:68 offset1:100
	v_cvt_pk_bf16_f32 v0, v18, v2
	v_fmac_f32_e32 v9, v134, v8
	v_fmac_f32_e32 v36, v134, v35
	ds_write2_b32 v169, v22, v0 offset0:136 offset1:168
	v_cvt_pk_bf16_f32 v0, v19, v3
	v_fma_f32 v10, v135, v36, v10
	v_fma_f32 v37, -v135, v9, v42
	ds_write2_b32 v169, v23, v0 offset0:204 offset1:236
	v_cvt_pk_bf16_f32 v0, v31, v4
	v_fmac_f32_e32 v10, v134, v9
	v_fmac_f32_e32 v37, v134, v36
	ds_write2_b32 v213, v24, v0 offset0:16 offset1:48
	v_cvt_pk_bf16_f32 v0, v32, v5
	v_fma_f32 v11, v135, v37, v11
	v_fma_f32 v38, -v135, v10, v43
	ds_write2_b32 v213, v25, v0 offset0:84 offset1:116
	v_cvt_pk_bf16_f32 v0, v33, v6
	v_fmac_f32_e32 v11, v134, v10
	v_fmac_f32_e32 v38, v134, v37
	ds_write2_b32 v213, v26, v0 offset0:152 offset1:184
	v_cvt_pk_bf16_f32 v0, v34, v7
	v_fma_f32 v12, v135, v38, v12
	v_fma_f32 v39, -v135, v11, v44
	ds_write2_b32 v213, v27, v0 offset0:220 offset1:252
	v_cvt_pk_bf16_f32 v0, v35, v8
	v_fmac_f32_e32 v12, v134, v11
	v_fmac_f32_e32 v39, v134, v38
	ds_write2_b32 v214, v28, v0 offset0:32 offset1:64
	v_cvt_pk_bf16_f32 v0, v36, v9
	v_fma_f32 v13, v135, v39, v13
	v_fma_f32 v40, -v135, v12, v45
	ds_write2_b32 v214, v29, v0 offset0:100 offset1:132
	v_cvt_pk_bf16_f32 v0, v37, v10
	v_fmac_f32_e32 v13, v134, v12
	v_fmac_f32_e32 v40, v134, v39
	ds_write2_b32 v214, v30, v0 offset0:168 offset1:200
	v_cvt_pk_bf16_f32 v0, v38, v11
	v_fma_f32 v14, v135, v40, v14
	v_fma_f32 v41, -v135, v13, v46
	ds_write2_b32 v217, v48, v0 offset0:108 offset1:140
	v_cvt_pk_bf16_f32 v0, v39, v12
	v_fmac_f32_e32 v14, v134, v13
	v_fmac_f32_e32 v41, v134, v40
	ds_write2_b32 v215, v49, v0 offset0:48 offset1:80
	v_cvt_pk_bf16_f32 v0, v40, v13
	v_fmac_f32_e32 v15, v135, v41
	v_fma_f32 v42, -v135, v14, v47
	ds_write2_b32 v215, v50, v0 offset0:116 offset1:148
	v_cvt_pk_bf16_f32 v0, v41, v14
	v_fmac_f32_e32 v15, v134, v14
	v_fmac_f32_e32 v42, v134, v41
	ds_write2_b32 v215, v51, v0 offset0:184 offset1:216
	v_cvt_pk_bf16_f32 v0, v42, v15
	ds_write2_b32 v216, v52, v0 offset0:124 offset1:156
	s_nop 7
	ds_read_b128 v[0:3], v171
	ds_read_b128 v[4:7], v171 offset:64
	ds_read_b128 v[116:119], v171 offset:128
	ds_read_b128 v[8:11], v171 offset:192
	s_waitcnt lgkmcnt(3)
	v_mfma_f32_16x16x32_bf16 v[0:3], v[112:115], v[0:3], 0
	s_waitcnt lgkmcnt(2)
	v_mfma_f32_16x16x32_bf16 v[0:3], v[108:111], v[4:7], v[0:3]
	s_waitcnt lgkmcnt(1)
	v_mfma_f32_16x16x32_bf16 v[0:3], v[104:107], v[116:119], v[0:3]
	s_waitcnt lgkmcnt(0)
	v_mfma_f32_16x16x32_bf16 v[50:53], v[100:103], v[8:11], v[0:3]
	s_nop 5
	s_nop 7
	ds_read_b128 v[0:3], v171 offset:4352
	ds_read_b128 v[4:7], v171 offset:4416
	ds_read_b128 v[116:119], v171 offset:4480
	ds_read_b128 v[8:11], v171 offset:4544
	s_waitcnt lgkmcnt(3)
	v_mfma_f32_16x16x32_bf16 v[0:3], v[112:115], v[0:3], 0
	s_waitcnt lgkmcnt(2)
	v_mfma_f32_16x16x32_bf16 v[0:3], v[108:111], v[4:7], v[0:3]
	s_waitcnt lgkmcnt(1)
	v_mfma_f32_16x16x32_bf16 v[0:3], v[104:107], v[116:119], v[0:3]
	s_waitcnt lgkmcnt(0)
	v_mfma_f32_16x16x32_bf16 v[54:57], v[100:103], v[8:11], v[0:3]
	v_readlane_b32 s3, v238, 3
	s_add_i32 s52, s3, s14
	s_ashr_i32 s53, s52, 31
	s_lshl_b64 s[54:55], s[52:53], 12
	s_lshl_b64 s[52:53], s[52:53], 9
	s_add_u32 s56, s65, s52
	v_lshl_add_u64 v[0:1], v[178:179], 0, s[54:55]
	s_addc_u32 s57, s61, s53
	flat_load_dwordx4 v[132:135], v[0:1]
	flat_load_dwordx4 v[124:127], v[0:1] offset:1024
	flat_load_dwordx4 v[136:139], v[0:1] offset:2048
	flat_load_dwordx4 v[120:123], v[0:1] offset:3072
	v_lshl_add_u64 v[0:1], s[56:57], 0, v[164:165]
	v_mov_b32_e32 v185, v165
	flat_load_dwordx2 v[188:189], v[0:1]
	v_lshl_add_u64 v[0:1], s[56:57], 0, v[184:185]
	v_mov_b32_e32 v187, v165
	flat_load_dword v219, v[0:1]
	v_lshl_add_u64 v[0:1], s[56:57], 0, v[186:187]
	s_add_u32 s52, s6, s52
	flat_load_dword v220, v[0:1]
	v_lshl_add_u64 v[0:1], v[180:181], 0, s[54:55]
	s_addc_u32 s53, s7, s53
	flat_load_dwordx4 v[116:119], v[0:1]
	flat_load_dwordx4 v[112:115], v[0:1] offset:64
	flat_load_dwordx4 v[108:111], v[0:1] offset:128
	flat_load_dwordx4 v[104:107], v[0:1] offset:192
	v_lshl_add_u64 v[0:1], s[52:53], 0, v[164:165]
	v_lshl_add_u64 v[2:3], s[52:53], 0, v[186:187]
	flat_load_dwordx2 v[4:5], v[0:1]
	s_mov_b32 s72, s61
	flat_load_dword v3, v[2:3]
	v_lshl_add_u64 v[0:1], s[52:53], 0, v[184:185]
	flat_load_dword v1, v[0:1]
	s_andn2_b64 vcc, exec, s[46:47]
	s_cbranch_vccnz .LBB0_211
	s_add_i32 s3, s9, -16
	s_lshr_b32 s3, s3, 3
	s_lshl_b32 s33, s3, 4
	s_add_i32 s38, s33, 32
	s_lshl_b32 s3, s3, 2
	v_readlane_b32 s33, v238, 4
	s_add_i32 s46, s33, s3
	s_ashr_i32 s47, s46, 31
	s_lshl_b64 s[46:47], s[46:47], 12
	s_add_u32 s3, s46, s5
	s_addc_u32 s33, s47, s15
	v_mov_b32_e32 v7, s33
	v_or_b32_e32 v6, s3, v168
	v_readlane_b32 s76, v239, 31
	v_lshlrev_b64 v[6:7], 2, v[6:7]
	v_readlane_b32 s80, v239, 35
	v_readlane_b32 s81, v239, 36
	v_readlane_b32 s82, v239, 37
	v_readlane_b32 s83, v239, 38
	v_lshl_add_u64 v[10:11], s[80:81], 0, v[6:7]
	v_readlane_b32 s78, v239, 33
	v_lshl_add_u64 v[12:13], s[82:83], 0, v[6:7]
	global_load_dword v8, v[10:11], off
	global_load_dword v7, v[10:11], off offset:128
	global_load_dword v6, v[12:13], off
	global_load_dword v9, v[12:13], off offset:128
	v_readlane_b32 s79, v239, 34
	v_readlane_b32 s79, v238, 11
	v_readlane_b32 s78, v238, 9
	v_readlane_b32 s77, v239, 32
	v_readlane_b32 s84, v239, 39
	v_readlane_b32 s85, v239, 40
	v_readlane_b32 s86, v239, 41
	v_readlane_b32 s87, v239, 42
	v_readlane_b32 s88, v239, 43
	v_readlane_b32 s89, v239, 44
	v_readlane_b32 s90, v239, 45
	v_readlane_b32 s91, v239, 46
	s_branch .LBB0_212

.LBB0_222:
	s_or_b64 exec, exec, s[38:39]
	v_fma_f32 v3, v220, v1, v32
	v_fmac_f32_e32 v3, v219, v2
	v_fma_f32 v4, -v220, v2, v48
	v_fmac_f32_e32 v4, v219, v1
	v_fma_f32 v6, -v220, v3, v47
	v_fma_f32 v5, v220, v4, v31
	v_fmac_f32_e32 v6, v219, v4
	v_fmac_f32_e32 v5, v219, v3
	v_fma_f32 v7, v220, v6, v30
	v_fmac_f32_e32 v7, v219, v5
	v_fma_f32 v8, -v220, v5, v46
	v_fmac_f32_e32 v8, v219, v6
	v_fma_f32 v10, -v220, v7, v45
	v_fma_f32 v9, v220, v8, v29
	v_fmac_f32_e32 v10, v219, v8
	v_fmac_f32_e32 v9, v219, v7
	v_fma_f32 v11, v220, v10, v28
	v_fmac_f32_e32 v11, v219, v9
	v_fma_f32 v12, -v220, v9, v44
	v_fmac_f32_e32 v12, v219, v10
	v_fma_f32 v14, -v220, v11, v43
	v_fma_f32 v13, v220, v12, v27
	v_fmac_f32_e32 v14, v219, v12
	v_fmac_f32_e32 v13, v219, v11
	v_fma_f32 v15, v220, v14, v26
	v_fmac_f32_e32 v15, v219, v13
	v_fma_f32 v17, -v220, v13, v42
	v_fmac_f32_e32 v17, v219, v14
	v_fma_f32 v26, -v220, v15, v41
	v_fma_f32 v25, v220, v17, v25
	v_fmac_f32_e32 v26, v219, v17
	v_fmac_f32_e32 v25, v219, v15
	v_fma_f32 v24, v220, v26, v24
	v_fmac_f32_e32 v24, v219, v25
	v_fma_f32 v27, -v220, v25, v40
	v_fmac_f32_e32 v27, v219, v26
	v_fma_f32 v28, -v220, v24, v39
	v_fma_f32 v23, v220, v27, v23
	v_fmac_f32_e32 v28, v219, v27
	v_fmac_f32_e32 v23, v219, v24
	v_fma_f32 v22, v220, v28, v22
	v_fmac_f32_e32 v22, v219, v23
	v_fma_f32 v29, -v220, v23, v38
	v_fmac_f32_e32 v29, v219, v28
	v_fma_f32 v30, -v220, v22, v37
	v_fma_f32 v21, v220, v29, v21
	v_fmac_f32_e32 v30, v219, v29
	v_fmac_f32_e32 v21, v219, v22
	v_fma_f32 v20, v220, v30, v20
	v_fmac_f32_e32 v20, v219, v21
	v_fma_f32 v31, -v220, v21, v36
	v_fmac_f32_e32 v31, v219, v30
	v_fma_f32 v32, -v220, v20, v35
	v_fma_f32 v19, v220, v31, v19
	v_fmac_f32_e32 v32, v219, v31
	v_fmac_f32_e32 v19, v219, v20
	v_fmac_f32_e32 v18, v220, v32
	v_fmac_f32_e32 v18, v219, v19
	v_fma_f32 v60, -v220, v19, v34
	v_cvt_pk_bf16_f32 v19, v32, v19
	v_fmac_f32_e32 v60, v219, v32
	v_cvt_pk_bf16_f32 v33, v60, v18
	ds_write2_b32 v169, v33, v19 offset0:32 offset1:100
	v_cvt_pk_bf16_f32 v19, v31, v20
	v_cvt_pk_bf16_f32 v20, v30, v21
	ds_write2_b32 v169, v19, v20 offset0:168 offset1:236
	v_cvt_pk_bf16_f32 v19, v29, v22
	v_cvt_pk_bf16_f32 v20, v28, v23
	ds_write2_b32 v213, v19, v20 offset0:48 offset1:116
	v_cvt_pk_bf16_f32 v19, v27, v24
	v_cvt_pk_bf16_f32 v20, v26, v25
	ds_write2_b32 v213, v19, v20 offset0:184 offset1:252
	v_cvt_pk_bf16_f32 v15, v17, v15
	v_cvt_pk_bf16_f32 v13, v14, v13
	ds_write2_b32 v214, v15, v13 offset0:64 offset1:132
	v_cvt_pk_bf16_f32 v11, v12, v11
	v_cvt_pk_bf16_f32 v9, v10, v9
	ds_write2_b32 v217, v11, v9 offset0:72 offset1:140
	v_cvt_pk_bf16_f32 v7, v8, v7
	v_cvt_pk_bf16_f32 v5, v6, v5
	ds_write2_b32 v215, v7, v5 offset0:80 offset1:148
	v_cvt_pk_bf16_f32 v3, v4, v3
	v_cvt_pk_bf16_f32 v1, v1, v2
	ds_write2_b32 v216, v3, v1 offset0:88 offset1:156
	ds_read_b128 v[2:5], v171
	ds_read_b128 v[6:9], v171 offset:64
	s_waitcnt lgkmcnt(1)
	v_mfma_f32_16x16x32_bf16 v[2:5], v[116:119], v[2:5], v[50:53]
	s_waitcnt lgkmcnt(0)
	v_mfma_f32_16x16x32_bf16 v[2:5], v[112:115], v[6:9], v[2:5]
	ds_read_b128 v[6:9], v171 offset:128
	ds_read_b128 v[10:13], v171 offset:192
	s_waitcnt lgkmcnt(1)
	v_mfma_f32_16x16x32_bf16 v[2:5], v[108:111], v[6:9], v[2:5]
	s_waitcnt lgkmcnt(0)
	v_mfma_f32_16x16x32_bf16 v[72:75], v[104:107], v[10:13], v[2:5]
	s_nop 5
	ds_read_b128 v[2:5], v171 offset:4352
	ds_read_b128 v[6:9], v171 offset:4416
	s_waitcnt lgkmcnt(1)
	v_mfma_f32_16x16x32_bf16 v[2:5], v[116:119], v[2:5], v[54:57]
	s_waitcnt lgkmcnt(0)
	v_mfma_f32_16x16x32_bf16 v[2:5], v[112:115], v[6:9], v[2:5]
	ds_read_b128 v[6:9], v171 offset:4480
	ds_read_b128 v[10:13], v171 offset:4544
	s_waitcnt lgkmcnt(1)
	v_mfma_f32_16x16x32_bf16 v[2:5], v[108:111], v[6:9], v[2:5]
	s_waitcnt lgkmcnt(0)
	v_mfma_f32_16x16x32_bf16 v[52:55], v[104:107], v[10:13], v[2:5]
	ds_read_b128 v[56:59], v212 offset:26112
	s_waitcnt lgkmcnt(0)
	v_mfma_f32_32x32x16_bf16 v[36:51], v[56:59], v[132:135], 0
	s_nop 11
	v_fma_f32 v17, -v189, v16, v51
	v_mfma_f32_32x32x16_bf16 v[20:35], v[56:59], v[136:139], 0
	v_fmac_f32_e32 v17, v188, v0
	s_nop 10
	v_fma_f32 v19, v189, v0, v35
	v_fmac_f32_e32 v19, v188, v16
	v_fma_f32 v16, -v189, v19, v50
	v_fma_f32 v34, v189, v17, v34
	v_fmac_f32_e32 v16, v188, v17
	v_fmac_f32_e32 v34, v188, v19
	v_fma_f32 v35, -v189, v34, v49
	v_fma_f32 v33, v189, v16, v33
	v_fmac_f32_e32 v35, v188, v16
	v_fmac_f32_e32 v33, v188, v34
	v_fma_f32 v48, -v189, v33, v48
	v_fma_f32 v32, v189, v35, v32
	v_fmac_f32_e32 v48, v188, v35
	v_fmac_f32_e32 v32, v188, v33
	v_fma_f32 v47, -v189, v32, v47
	v_fma_f32 v31, v189, v48, v31
	v_fmac_f32_e32 v47, v188, v48
	v_fmac_f32_e32 v31, v188, v32
	v_fma_f32 v46, -v189, v31, v46
	v_fma_f32 v30, v189, v47, v30
	v_fmac_f32_e32 v46, v188, v47
	v_fmac_f32_e32 v30, v188, v31
	v_fma_f32 v45, -v189, v30, v45
	v_fma_f32 v29, v189, v46, v29
	v_fmac_f32_e32 v45, v188, v46
	v_fmac_f32_e32 v29, v188, v30
	v_fma_f32 v0, -v189, v29, v44
	v_fma_f32 v1, v189, v45, v28
	v_fmac_f32_e32 v0, v188, v45
	v_fmac_f32_e32 v1, v188, v29
	v_fma_f32 v2, -v189, v1, v43
	v_fma_f32 v3, v189, v0, v27
	v_fmac_f32_e32 v2, v188, v0
	v_fmac_f32_e32 v3, v188, v1
	v_fma_f32 v4, -v189, v3, v42
	v_fma_f32 v5, v189, v2, v26
	v_fmac_f32_e32 v4, v188, v2
	v_fmac_f32_e32 v5, v188, v3
	v_fma_f32 v6, -v189, v5, v41
	v_fma_f32 v7, v189, v4, v25
	v_fmac_f32_e32 v6, v188, v4
	v_fmac_f32_e32 v7, v188, v5
	v_fma_f32 v8, -v189, v7, v40
	v_fma_f32 v9, v189, v6, v24
	v_fmac_f32_e32 v8, v188, v6
	v_fmac_f32_e32 v9, v188, v7
	v_fma_f32 v10, -v189, v9, v39
	v_fma_f32 v11, v189, v8, v23
	v_fmac_f32_e32 v10, v188, v8
	v_fmac_f32_e32 v11, v188, v9
	v_fma_f32 v12, -v189, v11, v38
	v_fma_f32 v13, v189, v10, v22
	v_fmac_f32_e32 v12, v188, v10
	v_fmac_f32_e32 v13, v188, v11
	v_fma_f32 v14, -v189, v13, v37
	v_fma_f32 v15, v189, v12, v21
	v_fmac_f32_e32 v14, v188, v12
	v_fmac_f32_e32 v15, v188, v13
	v_fma_f32 v21, -v189, v15, v36
	v_fmac_f32_e32 v20, v189, v14
	v_fmac_f32_e32 v21, v188, v14
	v_fmac_f32_e32 v20, v188, v15
	v_cvt_pk_bf16_f32 v39, v14, v15
	v_cvt_pk_bf16_f32 v40, v12, v13
	v_cvt_pk_bf16_f32 v41, v10, v11
	v_cvt_pk_bf16_f32 v42, v8, v9
	v_cvt_pk_bf16_f32 v43, v6, v7
	v_cvt_pk_bf16_f32 v44, v4, v5
	v_cvt_pk_bf16_f32 v49, v2, v3
	v_cvt_pk_bf16_f32 v50, v0, v1
	v_mfma_f32_32x32x16_bf16 v[0:15], v[56:59], v[124:127], 0
	v_cvt_pk_bf16_f32 v45, v45, v29
	v_cvt_pk_bf16_f32 v46, v46, v30
	v_cvt_pk_bf16_f32 v47, v47, v31
	v_cvt_pk_bf16_f32 v48, v48, v32
	v_cvt_pk_bf16_f32 v51, v35, v33
	v_cvt_pk_bf16_f32 v16, v16, v34
	v_cvt_pk_bf16_f32 v17, v17, v19
	v_mfma_f32_32x32x16_bf16 v[22:37], v[56:59], v[120:123], 0
	s_nop 10
	v_fma_f32 v15, -v220, v18, v15
	v_fmac_f32_e32 v15, v219, v60
	v_cvt_pk_bf16_f32 v38, v21, v20
	v_fma_f32 v19, v220, v60, v37
	v_fmac_f32_e32 v19, v219, v18
	v_fma_f32 v14, -v220, v19, v14
	v_fma_f32 v18, v220, v15, v36
	v_fmac_f32_e32 v14, v219, v15
	v_fmac_f32_e32 v18, v219, v19
	v_fma_f32 v13, -v220, v18, v13
	v_fma_f32 v35, v220, v14, v35
	v_fmac_f32_e32 v13, v219, v14
	v_fmac_f32_e32 v35, v219, v18
	v_fma_f32 v12, -v220, v35, v12
	v_fma_f32 v34, v220, v13, v34
	v_fmac_f32_e32 v12, v219, v13
	v_fmac_f32_e32 v34, v219, v35
	v_fma_f32 v11, -v220, v34, v11
	v_fma_f32 v33, v220, v12, v33
	v_fmac_f32_e32 v11, v219, v12
	v_fmac_f32_e32 v33, v219, v34
	v_fma_f32 v10, -v220, v33, v10
	v_fma_f32 v32, v220, v11, v32
	v_fmac_f32_e32 v10, v219, v11
	v_fmac_f32_e32 v32, v219, v33
	v_fma_f32 v9, -v220, v32, v9
	v_fma_f32 v31, v220, v10, v31
	v_fmac_f32_e32 v9, v219, v10
	v_fmac_f32_e32 v31, v219, v32
	v_fma_f32 v8, -v220, v31, v8
	v_fma_f32 v30, v220, v9, v30
	v_fmac_f32_e32 v8, v219, v9
	v_fmac_f32_e32 v30, v219, v31
	v_fma_f32 v7, -v220, v30, v7
	v_fma_f32 v29, v220, v8, v29
	v_fmac_f32_e32 v7, v219, v8
	v_fmac_f32_e32 v29, v219, v30
	v_fma_f32 v6, -v220, v29, v6
	v_fma_f32 v28, v220, v7, v28
	v_fmac_f32_e32 v6, v219, v7
	v_fmac_f32_e32 v28, v219, v29
	v_fma_f32 v5, -v220, v28, v5
	v_fma_f32 v27, v220, v6, v27
	v_fmac_f32_e32 v5, v219, v6
	v_fmac_f32_e32 v27, v219, v28
	v_fma_f32 v4, -v220, v27, v4
	v_fma_f32 v26, v220, v5, v26
	v_fmac_f32_e32 v4, v219, v5
	v_fmac_f32_e32 v26, v219, v27
	v_fma_f32 v3, -v220, v26, v3
	v_fma_f32 v25, v220, v4, v25
	v_fmac_f32_e32 v3, v219, v4
	v_fmac_f32_e32 v25, v219, v26
	v_fma_f32 v2, -v220, v25, v2
	v_fma_f32 v24, v220, v3, v24
	v_fmac_f32_e32 v2, v219, v3
	v_fmac_f32_e32 v24, v219, v25
	v_fma_f32 v1, -v220, v24, v1
	v_fma_f32 v23, v220, v2, v23
	v_fmac_f32_e32 v1, v219, v2
	v_fmac_f32_e32 v23, v219, v24
	v_fma_f32 v56, -v220, v23, v0
	v_fmac_f32_e32 v22, v220, v1
	v_fmac_f32_e32 v56, v219, v1
	v_fmac_f32_e32 v22, v219, v23
	v_cvt_pk_bf16_f32 v0, v56, v22
	ds_write2_b32 v169, v38, v0 offset1:32
	v_cvt_pk_bf16_f32 v0, v1, v23
	ds_write2_b32 v169, v39, v0 offset0:68 offset1:100
	v_cvt_pk_bf16_f32 v0, v2, v24
	ds_write2_b32 v169, v40, v0 offset0:136 offset1:168
	v_cvt_pk_bf16_f32 v0, v3, v25
	ds_write2_b32 v169, v41, v0 offset0:204 offset1:236
	v_cvt_pk_bf16_f32 v0, v4, v26
	ds_write2_b32 v213, v42, v0 offset0:16 offset1:48
	v_cvt_pk_bf16_f32 v0, v5, v27
	ds_write2_b32 v213, v43, v0 offset0:84 offset1:116
	v_cvt_pk_bf16_f32 v0, v6, v28
	ds_write2_b32 v213, v44, v0 offset0:152 offset1:184
	v_cvt_pk_bf16_f32 v0, v7, v29
	ds_write2_b32 v213, v49, v0 offset0:220 offset1:252
	v_cvt_pk_bf16_f32 v0, v8, v30
	ds_write2_b32 v214, v50, v0 offset0:32 offset1:64
	v_cvt_pk_bf16_f32 v0, v9, v31
	ds_write2_b32 v214, v45, v0 offset0:100 offset1:132
	v_cvt_pk_bf16_f32 v0, v10, v32
	ds_write2_b32 v214, v46, v0 offset0:168 offset1:200
	v_cvt_pk_bf16_f32 v0, v11, v33
	ds_write2_b32 v217, v47, v0 offset0:108 offset1:140
	v_cvt_pk_bf16_f32 v0, v12, v34
	ds_write2_b32 v215, v48, v0 offset0:48 offset1:80
	v_cvt_pk_bf16_f32 v0, v13, v35
	ds_write2_b32 v215, v51, v0 offset0:116 offset1:148
	v_cvt_pk_bf16_f32 v0, v14, v18
	ds_write2_b32 v215, v16, v0 offset0:184 offset1:216
	v_cvt_pk_bf16_f32 v0, v15, v19
	ds_write2_b32 v216, v17, v0 offset0:124 offset1:156
	s_nop 7
	ds_read_b128 v[0:3], v171
	ds_read_b128 v[4:7], v171 offset:64
	ds_read_b128 v[40:43], v171 offset:128
	ds_read_b128 v[8:11], v171 offset:192
	s_waitcnt lgkmcnt(3)
	v_mfma_f32_16x16x32_bf16 v[0:3], v[116:119], v[0:3], v[156:159]
	s_waitcnt lgkmcnt(2)
	v_mfma_f32_16x16x32_bf16 v[0:3], v[112:115], v[4:7], v[0:3]
	s_waitcnt lgkmcnt(1)
	v_mfma_f32_16x16x32_bf16 v[0:3], v[108:111], v[40:43], v[0:3]
	s_waitcnt lgkmcnt(0)
	v_mfma_f32_16x16x32_bf16 v[100:103], v[104:107], v[8:11], v[0:3]
	s_nop 5
	s_nop 7
	ds_read_b128 v[0:3], v171 offset:4352
	ds_read_b128 v[4:7], v171 offset:4416
	ds_read_b128 v[40:43], v171 offset:4480
	ds_read_b128 v[8:11], v171 offset:4544
	s_waitcnt lgkmcnt(3)
	v_mfma_f32_16x16x32_bf16 v[0:3], v[116:119], v[0:3], v[160:163]
	s_waitcnt lgkmcnt(2)
	v_mfma_f32_16x16x32_bf16 v[0:3], v[112:115], v[4:7], v[0:3]
	s_waitcnt lgkmcnt(1)
	v_mfma_f32_16x16x32_bf16 v[0:3], v[108:111], v[40:43], v[0:3]
	s_waitcnt lgkmcnt(0)
	v_mfma_f32_16x16x32_bf16 v[46:49], v[104:107], v[8:11], v[0:3]
	ds_read_b128 v[40:43], v212 offset:21760
	s_waitcnt lgkmcnt(0)
	v_mfma_f32_32x32x16_bf16 v[24:39], v[40:43], v[132:135], 0
	s_nop 11
	v_fma_f32 v18, -v189, v20, v39
	v_mfma_f32_32x32x16_bf16 v[0:15], v[40:43], v[136:139], 0
	v_fmac_f32_e32 v18, v188, v21
	s_nop 10
	v_fma_f32 v19, v189, v21, v15
	v_fmac_f32_e32 v19, v188, v20
	v_fma_f32 v20, -v189, v19, v38
	v_fma_f32 v21, v189, v18, v14
	v_fmac_f32_e32 v20, v188, v18
	v_fmac_f32_e32 v21, v188, v19
	v_fma_f32 v23, -v189, v21, v37
	v_fma_f32 v37, v189, v20, v13
	v_fmac_f32_e32 v23, v188, v20
	v_fmac_f32_e32 v37, v188, v21
	v_fma_f32 v36, -v189, v37, v36
	v_fma_f32 v38, v189, v23, v12
	v_fmac_f32_e32 v36, v188, v23
	v_fmac_f32_e32 v38, v188, v37
	v_fma_f32 v35, -v189, v38, v35
	v_fma_f32 v39, v189, v36, v11
	v_fmac_f32_e32 v35, v188, v36
	v_fmac_f32_e32 v39, v188, v38
	v_fma_f32 v34, -v189, v39, v34
	v_fma_f32 v44, v189, v35, v10
	v_fmac_f32_e32 v34, v188, v35
	v_fmac_f32_e32 v44, v188, v39
	v_fma_f32 v33, -v189, v44, v33
	v_fma_f32 v45, v189, v34, v9
	v_fmac_f32_e32 v33, v188, v34
	v_fmac_f32_e32 v45, v188, v44
	v_fma_f32 v9, -v189, v45, v32
	v_fma_f32 v8, v189, v33, v8
	v_fmac_f32_e32 v9, v188, v33
	v_fmac_f32_e32 v8, v188, v45
	v_fma_f32 v10, -v189, v8, v31
	v_fma_f32 v7, v189, v9, v7
	v_fmac_f32_e32 v10, v188, v9
	v_fmac_f32_e32 v7, v188, v8
	v_fma_f32 v11, -v189, v7, v30
	v_fma_f32 v6, v189, v10, v6
	v_fmac_f32_e32 v11, v188, v10
	v_fmac_f32_e32 v6, v188, v7
	v_fma_f32 v12, -v189, v6, v29
	v_fma_f32 v5, v189, v11, v5
	v_fmac_f32_e32 v12, v188, v11
	v_fmac_f32_e32 v5, v188, v6
	v_fma_f32 v13, -v189, v5, v28
	v_fma_f32 v4, v189, v12, v4
	v_fmac_f32_e32 v13, v188, v12
	v_fmac_f32_e32 v4, v188, v5
	v_fma_f32 v14, -v189, v4, v27
	v_fma_f32 v3, v189, v13, v3
	v_fmac_f32_e32 v14, v188, v13
	v_fmac_f32_e32 v3, v188, v4
	v_fma_f32 v15, -v189, v3, v26
	v_fma_f32 v2, v189, v14, v2
	v_fmac_f32_e32 v15, v188, v14
	v_fmac_f32_e32 v2, v188, v3
	v_fma_f32 v16, -v189, v2, v25
	v_fma_f32 v1, v189, v15, v1
	v_fmac_f32_e32 v16, v188, v15
	v_fmac_f32_e32 v1, v188, v2
	v_fma_f32 v50, -v189, v1, v24
	v_fmac_f32_e32 v0, v189, v16
	v_fmac_f32_e32 v50, v188, v16
	v_fmac_f32_e32 v0, v188, v1
	v_cvt_pk_bf16_f32 v1, v16, v1
	v_cvt_pk_bf16_f32 v57, v15, v2
	v_cvt_pk_bf16_f32 v58, v14, v3
	v_cvt_pk_bf16_f32 v59, v13, v4
	v_cvt_pk_bf16_f32 v60, v12, v5
	v_cvt_pk_bf16_f32 v61, v11, v6
	v_cvt_pk_bf16_f32 v62, v10, v7
	v_cvt_pk_bf16_f32 v63, v9, v8
	v_mfma_f32_32x32x16_bf16 v[2:17], v[40:43], v[124:127], 0
	v_cvt_pk_bf16_f32 v45, v33, v45
	v_cvt_pk_bf16_f32 v44, v34, v44
	v_cvt_pk_bf16_f32 v128, v35, v39
	v_cvt_pk_bf16_f32 v129, v36, v38
	v_cvt_pk_bf16_f32 v23, v23, v37
	v_cvt_pk_bf16_f32 v18, v18, v19
	v_cvt_pk_bf16_f32 v20, v20, v21
	v_mfma_f32_32x32x16_bf16 v[24:39], v[40:43], v[120:123], 0
	s_nop 10
	v_fma_f32 v17, -v220, v22, v17
	v_fmac_f32_e32 v17, v219, v56
	v_cvt_pk_bf16_f32 v51, v50, v0
	v_fma_f32 v19, v220, v56, v39
	v_fmac_f32_e32 v19, v219, v22
	v_fma_f32 v16, -v220, v19, v16
	v_fma_f32 v21, v220, v17, v38
	v_fmac_f32_e32 v16, v219, v17
	v_fmac_f32_e32 v21, v219, v19
	v_fma_f32 v15, -v220, v21, v15
	v_fma_f32 v22, v220, v16, v37
	v_fmac_f32_e32 v15, v219, v16
	v_fmac_f32_e32 v22, v219, v21
	v_fma_f32 v14, -v220, v22, v14
	v_fma_f32 v36, v220, v15, v36
	v_fmac_f32_e32 v14, v219, v15
	v_fmac_f32_e32 v36, v219, v22
	v_fma_f32 v13, -v220, v36, v13
	v_fma_f32 v35, v220, v14, v35
	v_fmac_f32_e32 v13, v219, v14
	v_fmac_f32_e32 v35, v219, v36
	v_fma_f32 v12, -v220, v35, v12
	v_fma_f32 v34, v220, v13, v34
	v_fmac_f32_e32 v12, v219, v13
	v_fmac_f32_e32 v34, v219, v35
	v_fma_f32 v11, -v220, v34, v11
	v_fma_f32 v33, v220, v12, v33
	v_fmac_f32_e32 v11, v219, v12
	v_fmac_f32_e32 v33, v219, v34
	v_fma_f32 v10, -v220, v33, v10
	v_fma_f32 v32, v220, v11, v32
	v_fmac_f32_e32 v10, v219, v11
	v_fmac_f32_e32 v32, v219, v33
	v_fma_f32 v9, -v220, v32, v9
	v_fma_f32 v31, v220, v10, v31
	v_fmac_f32_e32 v9, v219, v10
	v_fmac_f32_e32 v31, v219, v32
	v_fma_f32 v8, -v220, v31, v8
	v_fma_f32 v30, v220, v9, v30
	v_fmac_f32_e32 v8, v219, v9
	v_fmac_f32_e32 v30, v219, v31
	v_fma_f32 v7, -v220, v30, v7
	v_fma_f32 v29, v220, v8, v29
	v_fmac_f32_e32 v7, v219, v8
	v_fmac_f32_e32 v29, v219, v30
	v_fma_f32 v6, -v220, v29, v6
	v_fma_f32 v28, v220, v7, v28
	v_fmac_f32_e32 v6, v219, v7
	v_fmac_f32_e32 v28, v219, v29
	v_fma_f32 v5, -v220, v28, v5
	v_fma_f32 v27, v220, v6, v27
	v_fmac_f32_e32 v5, v219, v6
	v_fmac_f32_e32 v27, v219, v28
	v_fma_f32 v4, -v220, v27, v4
	v_fma_f32 v26, v220, v5, v26
	v_fmac_f32_e32 v4, v219, v5
	v_fmac_f32_e32 v26, v219, v27
	v_fma_f32 v3, -v220, v26, v3
	v_fma_f32 v25, v220, v4, v25
	v_fmac_f32_e32 v3, v219, v4
	v_fmac_f32_e32 v25, v219, v26
	v_fma_f32 v42, -v220, v25, v2
	v_fmac_f32_e32 v24, v220, v3
	v_fmac_f32_e32 v42, v219, v3
	v_fmac_f32_e32 v24, v219, v25
	v_cvt_pk_bf16_f32 v2, v42, v24
	ds_write2_b32 v169, v51, v2 offset1:32
	v_cvt_pk_bf16_f32 v2, v3, v25
	ds_write2_b32 v169, v1, v2 offset0:68 offset1:100
	v_cvt_pk_bf16_f32 v1, v4, v26
	ds_write2_b32 v169, v57, v1 offset0:136 offset1:168
	v_cvt_pk_bf16_f32 v1, v5, v27
	ds_write2_b32 v169, v58, v1 offset0:204 offset1:236
	v_cvt_pk_bf16_f32 v1, v6, v28
	ds_write2_b32 v213, v59, v1 offset0:16 offset1:48
	v_cvt_pk_bf16_f32 v1, v7, v29
	ds_write2_b32 v213, v60, v1 offset0:84 offset1:116
	v_cvt_pk_bf16_f32 v1, v8, v30
	ds_write2_b32 v213, v61, v1 offset0:152 offset1:184
	v_cvt_pk_bf16_f32 v1, v9, v31
	ds_write2_b32 v213, v62, v1 offset0:220 offset1:252
	v_cvt_pk_bf16_f32 v1, v10, v32
	ds_write2_b32 v214, v63, v1 offset0:32 offset1:64
	v_cvt_pk_bf16_f32 v1, v11, v33
	ds_write2_b32 v214, v45, v1 offset0:100 offset1:132
	v_cvt_pk_bf16_f32 v1, v12, v34
	ds_write2_b32 v214, v44, v1 offset0:168 offset1:200
	v_cvt_pk_bf16_f32 v1, v13, v35
	ds_write2_b32 v217, v128, v1 offset0:108 offset1:140
	v_cvt_pk_bf16_f32 v1, v14, v36
	ds_write2_b32 v215, v129, v1 offset0:48 offset1:80
	v_cvt_pk_bf16_f32 v1, v15, v22
	ds_write2_b32 v215, v23, v1 offset0:116 offset1:148
	v_cvt_pk_bf16_f32 v1, v16, v21
	ds_write2_b32 v215, v20, v1 offset0:184 offset1:216
	v_cvt_pk_bf16_f32 v1, v17, v19
	ds_write2_b32 v216, v18, v1 offset0:124 offset1:156
	s_nop 7
	ds_read_b128 v[2:5], v171
	ds_read_b128 v[6:9], v171 offset:64
	ds_read_b128 v[20:23], v171 offset:128
	ds_read_b128 v[10:13], v171 offset:192
	s_waitcnt lgkmcnt(3)
	v_mfma_f32_16x16x32_bf16 v[2:5], v[116:119], v[2:5], v[148:151]
	s_waitcnt lgkmcnt(2)
	v_mfma_f32_16x16x32_bf16 v[2:5], v[112:115], v[6:9], v[2:5]
	s_waitcnt lgkmcnt(1)
	v_mfma_f32_16x16x32_bf16 v[2:5], v[108:111], v[20:23], v[2:5]
	s_waitcnt lgkmcnt(0)
	v_mfma_f32_16x16x32_bf16 v[128:131], v[104:107], v[10:13], v[2:5]
	s_nop 5
	s_nop 7
	ds_read_b128 v[2:5], v171 offset:4352
	ds_read_b128 v[6:9], v171 offset:4416
	ds_read_b128 v[20:23], v171 offset:4480
	ds_read_b128 v[10:13], v171 offset:4544
	s_waitcnt lgkmcnt(3)
	v_mfma_f32_16x16x32_bf16 v[2:5], v[116:119], v[2:5], v[152:155]
	s_waitcnt lgkmcnt(2)
	v_mfma_f32_16x16x32_bf16 v[2:5], v[112:115], v[6:9], v[2:5]
	s_waitcnt lgkmcnt(1)
	v_mfma_f32_16x16x32_bf16 v[2:5], v[108:111], v[20:23], v[2:5]
	s_waitcnt lgkmcnt(0)
	v_mfma_f32_16x16x32_bf16 v[56:59], v[104:107], v[10:13], v[2:5]
	ds_read_b128 v[20:23], v212 offset:17408
	s_waitcnt lgkmcnt(0)
	v_mfma_f32_32x32x16_bf16 v[26:41], v[20:23], v[132:135], 0
	s_nop 11
	v_fma_f32 v1, -v189, v0, v41
	v_mfma_f32_32x32x16_bf16 v[2:17], v[20:23], v[136:139], 0
	v_fmac_f32_e32 v1, v188, v50
	s_nop 10
	v_fma_f32 v25, v189, v50, v17
	v_fmac_f32_e32 v25, v188, v0
	v_fma_f32 v0, -v189, v25, v40
	v_fma_f32 v40, v189, v1, v16
	v_fmac_f32_e32 v0, v188, v1
	v_fmac_f32_e32 v40, v188, v25
	v_fma_f32 v39, -v189, v40, v39
	v_fma_f32 v41, v189, v0, v15
	v_fmac_f32_e32 v39, v188, v0
	v_fmac_f32_e32 v41, v188, v40
	v_fma_f32 v38, -v189, v41, v38
	v_fma_f32 v43, v189, v39, v14
	v_fmac_f32_e32 v38, v188, v39
	v_fmac_f32_e32 v43, v188, v41
	v_fma_f32 v37, -v189, v43, v37
	v_fma_f32 v44, v189, v38, v13
	v_fmac_f32_e32 v37, v188, v38
	v_fmac_f32_e32 v44, v188, v43
	v_fma_f32 v36, -v189, v44, v36
	v_fma_f32 v45, v189, v37, v12
	v_fmac_f32_e32 v36, v188, v37
	v_fmac_f32_e32 v45, v188, v44
	v_fma_f32 v35, -v189, v45, v35
	v_fma_f32 v50, v189, v36, v11
	v_fmac_f32_e32 v35, v188, v36
	v_fmac_f32_e32 v50, v188, v45
	v_fma_f32 v11, -v189, v50, v34
	v_fma_f32 v10, v189, v35, v10
	v_fmac_f32_e32 v11, v188, v35
	v_fmac_f32_e32 v10, v188, v50
	v_fma_f32 v12, -v189, v10, v33
	v_fma_f32 v9, v189, v11, v9
	v_fmac_f32_e32 v12, v188, v11
	v_fmac_f32_e32 v9, v188, v10
	v_fma_f32 v13, -v189, v9, v32
	v_fma_f32 v8, v189, v12, v8
	v_fmac_f32_e32 v13, v188, v12
	v_fmac_f32_e32 v8, v188, v9
	v_fma_f32 v14, -v189, v8, v31
	v_fma_f32 v7, v189, v13, v7
	v_fmac_f32_e32 v14, v188, v13
	v_fmac_f32_e32 v7, v188, v8
	v_fma_f32 v15, -v189, v7, v30
	v_fma_f32 v6, v189, v14, v6
	v_fmac_f32_e32 v15, v188, v14
	v_fmac_f32_e32 v6, v188, v7
	v_fma_f32 v16, -v189, v6, v29
	v_fma_f32 v5, v189, v15, v5
	v_fmac_f32_e32 v16, v188, v15
	v_fmac_f32_e32 v5, v188, v6
	v_fma_f32 v17, -v189, v5, v28
	v_fma_f32 v4, v189, v16, v4
	v_fmac_f32_e32 v17, v188, v16
	v_fmac_f32_e32 v4, v188, v5
	v_fma_f32 v18, -v189, v4, v27
	v_fma_f32 v3, v189, v17, v3
	v_fmac_f32_e32 v18, v188, v17
	v_fmac_f32_e32 v3, v188, v4
	v_fma_f32 v51, -v189, v3, v26
	v_fmac_f32_e32 v2, v189, v18
	v_fmac_f32_e32 v51, v188, v18
	v_fmac_f32_e32 v2, v188, v3
	v_cvt_pk_bf16_f32 v3, v18, v3
	v_cvt_pk_bf16_f32 v61, v17, v4
	v_cvt_pk_bf16_f32 v62, v16, v5
	v_cvt_pk_bf16_f32 v63, v15, v6
	v_cvt_pk_bf16_f32 v148, v14, v7
	v_cvt_pk_bf16_f32 v149, v13, v8
	v_cvt_pk_bf16_f32 v150, v12, v9
	v_cvt_pk_bf16_f32 v151, v11, v10
	v_mfma_f32_32x32x16_bf16 v[4:19], v[20:23], v[124:127], 0
	v_cvt_pk_bf16_f32 v50, v35, v50
	v_cvt_pk_bf16_f32 v45, v36, v45
	v_cvt_pk_bf16_f32 v44, v37, v44
	v_cvt_pk_bf16_f32 v43, v38, v43
	v_cvt_pk_bf16_f32 v152, v39, v41
	v_cvt_pk_bf16_f32 v0, v0, v40
	v_cvt_pk_bf16_f32 v1, v1, v25
	v_mfma_f32_32x32x16_bf16 v[26:41], v[20:23], v[120:123], 0
	s_nop 10
	v_fma_f32 v19, -v220, v24, v19
	v_fmac_f32_e32 v19, v219, v42
	v_cvt_pk_bf16_f32 v60, v51, v2
	v_fma_f32 v20, v220, v42, v41
	v_fmac_f32_e32 v20, v219, v24
	v_fma_f32 v18, -v220, v20, v18
	v_fma_f32 v21, v220, v19, v40
	v_fmac_f32_e32 v18, v219, v19
	v_fmac_f32_e32 v21, v219, v20
	v_fma_f32 v17, -v220, v21, v17
	v_fma_f32 v22, v220, v18, v39
	v_fmac_f32_e32 v17, v219, v18
	v_fmac_f32_e32 v22, v219, v21
	v_fma_f32 v16, -v220, v22, v16
	v_fma_f32 v23, v220, v17, v38
	v_fmac_f32_e32 v16, v219, v17
	v_fmac_f32_e32 v23, v219, v22
	v_fma_f32 v15, -v220, v23, v15
	v_fma_f32 v24, v220, v16, v37
	v_fmac_f32_e32 v15, v219, v16
	v_fmac_f32_e32 v24, v219, v23
	v_fma_f32 v14, -v220, v24, v14
	v_fma_f32 v25, v220, v15, v36
	v_fmac_f32_e32 v14, v219, v15
	v_fmac_f32_e32 v25, v219, v24
	v_fma_f32 v13, -v220, v25, v13
	v_fma_f32 v35, v220, v14, v35
	v_fmac_f32_e32 v13, v219, v14
	v_fmac_f32_e32 v35, v219, v25
	v_fma_f32 v12, -v220, v35, v12
	v_fma_f32 v34, v220, v13, v34
	v_fmac_f32_e32 v12, v219, v13
	v_fmac_f32_e32 v34, v219, v35
	v_fma_f32 v11, -v220, v34, v11
	v_fma_f32 v33, v220, v12, v33
	v_fmac_f32_e32 v11, v219, v12
	v_fmac_f32_e32 v33, v219, v34
	v_fma_f32 v10, -v220, v33, v10
	v_fma_f32 v32, v220, v11, v32
	v_fmac_f32_e32 v10, v219, v11
	v_fmac_f32_e32 v32, v219, v33
	v_fma_f32 v9, -v220, v32, v9
	v_fma_f32 v31, v220, v10, v31
	v_fmac_f32_e32 v9, v219, v10
	v_fmac_f32_e32 v31, v219, v32
	v_fma_f32 v8, -v220, v31, v8
	v_fma_f32 v30, v220, v9, v30
	v_fmac_f32_e32 v8, v219, v9
	v_fmac_f32_e32 v30, v219, v31
	v_fma_f32 v7, -v220, v30, v7
	v_fma_f32 v29, v220, v8, v29
	v_fmac_f32_e32 v7, v219, v8
	v_fmac_f32_e32 v29, v219, v30
	v_fma_f32 v6, -v220, v29, v6
	v_fma_f32 v28, v220, v7, v28
	v_fmac_f32_e32 v6, v219, v7
	v_fmac_f32_e32 v28, v219, v29
	v_fma_f32 v5, -v220, v28, v5
	v_fma_f32 v27, v220, v6, v27
	v_fmac_f32_e32 v5, v219, v6
	v_fmac_f32_e32 v27, v219, v28
	v_fma_f32 v153, -v220, v27, v4
	v_fmac_f32_e32 v26, v220, v5
	v_fmac_f32_e32 v153, v219, v5
	v_fmac_f32_e32 v26, v219, v27
	v_cvt_pk_bf16_f32 v4, v153, v26
	ds_write2_b32 v169, v60, v4 offset1:32
	v_cvt_pk_bf16_f32 v4, v5, v27
	ds_write2_b32 v169, v3, v4 offset0:68 offset1:100
	v_cvt_pk_bf16_f32 v3, v6, v28
	ds_write2_b32 v169, v61, v3 offset0:136 offset1:168
	v_cvt_pk_bf16_f32 v3, v7, v29
	ds_write2_b32 v169, v62, v3 offset0:204 offset1:236
	v_cvt_pk_bf16_f32 v3, v8, v30
	ds_write2_b32 v213, v63, v3 offset0:16 offset1:48
	v_cvt_pk_bf16_f32 v3, v9, v31
	ds_write2_b32 v213, v148, v3 offset0:84 offset1:116
	v_cvt_pk_bf16_f32 v3, v10, v32
	ds_write2_b32 v213, v149, v3 offset0:152 offset1:184
	v_cvt_pk_bf16_f32 v3, v11, v33
	ds_write2_b32 v213, v150, v3 offset0:220 offset1:252
	v_cvt_pk_bf16_f32 v3, v12, v34
	ds_write2_b32 v214, v151, v3 offset0:32 offset1:64
	v_cvt_pk_bf16_f32 v3, v13, v35
	ds_write2_b32 v214, v50, v3 offset0:100 offset1:132
	v_cvt_pk_bf16_f32 v3, v14, v25
	ds_write2_b32 v214, v45, v3 offset0:168 offset1:200
	v_cvt_pk_bf16_f32 v3, v15, v24
	ds_write2_b32 v217, v44, v3 offset0:108 offset1:140
	v_cvt_pk_bf16_f32 v3, v16, v23
	ds_write2_b32 v215, v43, v3 offset0:48 offset1:80
	v_cvt_pk_bf16_f32 v3, v17, v22
	ds_write2_b32 v215, v152, v3 offset0:116 offset1:148
	v_cvt_pk_bf16_f32 v3, v18, v21
	ds_write2_b32 v215, v0, v3 offset0:184 offset1:216
	v_cvt_pk_bf16_f32 v0, v19, v20
	ds_write2_b32 v216, v1, v0 offset0:124 offset1:156
	s_nop 7
	ds_read_b128 v[4:7], v171
	ds_read_b128 v[8:11], v171 offset:64
	ds_read_b128 v[22:25], v171 offset:128
	ds_read_b128 v[12:15], v171 offset:192
	s_waitcnt lgkmcnt(3)
	v_mfma_f32_16x16x32_bf16 v[4:7], v[116:119], v[4:7], v[140:143]
	s_waitcnt lgkmcnt(2)
	v_mfma_f32_16x16x32_bf16 v[4:7], v[112:115], v[8:11], v[4:7]
	s_waitcnt lgkmcnt(1)
	v_mfma_f32_16x16x32_bf16 v[4:7], v[108:111], v[22:25], v[4:7]
	s_waitcnt lgkmcnt(0)
	v_mfma_f32_16x16x32_bf16 v[140:143], v[104:107], v[12:15], v[4:7]
	s_nop 5
	s_nop 7
	ds_read_b128 v[4:7], v171 offset:4352
	ds_read_b128 v[8:11], v171 offset:4416
	ds_read_b128 v[22:25], v171 offset:4480
	ds_read_b128 v[12:15], v171 offset:4544
	s_waitcnt lgkmcnt(3)
	v_mfma_f32_16x16x32_bf16 v[4:7], v[116:119], v[4:7], v[144:147]
	s_waitcnt lgkmcnt(2)
	v_mfma_f32_16x16x32_bf16 v[4:7], v[112:115], v[8:11], v[4:7]
	s_waitcnt lgkmcnt(1)
	v_mfma_f32_16x16x32_bf16 v[4:7], v[108:111], v[22:25], v[4:7]
	s_waitcnt lgkmcnt(0)
	v_mfma_f32_16x16x32_bf16 v[60:63], v[104:107], v[12:15], v[4:7]
	ds_read_b128 v[22:25], v212 offset:13056
	s_waitcnt lgkmcnt(0)
	v_mfma_f32_32x32x16_bf16 v[28:43], v[22:25], v[132:135], 0
	s_nop 11
	v_fma_f32 v0, -v189, v2, v43
	v_mfma_f32_32x32x16_bf16 v[4:19], v[22:25], v[136:139], 0
	v_fmac_f32_e32 v0, v188, v51
	s_nop 10
	v_fma_f32 v1, v189, v51, v19
	v_fmac_f32_e32 v1, v188, v2
	v_fma_f32 v2, -v189, v1, v42
	v_fma_f32 v3, v189, v0, v18
	v_fmac_f32_e32 v2, v188, v0
	v_fmac_f32_e32 v3, v188, v1
	v_fma_f32 v27, -v189, v3, v41
	v_fma_f32 v41, v189, v2, v17
	v_fmac_f32_e32 v27, v188, v2
	v_fmac_f32_e32 v41, v188, v3
	v_fma_f32 v40, -v189, v41, v40
	v_fma_f32 v42, v189, v27, v16
	v_fmac_f32_e32 v40, v188, v27
	v_fmac_f32_e32 v42, v188, v41
	v_fma_f32 v39, -v189, v42, v39
	v_fma_f32 v43, v189, v40, v15
	v_fmac_f32_e32 v39, v188, v40
	v_fmac_f32_e32 v43, v188, v42
	v_fma_f32 v38, -v189, v43, v38
	v_fma_f32 v44, v189, v39, v14
	v_fmac_f32_e32 v38, v188, v39
	v_fmac_f32_e32 v44, v188, v43
	v_fma_f32 v37, -v189, v44, v37
	v_fma_f32 v45, v189, v38, v13
	v_fmac_f32_e32 v37, v188, v38
	v_fmac_f32_e32 v45, v188, v44
	v_fma_f32 v13, -v189, v45, v36
	v_fma_f32 v12, v189, v37, v12
	v_fmac_f32_e32 v13, v188, v37
	v_fmac_f32_e32 v12, v188, v45
	v_fma_f32 v14, -v189, v12, v35
	v_fma_f32 v11, v189, v13, v11
	v_fmac_f32_e32 v14, v188, v13
	v_fmac_f32_e32 v11, v188, v12
	v_fma_f32 v15, -v189, v11, v34
	v_fma_f32 v10, v189, v14, v10
	v_fmac_f32_e32 v15, v188, v14
	v_fmac_f32_e32 v10, v188, v11
	v_fma_f32 v16, -v189, v10, v33
	v_fma_f32 v9, v189, v15, v9
	v_fmac_f32_e32 v16, v188, v15
	v_fmac_f32_e32 v9, v188, v10
	v_fma_f32 v17, -v189, v9, v32
	v_fma_f32 v8, v189, v16, v8
	v_fmac_f32_e32 v17, v188, v16
	v_fmac_f32_e32 v8, v188, v9
	v_fma_f32 v18, -v189, v8, v31
	v_fma_f32 v7, v189, v17, v7
	v_fmac_f32_e32 v18, v188, v17
	v_fmac_f32_e32 v7, v188, v8
	v_fma_f32 v19, -v189, v7, v30
	v_fma_f32 v6, v189, v18, v6
	v_fmac_f32_e32 v19, v188, v18
	v_fmac_f32_e32 v6, v188, v7
	v_fma_f32 v20, -v189, v6, v29
	v_fma_f32 v5, v189, v19, v5
	v_fmac_f32_e32 v20, v188, v19
	v_fmac_f32_e32 v5, v188, v6
	v_fma_f32 v50, -v189, v5, v28
	v_fmac_f32_e32 v4, v189, v20
	v_fmac_f32_e32 v50, v188, v20
	v_fmac_f32_e32 v4, v188, v5
	v_cvt_pk_bf16_f32 v5, v20, v5
	v_cvt_pk_bf16_f32 v144, v19, v6
	v_cvt_pk_bf16_f32 v145, v18, v7
	v_cvt_pk_bf16_f32 v146, v17, v8
	v_cvt_pk_bf16_f32 v147, v16, v9
	v_cvt_pk_bf16_f32 v148, v15, v10
	v_cvt_pk_bf16_f32 v149, v14, v11
	v_cvt_pk_bf16_f32 v150, v13, v12
	v_mfma_f32_32x32x16_bf16 v[6:21], v[22:25], v[124:127], 0
	v_cvt_pk_bf16_f32 v45, v37, v45
	v_cvt_pk_bf16_f32 v44, v38, v44
	v_cvt_pk_bf16_f32 v151, v39, v43
	v_cvt_pk_bf16_f32 v152, v40, v42
	v_cvt_pk_bf16_f32 v27, v27, v41
	v_cvt_pk_bf16_f32 v2, v2, v3
	v_cvt_pk_bf16_f32 v0, v0, v1
	v_mfma_f32_32x32x16_bf16 v[28:43], v[22:25], v[120:123], 0
	s_nop 10
	v_fma_f32 v1, -v220, v26, v21
	v_fmac_f32_e32 v1, v219, v153
	v_cvt_pk_bf16_f32 v51, v50, v4
	v_fma_f32 v3, v220, v153, v43
	v_fmac_f32_e32 v3, v219, v26
	v_fma_f32 v20, -v220, v3, v20
	v_fma_f32 v21, v220, v1, v42
	v_fmac_f32_e32 v20, v219, v1
	v_fmac_f32_e32 v21, v219, v3
	v_fma_f32 v19, -v220, v21, v19
	v_fma_f32 v22, v220, v20, v41
	v_fmac_f32_e32 v19, v219, v20
	v_fmac_f32_e32 v22, v219, v21
	v_fma_f32 v18, -v220, v22, v18
	v_fma_f32 v23, v220, v19, v40
	v_fmac_f32_e32 v18, v219, v19
	v_fmac_f32_e32 v23, v219, v22
	v_fma_f32 v17, -v220, v23, v17
	v_fma_f32 v24, v220, v18, v39
	v_fmac_f32_e32 v17, v219, v18
	v_fmac_f32_e32 v24, v219, v23
	v_fma_f32 v16, -v220, v24, v16
	v_fma_f32 v25, v220, v17, v38
	v_fmac_f32_e32 v16, v219, v17
	v_fmac_f32_e32 v25, v219, v24
	v_fma_f32 v15, -v220, v25, v15
	v_fma_f32 v26, v220, v16, v37
	v_fmac_f32_e32 v15, v219, v16
	v_fmac_f32_e32 v26, v219, v25
	v_fma_f32 v14, -v220, v26, v14
	v_fma_f32 v36, v220, v15, v36
	v_fmac_f32_e32 v14, v219, v15
	v_fmac_f32_e32 v36, v219, v26
	v_fma_f32 v13, -v220, v36, v13
	v_fma_f32 v35, v220, v14, v35
	v_fmac_f32_e32 v13, v219, v14
	v_fmac_f32_e32 v35, v219, v36
	v_fma_f32 v12, -v220, v35, v12
	v_fma_f32 v34, v220, v13, v34
	v_fmac_f32_e32 v12, v219, v13
	v_fmac_f32_e32 v34, v219, v35
	v_fma_f32 v11, -v220, v34, v11
	v_fma_f32 v33, v220, v12, v33
	v_fmac_f32_e32 v11, v219, v12
	v_fmac_f32_e32 v33, v219, v34
	v_fma_f32 v10, -v220, v33, v10
	v_fma_f32 v32, v220, v11, v32
	v_fmac_f32_e32 v10, v219, v11
	v_fmac_f32_e32 v32, v219, v33
	v_fma_f32 v9, -v220, v32, v9
	v_fma_f32 v31, v220, v10, v31
	v_fmac_f32_e32 v9, v219, v10
	v_fmac_f32_e32 v31, v219, v32
	v_fma_f32 v8, -v220, v31, v8
	v_fma_f32 v30, v220, v9, v30
	v_fmac_f32_e32 v8, v219, v9
	v_fmac_f32_e32 v30, v219, v31
	v_fma_f32 v7, -v220, v30, v7
	v_fma_f32 v29, v220, v8, v29
	v_fmac_f32_e32 v7, v219, v8
	v_fmac_f32_e32 v29, v219, v30
	v_fma_f32 v153, -v220, v29, v6
	v_fmac_f32_e32 v28, v220, v7
	v_fmac_f32_e32 v153, v219, v7
	v_fmac_f32_e32 v28, v219, v29
	v_cvt_pk_bf16_f32 v6, v153, v28
	ds_write2_b32 v169, v51, v6 offset1:32
	v_cvt_pk_bf16_f32 v6, v7, v29
	ds_write2_b32 v169, v5, v6 offset0:68 offset1:100
	v_cvt_pk_bf16_f32 v5, v8, v30
	ds_write2_b32 v169, v144, v5 offset0:136 offset1:168
	v_cvt_pk_bf16_f32 v5, v9, v31
	ds_write2_b32 v169, v145, v5 offset0:204 offset1:236
	v_cvt_pk_bf16_f32 v5, v10, v32
	ds_write2_b32 v213, v146, v5 offset0:16 offset1:48
	v_cvt_pk_bf16_f32 v5, v11, v33
	ds_write2_b32 v213, v147, v5 offset0:84 offset1:116
	v_cvt_pk_bf16_f32 v5, v12, v34
	ds_write2_b32 v213, v148, v5 offset0:152 offset1:184
	v_cvt_pk_bf16_f32 v5, v13, v35
	ds_write2_b32 v213, v149, v5 offset0:220 offset1:252
	v_cvt_pk_bf16_f32 v5, v14, v36
	ds_write2_b32 v214, v150, v5 offset0:32 offset1:64
	v_cvt_pk_bf16_f32 v5, v15, v26
	ds_write2_b32 v214, v45, v5 offset0:100 offset1:132
	v_cvt_pk_bf16_f32 v5, v16, v25
	ds_write2_b32 v214, v44, v5 offset0:168 offset1:200
	v_cvt_pk_bf16_f32 v5, v17, v24
	ds_write2_b32 v217, v151, v5 offset0:108 offset1:140
	v_cvt_pk_bf16_f32 v5, v18, v23
	ds_write2_b32 v215, v152, v5 offset0:48 offset1:80
	v_cvt_pk_bf16_f32 v5, v19, v22
	ds_write2_b32 v215, v27, v5 offset0:116 offset1:148
	v_cvt_pk_bf16_f32 v5, v20, v21
	ds_write2_b32 v215, v2, v5 offset0:184 offset1:216
	v_cvt_pk_bf16_f32 v1, v1, v3
	ds_write2_b32 v216, v0, v1 offset0:124 offset1:156
	s_nop 7
	ds_read_b128 v[0:3], v171
	ds_read_b128 v[6:9], v171 offset:64
	ds_read_b128 v[24:27], v171 offset:128
	ds_read_b128 v[10:13], v171 offset:192
	s_waitcnt lgkmcnt(3)
	v_mfma_f32_16x16x32_bf16 v[0:3], v[116:119], v[0:3], v[76:79]
	s_waitcnt lgkmcnt(2)
	v_mfma_f32_16x16x32_bf16 v[0:3], v[112:115], v[6:9], v[0:3]
	s_waitcnt lgkmcnt(1)
	v_mfma_f32_16x16x32_bf16 v[0:3], v[108:111], v[24:27], v[0:3]
	s_waitcnt lgkmcnt(0)
	v_mfma_f32_16x16x32_bf16 v[144:147], v[104:107], v[10:13], v[0:3]
	s_nop 5
	s_nop 7
	ds_read_b128 v[0:3], v171 offset:4352
	ds_read_b128 v[6:9], v171 offset:4416
	ds_read_b128 v[24:27], v171 offset:4480
	ds_read_b128 v[10:13], v171 offset:4544
	s_waitcnt lgkmcnt(3)
	v_mfma_f32_16x16x32_bf16 v[0:3], v[116:119], v[0:3], v[96:99]
	s_waitcnt lgkmcnt(2)
	v_mfma_f32_16x16x32_bf16 v[0:3], v[112:115], v[6:9], v[0:3]
	s_waitcnt lgkmcnt(1)
	v_mfma_f32_16x16x32_bf16 v[0:3], v[108:111], v[24:27], v[0:3]
	s_waitcnt lgkmcnt(0)
	v_mfma_f32_16x16x32_bf16 v[76:79], v[104:107], v[10:13], v[0:3]
	s_nop 5
	ds_read_b128 v[0:3], v212 offset:8704
	s_waitcnt lgkmcnt(0)
	v_mfma_f32_32x32x16_bf16 v[30:45], v[0:3], v[132:135], 0
	s_nop 11
	v_fma_f32 v5, -v189, v4, v45
	v_mfma_f32_32x32x16_bf16 v[6:21], v[0:3], v[136:139], 0
	v_fmac_f32_e32 v5, v188, v50
	s_nop 10
	v_fma_f32 v21, v189, v50, v21
	v_fmac_f32_e32 v21, v188, v4
	v_fma_f32 v4, -v189, v21, v44
	v_fma_f32 v20, v189, v5, v20
	v_fmac_f32_e32 v4, v188, v5
	v_fmac_f32_e32 v20, v188, v21
	v_fma_f32 v22, -v189, v20, v43
	v_fma_f32 v19, v189, v4, v19
	v_fmac_f32_e32 v22, v188, v4
	v_fmac_f32_e32 v19, v188, v20
	v_fma_f32 v23, -v189, v19, v42
	v_fma_f32 v18, v189, v22, v18
	v_fmac_f32_e32 v23, v188, v22
	v_fmac_f32_e32 v18, v188, v19
	v_fma_f32 v24, -v189, v18, v41
	v_fma_f32 v17, v189, v23, v17
	v_fmac_f32_e32 v24, v188, v23
	v_fmac_f32_e32 v17, v188, v18
	v_fma_f32 v25, -v189, v17, v40
	v_fma_f32 v16, v189, v24, v16
	v_fmac_f32_e32 v25, v188, v24
	v_fmac_f32_e32 v16, v188, v17
	v_fma_f32 v26, -v189, v16, v39
	v_fma_f32 v15, v189, v25, v15
	v_fmac_f32_e32 v26, v188, v25
	v_fmac_f32_e32 v15, v188, v16
	v_fma_f32 v27, -v189, v15, v38
	v_fma_f32 v14, v189, v26, v14
	v_fmac_f32_e32 v27, v188, v26
	v_fmac_f32_e32 v14, v188, v15
	v_fma_f32 v29, -v189, v14, v37
	v_fma_f32 v13, v189, v27, v13
	v_fmac_f32_e32 v29, v188, v27
	v_fmac_f32_e32 v13, v188, v14
	v_fma_f32 v36, -v189, v13, v36
	v_fma_f32 v12, v189, v29, v12
	v_fmac_f32_e32 v36, v188, v29
	v_fmac_f32_e32 v12, v188, v13
	v_fma_f32 v35, -v189, v12, v35
	v_fma_f32 v11, v189, v36, v11
	v_fmac_f32_e32 v35, v188, v36
	v_fmac_f32_e32 v11, v188, v12
	v_fma_f32 v34, -v189, v11, v34
	v_fma_f32 v10, v189, v35, v10
	v_fmac_f32_e32 v34, v188, v35
	v_fmac_f32_e32 v10, v188, v11
	v_fma_f32 v33, -v189, v10, v33
	v_fma_f32 v9, v189, v34, v9
	v_fmac_f32_e32 v33, v188, v34
	v_fmac_f32_e32 v9, v188, v10
	v_fma_f32 v32, -v189, v9, v32
	v_fma_f32 v8, v189, v33, v8
	v_fmac_f32_e32 v32, v188, v33
	v_fmac_f32_e32 v8, v188, v9
	v_fma_f32 v31, -v189, v8, v31
	v_fma_f32 v7, v189, v32, v7
	v_fmac_f32_e32 v31, v188, v32
	v_fmac_f32_e32 v7, v188, v8
	v_fma_f32 v50, -v189, v7, v30
	v_fmac_f32_e32 v6, v189, v31
	v_fmac_f32_e32 v50, v188, v31
	v_fmac_f32_e32 v6, v188, v7
	v_cvt_pk_bf16_f32 v7, v31, v7
	v_cvt_pk_bf16_f32 v96, v32, v8
	v_cvt_pk_bf16_f32 v97, v33, v9
	v_cvt_pk_bf16_f32 v98, v34, v10
	v_cvt_pk_bf16_f32 v99, v35, v11
	v_cvt_pk_bf16_f32 v148, v36, v12
	v_mfma_f32_32x32x16_bf16 v[30:45], v[0:3], v[124:127], 0
	v_cvt_pk_bf16_f32 v29, v29, v13
	v_cvt_pk_bf16_f32 v27, v27, v14
	v_cvt_pk_bf16_f32 v26, v26, v15
	v_cvt_pk_bf16_f32 v25, v25, v16
	v_cvt_pk_bf16_f32 v24, v24, v17
	v_cvt_pk_bf16_f32 v149, v23, v18
	v_cvt_pk_bf16_f32 v150, v22, v19
	v_cvt_pk_bf16_f32 v4, v4, v20
	v_cvt_pk_bf16_f32 v5, v5, v21
	v_mfma_f32_32x32x16_bf16 v[8:23], v[0:3], v[120:123], 0
	s_nop 10
	v_fma_f32 v0, -v220, v28, v45
	v_fmac_f32_e32 v0, v219, v153
	v_cvt_pk_bf16_f32 v51, v50, v6
	v_fma_f32 v1, v220, v153, v23
	v_fmac_f32_e32 v1, v219, v28
	v_fma_f32 v3, v220, v0, v22
	v_fma_f32 v2, -v220, v1, v44
	v_fmac_f32_e32 v3, v219, v1
	v_fmac_f32_e32 v2, v219, v0
	v_fma_f32 v22, -v220, v3, v43
	v_fmac_f32_e32 v22, v219, v2
	v_fma_f32 v21, v220, v2, v21
	v_fmac_f32_e32 v21, v219, v3
	v_fma_f32 v20, v220, v22, v20
	v_fma_f32 v23, -v220, v21, v42
	v_fmac_f32_e32 v20, v219, v21
	v_fmac_f32_e32 v23, v219, v22
	v_fma_f32 v28, -v220, v20, v41
	v_fmac_f32_e32 v28, v219, v23
	v_fma_f32 v19, v220, v23, v19
	v_fmac_f32_e32 v19, v219, v20
	v_fma_f32 v18, v220, v28, v18
	v_fma_f32 v40, -v220, v19, v40
	v_fmac_f32_e32 v18, v219, v19
	v_fmac_f32_e32 v40, v219, v28
	v_fma_f32 v39, -v220, v18, v39
	v_fmac_f32_e32 v39, v219, v40
	v_fma_f32 v17, v220, v40, v17
	v_fmac_f32_e32 v17, v219, v18
	v_fma_f32 v16, v220, v39, v16
	v_fma_f32 v38, -v220, v17, v38
	v_fmac_f32_e32 v16, v219, v17
	v_fmac_f32_e32 v38, v219, v39
	v_fma_f32 v37, -v220, v16, v37
	v_fmac_f32_e32 v37, v219, v38
	v_fma_f32 v15, v220, v38, v15
	v_fmac_f32_e32 v15, v219, v16
	v_fma_f32 v14, v220, v37, v14
	v_fma_f32 v36, -v220, v15, v36
	v_fmac_f32_e32 v14, v219, v15
	v_fmac_f32_e32 v36, v219, v37
	v_fma_f32 v35, -v220, v14, v35
	v_fmac_f32_e32 v35, v219, v36
	v_fma_f32 v13, v220, v36, v13
	v_fmac_f32_e32 v13, v219, v14
	v_fma_f32 v12, v220, v35, v12
	v_fma_f32 v34, -v220, v13, v34
	v_fmac_f32_e32 v12, v219, v13
	v_fmac_f32_e32 v34, v219, v35
	v_fma_f32 v33, -v220, v12, v33
	v_fmac_f32_e32 v33, v219, v34
	v_fma_f32 v11, v220, v34, v11
	v_fmac_f32_e32 v11, v219, v12
	v_fma_f32 v10, v220, v33, v10
	v_fma_f32 v32, -v220, v11, v32
	v_fmac_f32_e32 v10, v219, v11
	v_fmac_f32_e32 v32, v219, v33
	v_fma_f32 v31, -v220, v10, v31
	v_fmac_f32_e32 v31, v219, v32
	v_fma_f32 v9, v220, v32, v9
	v_fmac_f32_e32 v9, v219, v10
	v_fmac_f32_e32 v8, v220, v31
	v_fma_f32 v44, -v220, v9, v30
	v_fmac_f32_e32 v8, v219, v9
	v_cvt_pk_bf16_f32 v9, v31, v9
	ds_write2_b32 v169, v7, v9 offset0:68 offset1:100
	v_cvt_pk_bf16_f32 v7, v32, v10
	ds_write2_b32 v169, v96, v7 offset0:136 offset1:168
	v_cvt_pk_bf16_f32 v7, v33, v11
	ds_write2_b32 v169, v97, v7 offset0:204 offset1:236
	v_cvt_pk_bf16_f32 v7, v34, v12
	ds_write2_b32 v213, v98, v7 offset0:16 offset1:48
	v_cvt_pk_bf16_f32 v7, v35, v13
	ds_write2_b32 v213, v99, v7 offset0:84 offset1:116
	v_cvt_pk_bf16_f32 v7, v36, v14
	ds_write2_b32 v213, v148, v7 offset0:152 offset1:184
	v_cvt_pk_bf16_f32 v7, v37, v15
	ds_write2_b32 v213, v29, v7 offset0:220 offset1:252
	v_cvt_pk_bf16_f32 v7, v38, v16
	ds_write2_b32 v214, v27, v7 offset0:32 offset1:64
	v_cvt_pk_bf16_f32 v7, v39, v17
	ds_write2_b32 v214, v26, v7 offset0:100 offset1:132
	v_cvt_pk_bf16_f32 v7, v40, v18
	ds_write2_b32 v214, v25, v7 offset0:168 offset1:200
	v_cvt_pk_bf16_f32 v7, v28, v19
	ds_write2_b32 v217, v24, v7 offset0:108 offset1:140
	v_cvt_pk_bf16_f32 v7, v23, v20
	v_fmac_f32_e32 v44, v219, v31
	v_cvt_pk_bf16_f32 v30, v44, v8
	ds_write2_b32 v169, v51, v30 offset1:32
	ds_write2_b32 v215, v149, v7 offset0:48 offset1:80
	v_cvt_pk_bf16_f32 v7, v22, v21
	ds_write2_b32 v215, v150, v7 offset0:116 offset1:148
	v_cvt_pk_bf16_f32 v2, v2, v3
	ds_write2_b32 v215, v4, v2 offset0:184 offset1:216
	v_cvt_pk_bf16_f32 v0, v0, v1
	ds_write2_b32 v216, v5, v0 offset0:124 offset1:156
	ds_read_b128 v[0:3], v171
	ds_read_b128 v[10:13], v171 offset:64
	s_waitcnt lgkmcnt(1)
	v_mfma_f32_16x16x32_bf16 v[0:3], v[116:119], v[0:3], v[88:91]
	s_waitcnt lgkmcnt(0)
	v_mfma_f32_16x16x32_bf16 v[0:3], v[112:115], v[10:13], v[0:3]
	ds_read_b128 v[10:13], v171 offset:128
	ds_read_b128 v[14:17], v171 offset:192
	s_waitcnt lgkmcnt(1)
	v_mfma_f32_16x16x32_bf16 v[0:3], v[108:111], v[10:13], v[0:3]
	s_waitcnt lgkmcnt(0)
	v_mfma_f32_16x16x32_bf16 v[96:99], v[104:107], v[14:17], v[0:3]
	s_nop 5
	ds_read_b128 v[0:3], v171 offset:4352
	ds_read_b128 v[10:13], v171 offset:4416
	s_waitcnt lgkmcnt(1)
	v_mfma_f32_16x16x32_bf16 v[0:3], v[116:119], v[0:3], v[92:95]
	s_waitcnt lgkmcnt(0)
	v_mfma_f32_16x16x32_bf16 v[0:3], v[112:115], v[10:13], v[0:3]
	ds_read_b128 v[10:13], v171 offset:4480
	ds_read_b128 v[14:17], v171 offset:4544
	s_waitcnt lgkmcnt(1)
	v_mfma_f32_16x16x32_bf16 v[0:3], v[108:111], v[10:13], v[0:3]
	s_waitcnt lgkmcnt(0)
	v_mfma_f32_16x16x32_bf16 v[88:91], v[104:107], v[14:17], v[0:3]
	s_nop 5
	ds_read_b128 v[0:3], v212 offset:4352
	s_waitcnt lgkmcnt(0)
	v_mfma_f32_32x32x16_bf16 v[26:41], v[0:3], v[132:135], 0
	s_nop 11
	v_fma_f32 v4, -v189, v6, v41
	v_mfma_f32_32x32x16_bf16 v[10:25], v[0:3], v[136:139], 0
	v_fmac_f32_e32 v4, v188, v50
	s_nop 10
	v_fma_f32 v5, v189, v50, v25
	v_fmac_f32_e32 v5, v188, v6
	v_fma_f32 v6, -v189, v5, v40
	v_fma_f32 v7, v189, v4, v24
	v_fmac_f32_e32 v6, v188, v4
	v_fmac_f32_e32 v7, v188, v5
	v_fma_f32 v9, -v189, v7, v39
	v_fma_f32 v23, v189, v6, v23
	v_fmac_f32_e32 v9, v188, v6
	v_fmac_f32_e32 v23, v188, v7
	v_fma_f32 v24, -v189, v23, v38
	v_fma_f32 v22, v189, v9, v22
	v_fmac_f32_e32 v24, v188, v9
	v_fmac_f32_e32 v22, v188, v23
	v_fma_f32 v25, -v189, v22, v37
	v_fma_f32 v21, v189, v24, v21
	v_fmac_f32_e32 v25, v188, v24
	v_fmac_f32_e32 v21, v188, v22
	v_fma_f32 v45, -v189, v21, v36
	v_fma_f32 v20, v189, v25, v20
	v_fmac_f32_e32 v45, v188, v25
	v_fmac_f32_e32 v20, v188, v21
	v_fma_f32 v50, -v189, v20, v35
	v_fma_f32 v19, v189, v45, v19
	v_fmac_f32_e32 v50, v188, v45
	v_fmac_f32_e32 v19, v188, v20
	v_fma_f32 v34, -v189, v19, v34
	v_fma_f32 v18, v189, v50, v18
	v_fmac_f32_e32 v34, v188, v50
	v_fmac_f32_e32 v18, v188, v19
	v_fma_f32 v33, -v189, v18, v33
	v_fma_f32 v17, v189, v34, v17
	v_fmac_f32_e32 v33, v188, v34
	v_fmac_f32_e32 v17, v188, v18
	v_fma_f32 v32, -v189, v17, v32
	v_fma_f32 v16, v189, v33, v16
	v_fmac_f32_e32 v32, v188, v33
	v_fmac_f32_e32 v16, v188, v17
	v_fma_f32 v31, -v189, v16, v31
	v_fma_f32 v15, v189, v32, v15
	v_fmac_f32_e32 v31, v188, v32
	v_fmac_f32_e32 v15, v188, v16
	v_fma_f32 v30, -v189, v15, v30
	v_fma_f32 v14, v189, v31, v14
	v_fmac_f32_e32 v30, v188, v31
	v_fmac_f32_e32 v14, v188, v15
	v_fma_f32 v29, -v189, v14, v29
	v_fma_f32 v13, v189, v30, v13
	v_fmac_f32_e32 v29, v188, v30
	v_fmac_f32_e32 v13, v188, v14
	v_fma_f32 v28, -v189, v13, v28
	v_fma_f32 v12, v189, v29, v12
	v_fmac_f32_e32 v28, v188, v29
	v_fmac_f32_e32 v12, v188, v13
	v_fma_f32 v27, -v189, v12, v27
	v_fma_f32 v11, v189, v28, v11
	v_fmac_f32_e32 v27, v188, v28
	v_fmac_f32_e32 v11, v188, v12
	v_fma_f32 v51, -v189, v11, v26
	v_fmac_f32_e32 v10, v189, v27
	v_cvt_pk_bf16_f32 v93, v28, v12
	v_cvt_pk_bf16_f32 v94, v29, v13
	v_cvt_pk_bf16_f32 v95, v30, v14
	v_cvt_pk_bf16_f32 v148, v31, v15
	v_cvt_pk_bf16_f32 v149, v32, v16
	v_cvt_pk_bf16_f32 v150, v33, v17
	v_cvt_pk_bf16_f32 v151, v34, v18
	v_mfma_f32_32x32x16_bf16 v[28:43], v[0:3], v[124:127], 0
	v_fmac_f32_e32 v51, v188, v27
	v_fmac_f32_e32 v10, v188, v11
	v_cvt_pk_bf16_f32 v11, v27, v11
	v_cvt_pk_bf16_f32 v50, v50, v19
	v_cvt_pk_bf16_f32 v45, v45, v20
	v_cvt_pk_bf16_f32 v152, v25, v21
	v_cvt_pk_bf16_f32 v153, v24, v22
	v_cvt_pk_bf16_f32 v9, v9, v23
	v_mfma_f32_32x32x16_bf16 v[12:27], v[0:3], v[120:123], 0
	s_nop 8
	v_fma_f32 v0, -v220, v8, v43
	v_fmac_f32_e32 v0, v219, v44
	v_cvt_pk_bf16_f32 v4, v4, v5
	v_cvt_pk_bf16_f32 v6, v6, v7
	v_cvt_pk_bf16_f32 v92, v51, v10
	s_nop 0
	v_fma_f32 v1, v220, v44, v27
	v_fmac_f32_e32 v1, v219, v8
	v_fma_f32 v3, v220, v0, v26
	v_fma_f32 v2, -v220, v1, v42
	v_fmac_f32_e32 v3, v219, v1
	v_fmac_f32_e32 v2, v219, v0
	v_fma_f32 v5, -v220, v3, v41
	v_fmac_f32_e32 v5, v219, v2
	v_fma_f32 v7, v220, v2, v25
	v_fmac_f32_e32 v7, v219, v3
	v_fma_f32 v24, v220, v5, v24
	v_fma_f32 v8, -v220, v7, v40
	v_fmac_f32_e32 v24, v219, v7
	v_fmac_f32_e32 v8, v219, v5
	v_fma_f32 v25, -v220, v24, v39
	v_fmac_f32_e32 v25, v219, v8
	v_fma_f32 v23, v220, v8, v23
	v_fmac_f32_e32 v23, v219, v24
	v_fma_f32 v22, v220, v25, v22
	v_fma_f32 v26, -v220, v23, v38
	v_fmac_f32_e32 v22, v219, v23
	v_fmac_f32_e32 v26, v219, v25
	v_fma_f32 v27, -v220, v22, v37
	v_fmac_f32_e32 v27, v219, v26
	v_fma_f32 v21, v220, v26, v21
	v_fmac_f32_e32 v21, v219, v22
	v_fma_f32 v20, v220, v27, v20
	v_fma_f32 v36, -v220, v21, v36
	v_fmac_f32_e32 v20, v219, v21
	v_fmac_f32_e32 v36, v219, v27
	v_fma_f32 v35, -v220, v20, v35
	v_fmac_f32_e32 v35, v219, v36
	v_fma_f32 v19, v220, v36, v19
	v_fmac_f32_e32 v19, v219, v20
	v_fma_f32 v18, v220, v35, v18
	v_fma_f32 v34, -v220, v19, v34
	v_fmac_f32_e32 v18, v219, v19
	v_fmac_f32_e32 v34, v219, v35
	v_fma_f32 v33, -v220, v18, v33
	v_fmac_f32_e32 v33, v219, v34
	v_fma_f32 v17, v220, v34, v17
	v_fmac_f32_e32 v17, v219, v18
	v_fma_f32 v16, v220, v33, v16
	v_fma_f32 v32, -v220, v17, v32
	v_fmac_f32_e32 v16, v219, v17
	v_fmac_f32_e32 v32, v219, v33
	v_fma_f32 v31, -v220, v16, v31
	v_fmac_f32_e32 v31, v219, v32
	v_fma_f32 v15, v220, v32, v15
	v_fmac_f32_e32 v15, v219, v16
	v_fma_f32 v14, v220, v31, v14
	v_fma_f32 v30, -v220, v15, v30
	v_fmac_f32_e32 v14, v219, v15
	v_fmac_f32_e32 v30, v219, v31
	v_fma_f32 v29, -v220, v14, v29
	v_fmac_f32_e32 v29, v219, v30
	v_fma_f32 v13, v220, v30, v13
	v_fmac_f32_e32 v13, v219, v14
	v_fmac_f32_e32 v12, v220, v29
	v_fma_f32 v154, -v220, v13, v28
	v_fmac_f32_e32 v12, v219, v13
	v_cvt_pk_bf16_f32 v13, v29, v13
	ds_write2_b32 v169, v11, v13 offset0:68 offset1:100
	v_cvt_pk_bf16_f32 v11, v30, v14
	ds_write2_b32 v169, v93, v11 offset0:136 offset1:168
	v_cvt_pk_bf16_f32 v11, v31, v15
	ds_write2_b32 v169, v94, v11 offset0:204 offset1:236
	v_cvt_pk_bf16_f32 v11, v32, v16
	ds_write2_b32 v213, v95, v11 offset0:16 offset1:48
	v_cvt_pk_bf16_f32 v11, v33, v17
	ds_write2_b32 v213, v148, v11 offset0:84 offset1:116
	v_cvt_pk_bf16_f32 v11, v34, v18
	ds_write2_b32 v213, v149, v11 offset0:152 offset1:184
	v_cvt_pk_bf16_f32 v11, v35, v19
	ds_write2_b32 v213, v150, v11 offset0:220 offset1:252
	v_cvt_pk_bf16_f32 v11, v36, v20
	ds_write2_b32 v214, v151, v11 offset0:32 offset1:64
	v_cvt_pk_bf16_f32 v11, v27, v21
	ds_write2_b32 v214, v50, v11 offset0:100 offset1:132
	v_cvt_pk_bf16_f32 v11, v26, v22
	v_fmac_f32_e32 v154, v219, v29
	v_cvt_pk_bf16_f32 v28, v154, v12
	ds_write2_b32 v169, v92, v28 offset1:32
	ds_write2_b32 v214, v45, v11 offset0:168 offset1:200
	v_cvt_pk_bf16_f32 v11, v25, v23
	ds_write2_b32 v217, v152, v11 offset0:108 offset1:140
	v_cvt_pk_bf16_f32 v8, v8, v24
	ds_write2_b32 v215, v153, v8 offset0:48 offset1:80
	v_cvt_pk_bf16_f32 v5, v5, v7
	ds_write2_b32 v215, v9, v5 offset0:116 offset1:148
	v_cvt_pk_bf16_f32 v2, v2, v3
	ds_write2_b32 v215, v6, v2 offset0:184 offset1:216
	v_cvt_pk_bf16_f32 v0, v0, v1
	ds_write2_b32 v216, v4, v0 offset0:124 offset1:156
	s_nop 7
	ds_read_b128 v[0:3], v171
	ds_read_b128 v[4:7], v171 offset:64
	ds_read_b128 v[92:95], v171 offset:128
	ds_read_b128 v[14:17], v171 offset:192
	s_waitcnt lgkmcnt(3)
	v_mfma_f32_16x16x32_bf16 v[0:3], v[116:119], v[0:3], v[64:67]
	s_waitcnt lgkmcnt(2)
	v_mfma_f32_16x16x32_bf16 v[0:3], v[112:115], v[4:7], v[0:3]
	s_waitcnt lgkmcnt(1)
	v_mfma_f32_16x16x32_bf16 v[0:3], v[108:111], v[92:95], v[0:3]
	s_waitcnt lgkmcnt(0)
	v_mfma_f32_16x16x32_bf16 v[64:67], v[104:107], v[14:17], v[0:3]
	s_nop 5
	ds_read_b128 v[0:3], v171 offset:4352
	ds_read_b128 v[4:7], v171 offset:4416
	s_waitcnt lgkmcnt(1)
	v_mfma_f32_16x16x32_bf16 v[0:3], v[116:119], v[0:3], v[68:71]
	s_waitcnt lgkmcnt(0)
	v_mfma_f32_16x16x32_bf16 v[0:3], v[112:115], v[4:7], v[0:3]
	ds_read_b128 v[4:7], v171 offset:4480
	ds_read_b128 v[14:17], v171 offset:4544
	s_waitcnt lgkmcnt(1)
	v_mfma_f32_16x16x32_bf16 v[0:3], v[108:111], v[4:7], v[0:3]
	s_waitcnt lgkmcnt(0)
	v_mfma_f32_16x16x32_bf16 v[4:7], v[104:107], v[14:17], v[0:3]
	s_nop 5
	ds_read_b128 v[0:3], v212
	s_waitcnt lgkmcnt(0)
	v_mfma_f32_32x32x16_bf16 v[30:45], v[0:3], v[132:135], 0
	s_nop 11
	v_fma_f32 v9, -v189, v10, v45
	v_mfma_f32_32x32x16_bf16 v[14:29], v[0:3], v[136:139], 0
	v_fmac_f32_e32 v9, v188, v51
	s_nop 10
	v_fma_f32 v8, v189, v51, v29
	v_fmac_f32_e32 v8, v188, v10
	v_fma_f32 v10, v189, v9, v28
	v_fma_f32 v11, -v189, v8, v44
	v_fmac_f32_e32 v10, v188, v8
	v_fmac_f32_e32 v11, v188, v9
	v_fma_f32 v13, v189, v11, v27
	v_fma_f32 v43, -v189, v10, v43
	v_fmac_f32_e32 v13, v188, v10
	v_fmac_f32_e32 v43, v188, v11
	v_fma_f32 v44, v189, v43, v26
	v_fma_f32 v42, -v189, v13, v42
	v_fmac_f32_e32 v44, v188, v13
	v_fmac_f32_e32 v42, v188, v43
	v_fma_f32 v45, v189, v42, v25
	v_fma_f32 v41, -v189, v44, v41
	v_fmac_f32_e32 v45, v188, v44
	v_fmac_f32_e32 v41, v188, v42
	v_fma_f32 v50, v189, v41, v24
	v_fma_f32 v40, -v189, v45, v40
	v_fmac_f32_e32 v50, v188, v45
	v_fmac_f32_e32 v40, v188, v41
	v_fma_f32 v51, v189, v40, v23
	v_fma_f32 v39, -v189, v50, v39
	v_fmac_f32_e32 v51, v188, v50
	v_fmac_f32_e32 v39, v188, v40
	v_fma_f32 v22, v189, v39, v22
	v_fma_f32 v23, -v189, v51, v38
	v_fmac_f32_e32 v22, v188, v51
	v_fmac_f32_e32 v23, v188, v39
	v_fma_f32 v21, v189, v23, v21
	v_fma_f32 v24, -v189, v22, v37
	v_fmac_f32_e32 v21, v188, v22
	v_fmac_f32_e32 v24, v188, v23
	v_fma_f32 v20, v189, v24, v20
	v_fma_f32 v25, -v189, v21, v36
	v_fmac_f32_e32 v20, v188, v21
	v_fmac_f32_e32 v25, v188, v24
	v_fma_f32 v19, v189, v25, v19
	v_fma_f32 v26, -v189, v20, v35
	v_fmac_f32_e32 v19, v188, v20
	v_fmac_f32_e32 v26, v188, v25
	v_fma_f32 v18, v189, v26, v18
	v_fma_f32 v27, -v189, v19, v34
	v_fmac_f32_e32 v18, v188, v19
	v_fmac_f32_e32 v27, v188, v26
	v_fma_f32 v17, v189, v27, v17
	v_fma_f32 v28, -v189, v18, v33
	v_fmac_f32_e32 v17, v188, v18
	v_fmac_f32_e32 v28, v188, v27
	v_fma_f32 v16, v189, v28, v16
	v_fma_f32 v29, -v189, v17, v32
	v_fmac_f32_e32 v16, v188, v17
	v_fmac_f32_e32 v29, v188, v28
	v_fma_f32 v15, v189, v29, v15
	v_fma_f32 v31, -v189, v16, v31
	v_fmac_f32_e32 v15, v188, v16
	v_fmac_f32_e32 v31, v188, v29
	v_fmac_f32_e32 v14, v189, v31
	v_fma_f32 v30, -v189, v15, v30
	v_fmac_f32_e32 v14, v188, v15
	v_fmac_f32_e32 v30, v188, v31
	v_cvt_pk_bf16_f32 v68, v30, v14
	v_cvt_pk_bf16_f32 v69, v31, v15
	v_cvt_pk_bf16_f32 v70, v29, v16
	v_cvt_pk_bf16_f32 v71, v28, v17
	v_cvt_pk_bf16_f32 v92, v27, v18
	v_cvt_pk_bf16_f32 v93, v26, v19
	v_cvt_pk_bf16_f32 v94, v25, v20
	v_cvt_pk_bf16_f32 v95, v24, v21
	v_cvt_pk_bf16_f32 v132, v23, v22
	v_mfma_f32_32x32x16_bf16 v[14:29], v[0:3], v[124:127], 0
	v_cvt_pk_bf16_f32 v51, v39, v51
	v_cvt_pk_bf16_f32 v50, v40, v50
	v_cvt_pk_bf16_f32 v124, v41, v45
	v_cvt_pk_bf16_f32 v125, v42, v44
	v_cvt_pk_bf16_f32 v13, v43, v13
	v_cvt_pk_bf16_f32 v8, v9, v8
	v_cvt_pk_bf16_f32 v10, v11, v10
	v_mfma_f32_32x32x16_bf16 v[30:45], v[0:3], v[120:123], 0
	s_nop 10
	v_fma_f32 v1, -v220, v12, v29
	v_fmac_f32_e32 v1, v219, v154
	v_fma_f32 v0, v220, v154, v45
	v_fmac_f32_e32 v0, v219, v12
	v_fma_f32 v3, -v220, v0, v28
	v_fma_f32 v2, v220, v1, v44
	v_fmac_f32_e32 v3, v219, v1
	v_fmac_f32_e32 v2, v219, v0
	v_fma_f32 v9, v220, v3, v43
	v_fmac_f32_e32 v9, v219, v2
	v_fma_f32 v11, -v220, v2, v27
	v_fmac_f32_e32 v11, v219, v3
	v_fma_f32 v26, -v220, v9, v26
	v_fma_f32 v12, v220, v11, v42
	v_fmac_f32_e32 v26, v219, v11
	v_fmac_f32_e32 v12, v219, v9
	v_fma_f32 v27, v220, v26, v41
	v_fmac_f32_e32 v27, v219, v12
	v_fma_f32 v25, -v220, v12, v25
	v_fmac_f32_e32 v25, v219, v26
	v_fma_f32 v24, -v220, v27, v24
	v_fma_f32 v28, v220, v25, v40
	v_fmac_f32_e32 v24, v219, v25
	v_fmac_f32_e32 v28, v219, v27
	v_fma_f32 v29, v220, v24, v39
	v_fmac_f32_e32 v29, v219, v28
	v_fma_f32 v23, -v220, v28, v23
	v_fmac_f32_e32 v23, v219, v24
	v_fma_f32 v22, -v220, v29, v22
	v_fma_f32 v38, v220, v23, v38
	v_fmac_f32_e32 v22, v219, v23
	v_fmac_f32_e32 v38, v219, v29
	v_fma_f32 v37, v220, v22, v37
	v_fmac_f32_e32 v37, v219, v38
	v_fma_f32 v21, -v220, v38, v21
	v_fmac_f32_e32 v21, v219, v22
	v_fma_f32 v20, -v220, v37, v20
	v_fma_f32 v36, v220, v21, v36
	v_fmac_f32_e32 v20, v219, v21
	v_fmac_f32_e32 v36, v219, v37
	v_fma_f32 v35, v220, v20, v35
	v_fmac_f32_e32 v35, v219, v36
	v_fma_f32 v19, -v220, v36, v19
	v_fmac_f32_e32 v19, v219, v20
	v_fma_f32 v18, -v220, v35, v18
	v_fma_f32 v34, v220, v19, v34
	v_fmac_f32_e32 v18, v219, v19
	v_fmac_f32_e32 v34, v219, v35
	v_fma_f32 v33, v220, v18, v33
	v_fmac_f32_e32 v33, v219, v34
	v_fma_f32 v17, -v220, v34, v17
	v_fmac_f32_e32 v17, v219, v18
	v_fma_f32 v16, -v220, v33, v16
	v_fma_f32 v32, v220, v17, v32
	v_fmac_f32_e32 v16, v219, v17
	v_fmac_f32_e32 v32, v219, v33
	v_fma_f32 v31, v220, v16, v31
	v_fmac_f32_e32 v31, v219, v32
	v_fma_f32 v15, -v220, v32, v15
	v_fmac_f32_e32 v15, v219, v16
	v_fma_f32 v14, -v220, v31, v14
	v_fmac_f32_e32 v30, v220, v15
	v_fmac_f32_e32 v14, v219, v15
	v_fmac_f32_e32 v30, v219, v31
	v_cvt_pk_bf16_f32 v14, v14, v30
	ds_write2_b32 v169, v68, v14 offset1:32
	v_cvt_pk_bf16_f32 v14, v15, v31
	ds_write2_b32 v169, v69, v14 offset0:68 offset1:100
	v_cvt_pk_bf16_f32 v14, v16, v32
	ds_write2_b32 v169, v70, v14 offset0:136 offset1:168
	v_cvt_pk_bf16_f32 v14, v17, v33
	ds_write2_b32 v169, v71, v14 offset0:204 offset1:236
	v_cvt_pk_bf16_f32 v14, v18, v34
	ds_write2_b32 v213, v92, v14 offset0:16 offset1:48
	v_cvt_pk_bf16_f32 v14, v19, v35
	ds_write2_b32 v213, v93, v14 offset0:84 offset1:116
	v_cvt_pk_bf16_f32 v14, v20, v36
	ds_write2_b32 v213, v94, v14 offset0:152 offset1:184
	v_cvt_pk_bf16_f32 v14, v21, v37
	ds_write2_b32 v213, v95, v14 offset0:220 offset1:252
	v_cvt_pk_bf16_f32 v14, v22, v38
	ds_write2_b32 v214, v132, v14 offset0:32 offset1:64
	v_cvt_pk_bf16_f32 v14, v23, v29
	ds_write2_b32 v214, v51, v14 offset0:100 offset1:132
	v_cvt_pk_bf16_f32 v14, v24, v28
	ds_write2_b32 v214, v50, v14 offset0:168 offset1:200
	v_cvt_pk_bf16_f32 v14, v25, v27
	ds_write2_b32 v217, v124, v14 offset0:108 offset1:140
	v_cvt_pk_bf16_f32 v12, v26, v12
	ds_write2_b32 v215, v125, v12 offset0:48 offset1:80
	v_cvt_pk_bf16_f32 v9, v11, v9
	ds_write2_b32 v215, v13, v9 offset0:116 offset1:148
	v_cvt_pk_bf16_f32 v2, v3, v2
	ds_write2_b32 v215, v10, v2 offset0:184 offset1:216
	v_cvt_pk_bf16_f32 v0, v1, v0
	ds_write2_b32 v216, v8, v0 offset0:124 offset1:156
	ds_read_b128 v[0:3], v171
	ds_read_b128 v[8:11], v171 offset:64
	s_waitcnt lgkmcnt(1)
	v_mfma_f32_16x16x32_bf16 v[0:3], v[116:119], v[0:3], v[80:83]
	s_waitcnt lgkmcnt(0)
	v_mfma_f32_16x16x32_bf16 v[0:3], v[112:115], v[8:11], v[0:3]
	ds_read_b128 v[8:11], v171 offset:128
	ds_read_b128 v[12:15], v171 offset:192
	s_waitcnt lgkmcnt(1)
	v_mfma_f32_16x16x32_bf16 v[0:3], v[108:111], v[8:11], v[0:3]
	s_waitcnt lgkmcnt(0)
	v_mfma_f32_16x16x32_bf16 v[12:15], v[104:107], v[12:15], v[0:3]
	s_nop 5
	ds_read_b128 v[0:3], v171 offset:4352
	ds_read_b128 v[8:11], v171 offset:4416
	s_waitcnt lgkmcnt(1)
	v_mfma_f32_16x16x32_bf16 v[0:3], v[116:119], v[0:3], v[84:87]
	s_waitcnt lgkmcnt(0)
	v_mfma_f32_16x16x32_bf16 v[0:3], v[112:115], v[8:11], v[0:3]
	ds_read_b128 v[8:11], v171 offset:4480
	ds_read_b128 v[16:19], v171 offset:4544
	s_waitcnt lgkmcnt(1)
	v_mfma_f32_16x16x32_bf16 v[0:3], v[108:111], v[8:11], v[0:3]
	s_waitcnt lgkmcnt(0)
	v_mfma_f32_16x16x32_bf16 v[8:11], v[104:107], v[16:19], v[0:3]
	s_lshl_b32 s14, s14, 4
	s_ashr_i32 s15, s14, 31
	s_nop 3
	v_lshl_add_u64 v[0:1], s[14:15], 2, v[182:183]
	global_load_dwordx4 v[0:3], v[0:1], off
	ds_read_b64 v[16:17], v175
	s_waitcnt lgkmcnt(0)
	v_lshlrev_b32_e32 v18, 16, v16
	v_and_b32_e32 v16, 0xffff0000, v16
	s_waitcnt vmcnt(0)
	v_fma_f32 v13, v1, v16, v13
	v_lshlrev_b32_e32 v16, 16, v17
	v_fma_f32 v12, v0, v18, v12
	v_fma_f32 v14, v2, v16, v14
	v_and_b32_e32 v16, 0xffff0000, v17
	v_fmac_f32_e32 v15, v3, v16
	v_mul_f32_e32 v16, v12, v12
	v_fmamk_f32 v16, v16, 0x3d922279, v192
	v_mul_f32_e32 v16, v12, v16
	v_mul_f32_e32 v16, 0xbfb8aa3b, v16
	v_exp_f32_e32 v16, v16
	s_nop 0
	v_add_f32_e32 v16, 1.0, v16
	v_rcp_f32_e32 v16, v16
	s_nop 0
	v_mul_f32_e32 v12, v12, v16
	v_mul_f32_e32 v16, v13, v13
	v_fmamk_f32 v16, v16, 0x3d922279, v192
	v_mul_f32_e32 v16, v13, v16
	v_mul_f32_e32 v16, 0xbfb8aa3b, v16
	v_exp_f32_e32 v16, v16
	s_nop 0
	v_add_f32_e32 v16, 1.0, v16
	v_rcp_f32_e32 v16, v16
	s_nop 0
	v_mul_f32_e32 v13, v13, v16
	v_cvt_pk_bf16_f32 v12, v12, v13
	v_mul_f32_e32 v13, v14, v14
	v_fmamk_f32 v13, v13, 0x3d922279, v192
	v_mul_f32_e32 v13, v14, v13
	v_mul_f32_e32 v13, 0xbfb8aa3b, v13
	v_exp_f32_e32 v13, v13
	s_nop 0
	v_add_f32_e32 v13, 1.0, v13
	v_rcp_f32_e32 v13, v13
	s_nop 0
	v_mul_f32_e32 v13, v14, v13
	v_mul_f32_e32 v14, v15, v15
	v_fmamk_f32 v14, v14, 0x3d922279, v192
	v_mul_f32_e32 v14, v15, v14
	v_mul_f32_e32 v14, 0xbfb8aa3b, v14
	v_exp_f32_e32 v14, v14
	s_nop 0
	v_add_f32_e32 v14, 1.0, v14
	v_rcp_f32_e32 v14, v14
	s_nop 0
	v_mul_f32_e32 v14, v15, v14
	v_cvt_pk_bf16_f32 v13, v13, v14
	ds_write_b64 v175, v[12:13]
	ds_read_b64 v[12:13], v175 offset:4352
	s_waitcnt lgkmcnt(0)
	v_lshlrev_b32_e32 v14, 16, v12
	v_fma_f32 v14, v0, v14, v64
	v_lshlrev_b32_e32 v15, 16, v13
	v_and_b32_e32 v13, 0xffff0000, v13
	v_fmac_f32_e32 v67, v3, v13
	v_mul_f32_e32 v13, v14, v14
	v_fmamk_f32 v13, v13, 0x3d922279, v192
	v_mul_f32_e32 v13, v14, v13
	v_mul_f32_e32 v13, 0xbfb8aa3b, v13
	v_exp_f32_e32 v13, v13
	v_and_b32_e32 v12, 0xffff0000, v12
	v_fma_f32 v12, v1, v12, v65
	v_fma_f32 v15, v2, v15, v66
	v_add_f32_e32 v13, 1.0, v13
	v_rcp_f32_e32 v13, v13
	s_nop 0
	v_mul_f32_e32 v13, v14, v13
	v_mul_f32_e32 v14, v12, v12
	v_fmamk_f32 v14, v14, 0x3d922279, v192
	v_mul_f32_e32 v14, v12, v14
	v_mul_f32_e32 v14, 0xbfb8aa3b, v14
	v_exp_f32_e32 v14, v14
	s_nop 0
	v_add_f32_e32 v14, 1.0, v14
	v_rcp_f32_e32 v14, v14
	s_nop 0
	v_mul_f32_e32 v12, v12, v14
	v_cvt_pk_bf16_f32 v12, v13, v12
	v_mul_f32_e32 v13, v15, v15
	v_fmamk_f32 v13, v13, 0x3d922279, v192
	v_mul_f32_e32 v14, v67, v67
	v_mul_f32_e32 v13, v15, v13
	v_fmamk_f32 v14, v14, 0x3d922279, v192
	v_mul_f32_e32 v13, 0xbfb8aa3b, v13
	v_mul_f32_e32 v14, v67, v14
	v_exp_f32_e32 v13, v13
	v_mul_f32_e32 v14, 0xbfb8aa3b, v14
	v_exp_f32_e32 v14, v14
	v_add_f32_e32 v13, 1.0, v13
	v_rcp_f32_e32 v13, v13
	v_add_f32_e32 v14, 1.0, v14
	v_rcp_f32_e32 v14, v14
	v_mul_f32_e32 v13, v15, v13
	v_mul_f32_e32 v14, v67, v14
	v_cvt_pk_bf16_f32 v13, v13, v14
	ds_write_b64 v175, v[12:13] offset:4352
	ds_read_b64 v[12:13], v175 offset:8704
	s_waitcnt lgkmcnt(0)
	v_lshlrev_b32_e32 v14, 16, v12
	v_fma_f32 v14, v0, v14, v96
	v_lshlrev_b32_e32 v15, 16, v13
	v_and_b32_e32 v13, 0xffff0000, v13
	v_fmac_f32_e32 v99, v3, v13
	v_mul_f32_e32 v13, v14, v14
	v_fmamk_f32 v13, v13, 0x3d922279, v192
	v_mul_f32_e32 v13, v14, v13
	v_mul_f32_e32 v13, 0xbfb8aa3b, v13
	v_exp_f32_e32 v13, v13
	v_and_b32_e32 v12, 0xffff0000, v12
	v_fma_f32 v12, v1, v12, v97
	v_fma_f32 v15, v2, v15, v98
	v_add_f32_e32 v13, 1.0, v13
	v_rcp_f32_e32 v13, v13
	s_nop 0
	v_mul_f32_e32 v13, v14, v13
	v_mul_f32_e32 v14, v12, v12
	v_fmamk_f32 v14, v14, 0x3d922279, v192
	v_mul_f32_e32 v14, v12, v14
	v_mul_f32_e32 v14, 0xbfb8aa3b, v14
	v_exp_f32_e32 v14, v14
	s_nop 0
	v_add_f32_e32 v14, 1.0, v14
	v_rcp_f32_e32 v14, v14
	s_nop 0
	v_mul_f32_e32 v12, v12, v14
	v_cvt_pk_bf16_f32 v12, v13, v12
	v_mul_f32_e32 v13, v15, v15
	v_fmamk_f32 v13, v13, 0x3d922279, v192
	v_mul_f32_e32 v14, v99, v99
	v_mul_f32_e32 v13, v15, v13
	v_fmamk_f32 v14, v14, 0x3d922279, v192
	v_mul_f32_e32 v13, 0xbfb8aa3b, v13
	v_mul_f32_e32 v14, v99, v14
	v_exp_f32_e32 v13, v13
	v_mul_f32_e32 v14, 0xbfb8aa3b, v14
	v_exp_f32_e32 v14, v14
	v_add_f32_e32 v13, 1.0, v13
	v_rcp_f32_e32 v13, v13
	v_add_f32_e32 v14, 1.0, v14
	v_rcp_f32_e32 v14, v14
	v_mul_f32_e32 v13, v15, v13
	v_mul_f32_e32 v14, v99, v14
	v_cvt_pk_bf16_f32 v13, v13, v14
	ds_write_b64 v175, v[12:13] offset:8704
	ds_read_b64 v[12:13], v175 offset:13056
	s_waitcnt lgkmcnt(0)
	v_lshlrev_b32_e32 v14, 16, v12
	v_fma_f32 v14, v0, v14, v144
	v_lshlrev_b32_e32 v15, 16, v13
	v_and_b32_e32 v13, 0xffff0000, v13
	v_fmac_f32_e32 v147, v3, v13
	v_mul_f32_e32 v13, v14, v14
	v_fmamk_f32 v13, v13, 0x3d922279, v192
	v_mul_f32_e32 v13, v14, v13
	v_mul_f32_e32 v13, 0xbfb8aa3b, v13
	v_exp_f32_e32 v13, v13
	v_and_b32_e32 v12, 0xffff0000, v12
	v_fma_f32 v12, v1, v12, v145
	v_fma_f32 v15, v2, v15, v146
	v_add_f32_e32 v13, 1.0, v13
	v_rcp_f32_e32 v13, v13
	s_nop 0
	v_mul_f32_e32 v13, v14, v13
	v_mul_f32_e32 v14, v12, v12
	v_fmamk_f32 v14, v14, 0x3d922279, v192
	v_mul_f32_e32 v14, v12, v14
	v_mul_f32_e32 v14, 0xbfb8aa3b, v14
	v_exp_f32_e32 v14, v14
	s_nop 0
	v_add_f32_e32 v14, 1.0, v14
	v_rcp_f32_e32 v14, v14
	s_nop 0
	v_mul_f32_e32 v12, v12, v14
	v_cvt_pk_bf16_f32 v12, v13, v12
	v_mul_f32_e32 v13, v15, v15
	v_fmamk_f32 v13, v13, 0x3d922279, v192
	v_mul_f32_e32 v14, v147, v147
	v_mul_f32_e32 v13, v15, v13
	v_fmamk_f32 v14, v14, 0x3d922279, v192
	v_mul_f32_e32 v13, 0xbfb8aa3b, v13
	v_mul_f32_e32 v14, v147, v14
	v_exp_f32_e32 v13, v13
	v_mul_f32_e32 v14, 0xbfb8aa3b, v14
	v_exp_f32_e32 v14, v14
	v_add_f32_e32 v13, 1.0, v13
	v_rcp_f32_e32 v13, v13
	v_add_f32_e32 v14, 1.0, v14
	v_rcp_f32_e32 v14, v14
	v_mul_f32_e32 v13, v15, v13
	v_mul_f32_e32 v14, v147, v14
	v_cvt_pk_bf16_f32 v13, v13, v14
	ds_write_b64 v175, v[12:13] offset:13056
	ds_read_b64 v[12:13], v175 offset:17408
	s_waitcnt lgkmcnt(0)
	v_lshlrev_b32_e32 v14, 16, v12
	v_fma_f32 v14, v0, v14, v140
	v_lshlrev_b32_e32 v15, 16, v13
	v_and_b32_e32 v13, 0xffff0000, v13
	v_fmac_f32_e32 v143, v3, v13
	v_mul_f32_e32 v13, v14, v14
	v_fmamk_f32 v13, v13, 0x3d922279, v192
	v_mul_f32_e32 v13, v14, v13
	v_mul_f32_e32 v13, 0xbfb8aa3b, v13
	v_exp_f32_e32 v13, v13
	v_and_b32_e32 v12, 0xffff0000, v12
	v_fma_f32 v12, v1, v12, v141
	v_fma_f32 v15, v2, v15, v142
	v_add_f32_e32 v13, 1.0, v13
	v_rcp_f32_e32 v13, v13
	s_nop 0
	v_mul_f32_e32 v13, v14, v13
	v_mul_f32_e32 v14, v12, v12
	v_fmamk_f32 v14, v14, 0x3d922279, v192
	v_mul_f32_e32 v14, v12, v14
	v_mul_f32_e32 v14, 0xbfb8aa3b, v14
	v_exp_f32_e32 v14, v14
	s_nop 0
	v_add_f32_e32 v14, 1.0, v14
	v_rcp_f32_e32 v14, v14
	s_nop 0
	v_mul_f32_e32 v12, v12, v14
	v_cvt_pk_bf16_f32 v12, v13, v12
	v_mul_f32_e32 v13, v15, v15
	v_fmamk_f32 v13, v13, 0x3d922279, v192
	v_mul_f32_e32 v14, v143, v143
	v_mul_f32_e32 v13, v15, v13
	v_fmamk_f32 v14, v14, 0x3d922279, v192
	v_mul_f32_e32 v13, 0xbfb8aa3b, v13
	v_mul_f32_e32 v14, v143, v14
	v_exp_f32_e32 v13, v13
	v_mul_f32_e32 v14, 0xbfb8aa3b, v14
	v_exp_f32_e32 v14, v14
	v_add_f32_e32 v13, 1.0, v13
	v_rcp_f32_e32 v13, v13
	v_add_f32_e32 v14, 1.0, v14
	v_rcp_f32_e32 v14, v14
	v_mul_f32_e32 v13, v15, v13
	v_mul_f32_e32 v14, v143, v14
	v_cvt_pk_bf16_f32 v13, v13, v14
	ds_write_b64 v175, v[12:13] offset:17408
	ds_read_b64 v[12:13], v175 offset:21760
	s_waitcnt lgkmcnt(0)
	v_lshlrev_b32_e32 v14, 16, v12
	v_fma_f32 v14, v0, v14, v128
	v_lshlrev_b32_e32 v15, 16, v13
	v_and_b32_e32 v13, 0xffff0000, v13
	v_fmac_f32_e32 v131, v3, v13
	v_mul_f32_e32 v13, v14, v14
	v_fmamk_f32 v13, v13, 0x3d922279, v192
	v_mul_f32_e32 v13, v14, v13
	v_mul_f32_e32 v13, 0xbfb8aa3b, v13
	v_exp_f32_e32 v13, v13
	v_and_b32_e32 v12, 0xffff0000, v12
	v_fma_f32 v12, v1, v12, v129
	v_fma_f32 v15, v2, v15, v130
	v_add_f32_e32 v13, 1.0, v13
	v_rcp_f32_e32 v13, v13
	s_nop 0
	v_mul_f32_e32 v13, v14, v13
	v_mul_f32_e32 v14, v12, v12
	v_fmamk_f32 v14, v14, 0x3d922279, v192
	v_mul_f32_e32 v14, v12, v14
	v_mul_f32_e32 v14, 0xbfb8aa3b, v14
	v_exp_f32_e32 v14, v14
	s_nop 0
	v_add_f32_e32 v14, 1.0, v14
	v_rcp_f32_e32 v14, v14
	s_nop 0
	v_mul_f32_e32 v12, v12, v14
	v_cvt_pk_bf16_f32 v12, v13, v12
	v_mul_f32_e32 v13, v15, v15
	v_fmamk_f32 v13, v13, 0x3d922279, v192
	v_mul_f32_e32 v14, v131, v131
	v_mul_f32_e32 v13, v15, v13
	v_fmamk_f32 v14, v14, 0x3d922279, v192
	v_mul_f32_e32 v13, 0xbfb8aa3b, v13
	v_mul_f32_e32 v14, v131, v14
	v_exp_f32_e32 v13, v13
	v_mul_f32_e32 v14, 0xbfb8aa3b, v14
	v_exp_f32_e32 v14, v14
	v_add_f32_e32 v13, 1.0, v13
	v_rcp_f32_e32 v13, v13
	v_add_f32_e32 v14, 1.0, v14
	v_rcp_f32_e32 v14, v14
	v_mul_f32_e32 v13, v15, v13
	v_mul_f32_e32 v14, v131, v14
	v_cvt_pk_bf16_f32 v13, v13, v14
	ds_write_b64 v175, v[12:13] offset:21760
	ds_read_b64 v[12:13], v175 offset:26112
	s_waitcnt lgkmcnt(0)
	v_lshlrev_b32_e32 v14, 16, v12
	v_fma_f32 v14, v0, v14, v100
	v_lshlrev_b32_e32 v15, 16, v13
	v_and_b32_e32 v13, 0xffff0000, v13
	v_fmac_f32_e32 v103, v3, v13
	v_mul_f32_e32 v13, v14, v14
	v_fmamk_f32 v13, v13, 0x3d922279, v192
	v_mul_f32_e32 v13, v14, v13
	v_mul_f32_e32 v13, 0xbfb8aa3b, v13
	v_exp_f32_e32 v13, v13
	v_and_b32_e32 v12, 0xffff0000, v12
	v_fma_f32 v12, v1, v12, v101
	v_fma_f32 v15, v2, v15, v102
	v_add_f32_e32 v13, 1.0, v13
	v_rcp_f32_e32 v13, v13
	s_nop 0
	v_mul_f32_e32 v13, v14, v13
	v_mul_f32_e32 v14, v12, v12
	v_fmamk_f32 v14, v14, 0x3d922279, v192
	v_mul_f32_e32 v14, v12, v14
	v_mul_f32_e32 v14, 0xbfb8aa3b, v14
	v_exp_f32_e32 v14, v14
	s_nop 0
	v_add_f32_e32 v14, 1.0, v14
	v_rcp_f32_e32 v14, v14
	s_nop 0
	v_mul_f32_e32 v12, v12, v14
	v_cvt_pk_bf16_f32 v12, v13, v12
	v_mul_f32_e32 v13, v15, v15
	v_fmamk_f32 v13, v13, 0x3d922279, v192
	v_mul_f32_e32 v14, v103, v103
	v_mul_f32_e32 v13, v15, v13
	v_fmamk_f32 v14, v14, 0x3d922279, v192
	v_mul_f32_e32 v13, 0xbfb8aa3b, v13
	v_mul_f32_e32 v14, v103, v14
	v_exp_f32_e32 v13, v13
	v_mul_f32_e32 v14, 0xbfb8aa3b, v14
	v_exp_f32_e32 v14, v14
	v_add_f32_e32 v13, 1.0, v13
	v_rcp_f32_e32 v13, v13
	v_add_f32_e32 v14, 1.0, v14
	v_rcp_f32_e32 v14, v14
	v_mul_f32_e32 v13, v15, v13
	v_mul_f32_e32 v14, v103, v14
	v_cvt_pk_bf16_f32 v13, v13, v14
	ds_write_b64 v175, v[12:13] offset:26112
	ds_read_b64 v[12:13], v175 offset:30464
	s_waitcnt lgkmcnt(0)
	v_lshlrev_b32_e32 v14, 16, v12
	v_fma_f32 v14, v0, v14, v72
	v_lshlrev_b32_e32 v15, 16, v13
	v_and_b32_e32 v13, 0xffff0000, v13
	v_fmac_f32_e32 v75, v3, v13
	v_mul_f32_e32 v13, v14, v14
	v_fmamk_f32 v13, v13, 0x3d922279, v192
	v_mul_f32_e32 v13, v14, v13
	v_mul_f32_e32 v13, 0xbfb8aa3b, v13
	v_exp_f32_e32 v13, v13
	v_and_b32_e32 v12, 0xffff0000, v12
	v_fma_f32 v12, v1, v12, v73
	v_fma_f32 v15, v2, v15, v74
	v_add_f32_e32 v13, 1.0, v13
	v_rcp_f32_e32 v13, v13
	s_nop 0
	v_mul_f32_e32 v13, v14, v13
	v_mul_f32_e32 v14, v12, v12
	v_fmamk_f32 v14, v14, 0x3d922279, v192
	v_mul_f32_e32 v14, v12, v14
	v_mul_f32_e32 v14, 0xbfb8aa3b, v14
	v_exp_f32_e32 v14, v14
	s_nop 0
	v_add_f32_e32 v14, 1.0, v14
	v_rcp_f32_e32 v14, v14
	s_nop 0
	v_mul_f32_e32 v12, v12, v14
	v_cvt_pk_bf16_f32 v12, v13, v12
	v_mul_f32_e32 v13, v15, v15
	v_fmamk_f32 v13, v13, 0x3d922279, v192
	v_mul_f32_e32 v14, v75, v75
	v_mul_f32_e32 v13, v15, v13
	v_fmamk_f32 v14, v14, 0x3d922279, v192
	v_mul_f32_e32 v13, 0xbfb8aa3b, v13
	v_mul_f32_e32 v14, v75, v14
	v_exp_f32_e32 v13, v13
	v_mul_f32_e32 v14, 0xbfb8aa3b, v14
	v_exp_f32_e32 v14, v14
	v_add_f32_e32 v13, 1.0, v13
	v_rcp_f32_e32 v13, v13
	v_add_f32_e32 v14, 1.0, v14
	v_rcp_f32_e32 v14, v14
	v_mul_f32_e32 v13, v15, v13
	v_mul_f32_e32 v14, v75, v14
	v_cvt_pk_bf16_f32 v13, v13, v14
	ds_write_b64 v175, v[12:13] offset:30464
	ds_read_b64 v[12:13], v175 offset:34816
	s_waitcnt lgkmcnt(0)
	v_lshlrev_b32_e32 v14, 16, v12
	v_and_b32_e32 v12, 0xffff0000, v12
	v_fma_f32 v9, v1, v12, v9
	v_lshlrev_b32_e32 v12, 16, v13
	v_fma_f32 v8, v0, v14, v8
	v_fma_f32 v10, v2, v12, v10
	v_and_b32_e32 v12, 0xffff0000, v13
	v_fmac_f32_e32 v11, v3, v12
	v_mul_f32_e32 v12, v8, v8
	v_fmamk_f32 v12, v12, 0x3d922279, v192
	v_mul_f32_e32 v12, v8, v12
	v_mul_f32_e32 v12, 0xbfb8aa3b, v12
	v_exp_f32_e32 v12, v12
	s_nop 0
	v_add_f32_e32 v12, 1.0, v12
	v_rcp_f32_e32 v12, v12
	s_nop 0
	v_mul_f32_e32 v8, v8, v12
	v_mul_f32_e32 v12, v9, v9
	v_fmamk_f32 v12, v12, 0x3d922279, v192
	v_mul_f32_e32 v12, v9, v12
	v_mul_f32_e32 v12, 0xbfb8aa3b, v12
	v_exp_f32_e32 v12, v12
	s_nop 0
	v_add_f32_e32 v12, 1.0, v12
	v_rcp_f32_e32 v12, v12
	s_nop 0
	v_mul_f32_e32 v9, v9, v12
	v_cvt_pk_bf16_f32 v8, v8, v9
	v_mul_f32_e32 v9, v10, v10
	v_fmamk_f32 v9, v9, 0x3d922279, v192
	v_mul_f32_e32 v9, v10, v9
	v_mul_f32_e32 v9, 0xbfb8aa3b, v9
	v_exp_f32_e32 v9, v9
	s_nop 0
	v_add_f32_e32 v9, 1.0, v9
	v_rcp_f32_e32 v9, v9
	s_nop 0
	v_mul_f32_e32 v9, v10, v9
	v_mul_f32_e32 v10, v11, v11
	v_fmamk_f32 v10, v10, 0x3d922279, v192
	v_mul_f32_e32 v10, v11, v10
	v_mul_f32_e32 v10, 0xbfb8aa3b, v10
	v_exp_f32_e32 v10, v10
	s_nop 0
	v_add_f32_e32 v10, 1.0, v10
	v_rcp_f32_e32 v10, v10
	s_nop 0
	v_mul_f32_e32 v10, v11, v10
	v_cvt_pk_bf16_f32 v9, v9, v10
	ds_write_b64 v175, v[8:9] offset:34816
	ds_read_b64 v[8:9], v175 offset:39168
	s_waitcnt lgkmcnt(0)
	v_lshlrev_b32_e32 v10, 16, v8
	v_and_b32_e32 v8, 0xffff0000, v8
	v_fma_f32 v5, v1, v8, v5
	v_lshlrev_b32_e32 v8, 16, v9
	v_fma_f32 v4, v0, v10, v4
	v_fma_f32 v6, v2, v8, v6
	v_and_b32_e32 v8, 0xffff0000, v9
	v_fmac_f32_e32 v7, v3, v8
	v_mul_f32_e32 v8, v4, v4
	v_fmamk_f32 v8, v8, 0x3d922279, v192
	v_mul_f32_e32 v8, v4, v8
	v_mul_f32_e32 v8, 0xbfb8aa3b, v8
	v_exp_f32_e32 v8, v8
	s_nop 0
	v_add_f32_e32 v8, 1.0, v8
	v_rcp_f32_e32 v8, v8
	s_nop 0
	v_mul_f32_e32 v4, v4, v8
	v_mul_f32_e32 v8, v5, v5
	v_fmamk_f32 v8, v8, 0x3d922279, v192
	v_mul_f32_e32 v8, v5, v8
	v_mul_f32_e32 v8, 0xbfb8aa3b, v8
	v_exp_f32_e32 v8, v8
	s_nop 0
	v_add_f32_e32 v8, 1.0, v8
	v_rcp_f32_e32 v8, v8
	s_nop 0
	v_mul_f32_e32 v5, v5, v8
	v_cvt_pk_bf16_f32 v4, v4, v5
	v_mul_f32_e32 v5, v6, v6
	v_fmamk_f32 v5, v5, 0x3d922279, v192
	v_mul_f32_e32 v5, v6, v5
	v_mul_f32_e32 v5, 0xbfb8aa3b, v5
	v_exp_f32_e32 v5, v5
	s_nop 0
	v_add_f32_e32 v5, 1.0, v5
	v_rcp_f32_e32 v5, v5
	s_nop 0
	v_mul_f32_e32 v5, v6, v5
	v_mul_f32_e32 v6, v7, v7
	v_fmamk_f32 v6, v6, 0x3d922279, v192
	v_mul_f32_e32 v6, v7, v6
	v_mul_f32_e32 v6, 0xbfb8aa3b, v6
	v_exp_f32_e32 v6, v6
	s_nop 0
	v_add_f32_e32 v6, 1.0, v6
	v_rcp_f32_e32 v6, v6
	s_nop 0
	v_mul_f32_e32 v6, v7, v6
	v_cvt_pk_bf16_f32 v5, v5, v6
	ds_write_b64 v175, v[4:5] offset:39168
	ds_read_b64 v[4:5], v175 offset:43520
	s_waitcnt lgkmcnt(0)
	v_lshlrev_b32_e32 v6, 16, v4
	v_fma_f32 v6, v0, v6, v88
	v_lshlrev_b32_e32 v7, 16, v5
	v_and_b32_e32 v5, 0xffff0000, v5
	v_fmac_f32_e32 v91, v3, v5
	v_mul_f32_e32 v5, v6, v6
	v_fmamk_f32 v5, v5, 0x3d922279, v192
	v_mul_f32_e32 v5, v6, v5
	v_mul_f32_e32 v5, 0xbfb8aa3b, v5
	v_exp_f32_e32 v5, v5
	v_and_b32_e32 v4, 0xffff0000, v4
	v_fma_f32 v4, v1, v4, v89
	v_fma_f32 v7, v2, v7, v90
	v_add_f32_e32 v5, 1.0, v5
	v_rcp_f32_e32 v5, v5
	s_nop 0
	v_mul_f32_e32 v5, v6, v5
	v_mul_f32_e32 v6, v4, v4
	v_fmamk_f32 v6, v6, 0x3d922279, v192
	v_mul_f32_e32 v6, v4, v6
	v_mul_f32_e32 v6, 0xbfb8aa3b, v6
	v_exp_f32_e32 v6, v6
	s_nop 0
	v_add_f32_e32 v6, 1.0, v6
	v_rcp_f32_e32 v6, v6
	s_nop 0
	v_mul_f32_e32 v4, v4, v6
	v_cvt_pk_bf16_f32 v4, v5, v4
	v_mul_f32_e32 v5, v7, v7
	v_fmamk_f32 v5, v5, 0x3d922279, v192
	v_mul_f32_e32 v6, v91, v91
	v_mul_f32_e32 v5, v7, v5
	v_fmamk_f32 v6, v6, 0x3d922279, v192
	v_mul_f32_e32 v5, 0xbfb8aa3b, v5
	v_mul_f32_e32 v6, v91, v6
	v_exp_f32_e32 v5, v5
	v_mul_f32_e32 v6, 0xbfb8aa3b, v6
	v_exp_f32_e32 v6, v6
	v_add_f32_e32 v5, 1.0, v5
	v_rcp_f32_e32 v5, v5
	v_add_f32_e32 v6, 1.0, v6
	v_rcp_f32_e32 v6, v6
	v_mul_f32_e32 v5, v7, v5
	v_mul_f32_e32 v6, v91, v6
	v_cvt_pk_bf16_f32 v5, v5, v6
	ds_write_b64 v175, v[4:5] offset:43520
	ds_read_b64 v[4:5], v175 offset:47872
	s_waitcnt lgkmcnt(0)
	v_lshlrev_b32_e32 v6, 16, v4
	v_fma_f32 v6, v0, v6, v76
	v_lshlrev_b32_e32 v7, 16, v5
	v_and_b32_e32 v5, 0xffff0000, v5
	v_fmac_f32_e32 v79, v3, v5
	v_mul_f32_e32 v5, v6, v6
	v_fmamk_f32 v5, v5, 0x3d922279, v192
	v_mul_f32_e32 v5, v6, v5
	v_mul_f32_e32 v5, 0xbfb8aa3b, v5
	v_exp_f32_e32 v5, v5
	v_and_b32_e32 v4, 0xffff0000, v4
	v_fma_f32 v4, v1, v4, v77
	v_fma_f32 v7, v2, v7, v78
	v_add_f32_e32 v5, 1.0, v5
	v_rcp_f32_e32 v5, v5
	s_nop 0
	v_mul_f32_e32 v5, v6, v5
	v_mul_f32_e32 v6, v4, v4
	v_fmamk_f32 v6, v6, 0x3d922279, v192
	v_mul_f32_e32 v6, v4, v6
	v_mul_f32_e32 v6, 0xbfb8aa3b, v6
	v_exp_f32_e32 v6, v6
	s_nop 0
	v_add_f32_e32 v6, 1.0, v6
	v_rcp_f32_e32 v6, v6
	s_nop 0
	v_mul_f32_e32 v4, v4, v6
	v_cvt_pk_bf16_f32 v4, v5, v4
	v_mul_f32_e32 v5, v7, v7
	v_fmamk_f32 v5, v5, 0x3d922279, v192
	v_mul_f32_e32 v6, v79, v79
	v_mul_f32_e32 v5, v7, v5
	v_fmamk_f32 v6, v6, 0x3d922279, v192
	v_mul_f32_e32 v5, 0xbfb8aa3b, v5
	v_mul_f32_e32 v6, v79, v6
	v_exp_f32_e32 v5, v5
	v_mul_f32_e32 v6, 0xbfb8aa3b, v6
	v_exp_f32_e32 v6, v6
	v_add_f32_e32 v5, 1.0, v5
	v_rcp_f32_e32 v5, v5
	v_add_f32_e32 v6, 1.0, v6
	v_rcp_f32_e32 v6, v6
	v_mul_f32_e32 v5, v7, v5
	v_mul_f32_e32 v6, v79, v6
	v_cvt_pk_bf16_f32 v5, v5, v6
	ds_write_b64 v175, v[4:5] offset:47872
	ds_read_b64 v[4:5], v175 offset:52224
	s_waitcnt lgkmcnt(0)
	v_lshlrev_b32_e32 v6, 16, v4
	v_fma_f32 v6, v0, v6, v60
	v_lshlrev_b32_e32 v7, 16, v5
	v_and_b32_e32 v5, 0xffff0000, v5
	v_fmac_f32_e32 v63, v3, v5
	v_mul_f32_e32 v5, v6, v6
	v_fmamk_f32 v5, v5, 0x3d922279, v192
	v_mul_f32_e32 v5, v6, v5
	v_mul_f32_e32 v5, 0xbfb8aa3b, v5
	v_exp_f32_e32 v5, v5
	v_and_b32_e32 v4, 0xffff0000, v4
	v_fma_f32 v4, v1, v4, v61
	v_fma_f32 v7, v2, v7, v62
	v_add_f32_e32 v5, 1.0, v5
	v_rcp_f32_e32 v5, v5
	s_nop 0
	v_mul_f32_e32 v5, v6, v5
	v_mul_f32_e32 v6, v4, v4
	v_fmamk_f32 v6, v6, 0x3d922279, v192
	v_mul_f32_e32 v6, v4, v6
	v_mul_f32_e32 v6, 0xbfb8aa3b, v6
	v_exp_f32_e32 v6, v6
	s_nop 0
	v_add_f32_e32 v6, 1.0, v6
	v_rcp_f32_e32 v6, v6
	s_nop 0
	v_mul_f32_e32 v4, v4, v6
	v_cvt_pk_bf16_f32 v4, v5, v4
	v_mul_f32_e32 v5, v7, v7
	v_fmamk_f32 v5, v5, 0x3d922279, v192
	v_mul_f32_e32 v6, v63, v63
	v_mul_f32_e32 v5, v7, v5
	v_fmamk_f32 v6, v6, 0x3d922279, v192
	v_mul_f32_e32 v5, 0xbfb8aa3b, v5
	v_mul_f32_e32 v6, v63, v6
	v_exp_f32_e32 v5, v5
	v_mul_f32_e32 v6, 0xbfb8aa3b, v6
	v_exp_f32_e32 v6, v6
	v_add_f32_e32 v5, 1.0, v5
	v_rcp_f32_e32 v5, v5
	v_add_f32_e32 v6, 1.0, v6
	v_rcp_f32_e32 v6, v6
	v_mul_f32_e32 v5, v7, v5
	v_mul_f32_e32 v6, v63, v6
	v_cvt_pk_bf16_f32 v5, v5, v6
	ds_write_b64 v175, v[4:5] offset:52224
	ds_read_b64 v[4:5], v175 offset:56576
	s_waitcnt lgkmcnt(0)
	v_lshlrev_b32_e32 v6, 16, v4
	v_fma_f32 v6, v0, v6, v56
	v_lshlrev_b32_e32 v7, 16, v5
	v_and_b32_e32 v5, 0xffff0000, v5
	v_fmac_f32_e32 v59, v3, v5
	v_mul_f32_e32 v5, v6, v6
	v_fmamk_f32 v5, v5, 0x3d922279, v192
	v_mul_f32_e32 v5, v6, v5
	v_mul_f32_e32 v5, 0xbfb8aa3b, v5
	v_exp_f32_e32 v5, v5
	v_and_b32_e32 v4, 0xffff0000, v4
	v_fma_f32 v4, v1, v4, v57
	v_fma_f32 v7, v2, v7, v58
	v_add_f32_e32 v5, 1.0, v5
	v_rcp_f32_e32 v5, v5
	s_nop 0
	v_mul_f32_e32 v5, v6, v5
	v_mul_f32_e32 v6, v4, v4
	v_fmamk_f32 v6, v6, 0x3d922279, v192
	v_mul_f32_e32 v6, v4, v6
	v_mul_f32_e32 v6, 0xbfb8aa3b, v6
	v_exp_f32_e32 v6, v6
	s_nop 0
	v_add_f32_e32 v6, 1.0, v6
	v_rcp_f32_e32 v6, v6
	s_nop 0
	v_mul_f32_e32 v4, v4, v6
	v_cvt_pk_bf16_f32 v4, v5, v4
	v_mul_f32_e32 v5, v7, v7
	v_fmamk_f32 v5, v5, 0x3d922279, v192
	v_mul_f32_e32 v6, v59, v59
	v_mul_f32_e32 v5, v7, v5
	v_fmamk_f32 v6, v6, 0x3d922279, v192
	v_mul_f32_e32 v5, 0xbfb8aa3b, v5
	v_mul_f32_e32 v6, v59, v6
	v_exp_f32_e32 v5, v5
	v_mul_f32_e32 v6, 0xbfb8aa3b, v6
	v_exp_f32_e32 v6, v6
	v_add_f32_e32 v5, 1.0, v5
	v_rcp_f32_e32 v5, v5
	v_add_f32_e32 v6, 1.0, v6
	v_rcp_f32_e32 v6, v6
	v_mul_f32_e32 v5, v7, v5
	v_mul_f32_e32 v6, v59, v6
	v_cvt_pk_bf16_f32 v5, v5, v6
	ds_write_b64 v175, v[4:5] offset:56576
	ds_read_b64 v[4:5], v175 offset:60928
	s_waitcnt lgkmcnt(0)
	v_lshlrev_b32_e32 v6, 16, v4
	v_fma_f32 v6, v0, v6, v46
	v_lshlrev_b32_e32 v7, 16, v5
	v_and_b32_e32 v5, 0xffff0000, v5
	v_fmac_f32_e32 v49, v3, v5
	v_mul_f32_e32 v5, v6, v6
	v_fmamk_f32 v5, v5, 0x3d922279, v192
	v_mul_f32_e32 v5, v6, v5
	v_mul_f32_e32 v5, 0xbfb8aa3b, v5
	v_exp_f32_e32 v5, v5
	v_and_b32_e32 v4, 0xffff0000, v4
	v_fma_f32 v4, v1, v4, v47
	v_fma_f32 v7, v2, v7, v48
	v_add_f32_e32 v5, 1.0, v5
	v_rcp_f32_e32 v5, v5
	s_nop 0
	v_mul_f32_e32 v5, v6, v5
	v_mul_f32_e32 v6, v4, v4
	v_fmamk_f32 v6, v6, 0x3d922279, v192
	v_mul_f32_e32 v6, v4, v6
	v_mul_f32_e32 v6, 0xbfb8aa3b, v6
	v_exp_f32_e32 v6, v6
	s_nop 0
	v_add_f32_e32 v6, 1.0, v6
	v_rcp_f32_e32 v6, v6
	s_nop 0
	v_mul_f32_e32 v4, v4, v6
	v_cvt_pk_bf16_f32 v4, v5, v4
	v_mul_f32_e32 v5, v7, v7
	v_fmamk_f32 v5, v5, 0x3d922279, v192
	v_mul_f32_e32 v6, v49, v49
	v_mul_f32_e32 v5, v7, v5
	v_fmamk_f32 v6, v6, 0x3d922279, v192
	v_mul_f32_e32 v5, 0xbfb8aa3b, v5
	v_mul_f32_e32 v6, v49, v6
	v_exp_f32_e32 v5, v5
	v_mul_f32_e32 v6, 0xbfb8aa3b, v6
	v_exp_f32_e32 v6, v6
	v_add_f32_e32 v5, 1.0, v5
	v_rcp_f32_e32 v5, v5
	v_add_f32_e32 v6, 1.0, v6
	v_rcp_f32_e32 v6, v6
	v_mul_f32_e32 v5, v7, v5
	v_mul_f32_e32 v6, v49, v6
	v_cvt_pk_bf16_f32 v5, v5, v6
	ds_write_b64 v175, v[4:5] offset:60928
	ds_read_b64 v[4:5], v175 offset:65280
	s_waitcnt lgkmcnt(0)
	v_lshlrev_b32_e32 v6, 16, v4
	v_and_b32_e32 v4, 0xffff0000, v4
	v_fma_f32 v1, v1, v4, v53
	v_lshlrev_b32_e32 v4, 16, v5
	v_fma_f32 v0, v0, v6, v52
	v_fma_f32 v2, v2, v4, v54
	v_and_b32_e32 v4, 0xffff0000, v5
	v_fmac_f32_e32 v55, v3, v4
	v_mul_f32_e32 v3, v0, v0
	v_fmamk_f32 v3, v3, 0x3d922279, v192
	v_mul_f32_e32 v3, v0, v3
	v_mul_f32_e32 v3, 0xbfb8aa3b, v3
	v_exp_f32_e32 v3, v3
	s_nop 0
	v_add_f32_e32 v3, 1.0, v3
	v_rcp_f32_e32 v3, v3
	s_nop 0
	v_mul_f32_e32 v0, v0, v3
	v_mul_f32_e32 v3, v1, v1
	v_fmamk_f32 v3, v3, 0x3d922279, v192
	v_mul_f32_e32 v3, v1, v3
	v_mul_f32_e32 v3, 0xbfb8aa3b, v3
	v_exp_f32_e32 v3, v3
	s_nop 0
	v_add_f32_e32 v3, 1.0, v3
	v_rcp_f32_e32 v3, v3
	s_nop 0
	v_mul_f32_e32 v1, v1, v3
	v_cvt_pk_bf16_f32 v0, v0, v1
	v_mul_f32_e32 v1, v2, v2
	v_fmamk_f32 v1, v1, 0x3d922279, v192
	v_mul_f32_e32 v1, v2, v1
	v_mul_f32_e32 v1, 0xbfb8aa3b, v1
	v_exp_f32_e32 v1, v1
	s_nop 0
	v_add_f32_e32 v1, 1.0, v1
	v_rcp_f32_e32 v1, v1
	s_nop 0
	v_mul_f32_e32 v1, v2, v1
	v_mul_f32_e32 v2, v55, v55
	v_fmamk_f32 v2, v2, 0x3d922279, v192
	v_mul_f32_e32 v2, v55, v2
	v_mul_f32_e32 v2, 0xbfb8aa3b, v2
	v_exp_f32_e32 v2, v2
	s_nop 0
	v_add_f32_e32 v2, 1.0, v2
	v_rcp_f32_e32 v2, v2
	s_nop 0
	v_mul_f32_e32 v2, v55, v2
	v_cvt_pk_bf16_f32 v1, v1, v2
	ds_write_b64 v175, v[0:1] offset:65280
	s_waitcnt lgkmcnt(0)
	s_barrier
	s_and_saveexec_b64 s[14:15], s[12:13]
	s_movk_i32 s33, 0x110
	s_movk_i32 s38, 0xdff
	s_cbranch_execz .LBB0_193
	v_readlane_b32 s34, v240, 62
	v_readlane_b32 s35, v240, 63
	s_lshl_b32 s34, s4, 8
	s_mov_b32 s5, s35
	s_lshl_b32 s3, s9, 8
	v_writelane_b32 v240, s4, 62
	v_lshl_add_u64 v[0:1], v[176:177], 0, s[34:35]
	s_mov_b64 s[34:35], 0
	v_mov_b32_e32 v2, v210
	v_writelane_b32 v240, s5, 63
